# pool mixer phase: never-taken denormal guards around rsqrt removed (scale multiplies dropped, selects become moves)
# speedup vs baseline: 1.0053x; 1.0053x over previous
.LBB0_2587:
	v_lshrrev_b32_e32 v1, 2, v141
	s_mov_b32 s0, 0xffff
	v_lshrrev_b32_e32 v0, 15, v141
	v_and_b32_e32 v151, 0x1ff8, v1
	v_cmp_lt_u32_e32 vcc, s0, v141
	s_and_saveexec_b64 s[0:1], vcc
	s_xor_b64 s[12:13], exec, s[0:1]
	s_cbranch_execz .LBB0_2599
	v_ashrrev_i32_e32 v1, 16, v141
	v_lshlrev_b32_e32 v0, 13, v0
	v_lshl_or_b32 v112, v1, 8, v104
	v_readlane_b32 s0, v254, 33
	s_waitcnt vmcnt(1)
	v_and_b32_e32 v65, 0x2000, v0
	v_ashrrev_i32_e32 v113, 31, v112
	v_readlane_b32 s1, v254, 34
	v_add_u32_e32 v173, -16, v65
	v_cmp_lt_i32_e32 vcc, 1, v1
	v_lshl_add_u64 v[114:115], v[112:113], 1, s[0:1]
	s_mov_b64 s[14:15], 0
	s_mov_b64 s[4:5], 0
	s_and_saveexec_b64 s[0:1], vcc
	s_xor_b64 s[16:17], exec, s[0:1]
	s_cbranch_execz .LBB0_2592
	v_cmp_eq_u32_e32 vcc, 2, v1
	s_mov_b64 s[4:5], -1
	s_and_saveexec_b64 s[18:19], vcc
	s_cbranch_execz .LBB0_2591
	v_add_u32_e32 v8, v151, v173
	v_add_u32_e32 v0, 9, v8
	v_cmp_eq_u32_e32 vcc, 0, v151
	v_mov_b32_e32 v1, 0x4009
	v_add_u32_e32 v4, 10, v8
	v_cndmask_b32_e32 v0, v0, v1, vcc
	v_ashrrev_i32_e32 v1, 31, v0
	v_lshlrev_b64 v[2:3], 11, v[0:1]
	v_lshl_add_u64 v[2:3], v[114:115], 0, v[2:3]
	v_lshl_add_u64 v[0:1], v[0:1], 2, s[42:43]
	global_load_dwordx4 v[52:55], v[2:3], off
	global_load_dword v64, v[0:1], off
	v_add_u32_e32 v0, 11, v8
	v_mov_b32_e32 v1, 0x400b
	v_cndmask_b32_e32 v0, v0, v1, vcc
	v_ashrrev_i32_e32 v1, 31, v0
	v_lshlrev_b64 v[2:3], 11, v[0:1]
	v_lshl_add_u64 v[2:3], v[114:115], 0, v[2:3]
	v_lshl_add_u64 v[0:1], v[0:1], 2, s[42:43]
	global_load_dwordx4 v[60:63], v[2:3], off
	global_load_dword v72, v[0:1], off
	v_add_u32_e32 v0, 12, v8
	v_mov_b32_e32 v1, 0x400c
	v_mov_b32_e32 v5, 0x400a
	v_cndmask_b32_e32 v0, v0, v1, vcc
	v_cndmask_b32_e32 v4, v4, v5, vcc
	v_ashrrev_i32_e32 v1, 31, v0
	v_ashrrev_i32_e32 v5, 31, v4
	v_lshlrev_b64 v[2:3], 11, v[0:1]
	v_lshl_add_u64 v[0:1], v[0:1], 2, s[42:43]
	v_lshl_add_u64 v[6:7], v[4:5], 2, s[42:43]
	v_lshl_add_u64 v[2:3], v[114:115], 0, v[2:3]
	global_load_dword v70, v[6:7], off
	global_load_dwordx4 v[90:93], v[2:3], off
	global_load_dword v99, v[0:1], off
	v_add_u32_e32 v0, 13, v8
	v_mov_b32_e32 v1, 0x400d
	v_cndmask_b32_e32 v0, v0, v1, vcc
	v_ashrrev_i32_e32 v1, 31, v0
	v_lshlrev_b64 v[4:5], 11, v[4:5]
	v_lshlrev_b64 v[2:3], 11, v[0:1]
	v_lshl_add_u64 v[0:1], v[0:1], 2, s[42:43]
	v_lshl_add_u64 v[4:5], v[114:115], 0, v[4:5]
	v_lshl_add_u64 v[2:3], v[114:115], 0, v[2:3]
	global_load_dwordx4 v[66:69], v[4:5], off
	global_load_dwordx4 v[36:39], v[2:3], off
	global_load_dword v101, v[0:1], off
	v_add_u32_e32 v0, 14, v8
	v_mov_b32_e32 v1, 0x400e
	v_cndmask_b32_e32 v0, v0, v1, vcc
	v_ashrrev_i32_e32 v1, 31, v0
	v_lshlrev_b64 v[2:3], 11, v[0:1]
	v_lshl_add_u64 v[2:3], v[114:115], 0, v[2:3]
	v_lshl_add_u64 v[0:1], v[0:1], 2, s[42:43]
	global_load_dwordx4 v[40:43], v[2:3], off
	global_load_dword v89, v[0:1], off
	v_add_u32_e32 v0, 15, v8
	v_mov_b32_e32 v1, 0x400f
	v_cndmask_b32_e32 v0, v0, v1, vcc
	v_ashrrev_i32_e32 v1, 31, v0
	v_lshlrev_b64 v[2:3], 11, v[0:1]
	v_lshl_add_u64 v[2:3], v[114:115], 0, v[2:3]
	v_lshl_add_u64 v[0:1], v[0:1], 2, s[42:43]
	global_load_dwordx4 v[44:47], v[2:3], off
	global_load_dword v103, v[0:1], off
	v_or_b32_e32 v2, v65, v151
	v_lshlrev_b32_e32 v192, 11, v2
	v_lshlrev_b32_e32 v9, 2, v2
	v_add_u32_e32 v2, 17, v8
	v_mov_b32_e32 v3, v193
	v_add_u32_e32 v4, 18, v8
	v_mov_b32_e32 v5, v193
	v_lshlrev_b64 v[2:3], 11, v[2:3]
	v_lshlrev_b64 v[4:5], 11, v[4:5]
	v_add_u32_e32 v6, 19, v8
	v_mov_b32_e32 v7, v193
	v_lshl_add_u64 v[2:3], v[114:115], 0, v[2:3]
	v_lshl_add_u64 v[4:5], v[114:115], 0, v[4:5]
	v_lshlrev_b64 v[6:7], 11, v[6:7]
	v_lshl_add_u64 v[0:1], v[114:115], 0, v[192:193]
	v_lshl_add_u64 v[6:7], v[114:115], 0, v[6:7]
	global_load_dwordx4 v[28:31], v[4:5], off
	global_load_dwordx4 v[24:27], v[6:7], off
	global_load_dwordx4 v[32:35], v[2:3], off
	global_load_dwordx4 v[56:59], v9, s[42:43] offset:16
	global_load_dwordx4 v[48:51], v[0:1], off
	global_load_dwordx4 v[94:97], v9, s[42:43]
	v_add_u32_e32 v4, 20, v8
	v_mov_b32_e32 v5, v193
	v_lshlrev_b64 v[4:5], 11, v[4:5]
	v_add_u32_e32 v0, 21, v8
	v_mov_b32_e32 v1, v193
	v_lshl_add_u64 v[4:5], v[114:115], 0, v[4:5]
	v_lshlrev_b64 v[0:1], 11, v[0:1]
	v_lshl_add_u64 v[0:1], v[114:115], 0, v[0:1]
	global_load_dwordx4 v[20:23], v[4:5], off
	global_load_dwordx4 v[16:19], v[0:1], off
	v_add_u32_e32 v0, 22, v8
	v_mov_b32_e32 v1, v193
	v_lshlrev_b64 v[0:1], 11, v[0:1]
	v_add_u32_e32 v2, 23, v8
	v_mov_b32_e32 v3, v193
	v_lshl_add_u64 v[0:1], v[114:115], 0, v[0:1]
	v_lshlrev_b64 v[2:3], 11, v[2:3]
	v_lshl_add_u64 v[2:3], v[114:115], 0, v[2:3]
	global_load_dwordx4 v[12:15], v[0:1], off
	global_load_dwordx4 v[4:7], v[2:3], off
	v_lshl_add_u64 v[8:9], v[112:113], 2, s[6:7]
	global_load_dwordx4 v[0:3], v[8:9], off offset:16
	s_nop 0
	global_load_dwordx4 v[8:11], v[8:9], off
	s_waitcnt vmcnt(24)
	v_fmamk_f32 v64, v64, 0x3a800000, v194
	v_cmp_gt_f32_e32 vcc, s2, v64
	v_and_b32_e32 v147, 0xffff0000, v52
	v_lshlrev_b32_e32 v146, 16, v52
	v_rsq_f32_e32 v64, v64
	v_and_b32_e32 v145, 0xffff0000, v53
	v_lshlrev_b32_e32 v144, 16, v53
	v_mov_b64_e32 v[52:53], s[24:25]
	v_mov_b32_e32 v86, v64
	v_and_b32_e32 v143, 0xffff0000, v54
	s_waitcnt vmcnt(21)
	v_fmamk_f32 v70, v70, 0x3a800000, v194
	v_cmp_gt_f32_e64 s[4:5], s2, v70
	v_lshlrev_b32_e32 v142, 16, v54
	v_and_b32_e32 v139, 0xffff0000, v55
	v_rsq_f32_e32 v70, v70
	v_lshlrev_b32_e32 v138, 16, v55
	v_and_b32_e32 v73, 0xffff0000, v62
	v_readlane_b32 s0, v254, 29
	v_fmamk_f32 v64, v72, 0x3a800000, v194
	s_waitcnt vmcnt(18)
	v_and_b32_e32 v85, 0xffff0000, v66
	v_lshlrev_b32_e32 v84, 16, v66
	v_cmp_gt_f32_e32 vcc, s2, v64
	v_and_b32_e32 v83, 0xffff0000, v67
	v_lshlrev_b32_e32 v82, 16, v67
	v_rsq_f32_e32 v64, v64
	v_and_b32_e32 v67, 0xffff0000, v90
	v_and_b32_e32 v79, 0xffff0000, v68
	v_lshlrev_b32_e32 v78, 16, v68
	v_lshlrev_b32_e32 v66, 16, v90
	v_and_b32_e32 v81, 0xffff0000, v69
	v_lshlrev_b32_e32 v80, 16, v69
	v_lshlrev_b32_e32 v72, 16, v62
	v_and_b32_e32 v69, 0xffff0000, v63
	v_lshlrev_b32_e32 v68, 16, v63
	v_and_b32_e32 v63, 0xffff0000, v91
	v_lshlrev_b32_e32 v62, 16, v91
	s_waitcnt vmcnt(17)
	v_lshlrev_b32_e32 v88, 16, v39
	v_readlane_b32 s1, v254, 30
	v_add_u32_e32 v71, v151, v65
	v_lshlrev_b32_e32 v121, 11, v71
	v_lshl_add_u64 v[130:131], v[112:113], 1, s[0:1]
	v_lshl_add_u64 v[156:157], v[130:131], 0, v[192:193]
	v_add_u32_e32 v192, 0x800, v121
	v_lshlrev_b32_e32 v87, 16, v93
	v_lshl_add_u64 v[148:149], v[130:131], 0, v[192:193]
	v_add_u32_e32 v192, 0x1000, v121
	s_waitcnt vmcnt(8)
	v_mov_b32_e32 v98, v56
	v_mov_b32_e32 v100, v57
	s_waitcnt vmcnt(6)
	v_pk_fma_f32 v[54:55], v[94:95], s[20:21], v[52:53] op_sel_hi:[1,0,0]
	v_mov_b32_e32 v102, v59
	v_cmp_gt_f32_e32 vcc, s2, v54
	v_cmp_gt_f32_e64 s[4:5], s2, v55
	v_pk_fma_f32 v[152:153], v[86:87], v[146:147], 0 op_sel_hi:[0,1,0]
	v_rsq_f32_e32 v54, v54
	v_rsq_f32_e32 v55, v55
	v_lshl_add_u64 v[134:135], v[130:131], 0, v[192:193]
	v_mov_b32_e32 v162, v54
	v_mov_b32_e32 v150, v55
	v_pk_fma_f32 v[54:55], v[96:97], s[20:21], v[52:53] op_sel_hi:[1,0,0]
	v_add_u32_e32 v192, 0x1800, v121
	v_cmp_gt_f32_e32 vcc, s2, v54
	v_cmp_gt_f32_e64 s[4:5], s2, v55
	v_and_b32_e32 v77, 0xffff0000, v60
	v_rsq_f32_e32 v54, v54
	v_rsq_f32_e32 v55, v55
	v_lshlrev_b32_e32 v76, 16, v60
	v_mov_b32_e32 v140, v54
	v_mov_b32_e32 v126, v55
	v_pk_fma_f32 v[54:55], v[98:99], s[20:21], v[52:53] op_sel_hi:[1,0,0]
	v_lshl_add_u64 v[132:133], v[130:131], 0, v[192:193]
	v_cmp_gt_f32_e32 vcc, s2, v55
	v_cmp_gt_f32_e64 s[4:5], s2, v54
	v_add_u32_e32 v192, 0x2000, v121
	v_rsq_f32_e32 v55, v55
	v_rsq_f32_e32 v54, v54
	s_waitcnt vmcnt(5)
	v_lshlrev_b32_e32 v56, 16, v23
	v_pk_fma_f32 v[152:153], v[70:71], v[84:85], v[152:153] op_sel_hi:[0,1,1]
	v_and_b32_e32 v75, 0xffff0000, v61
	v_pk_mul_f32 v[90:91], v[54:55], s[22:23] op_sel_hi:[1,0]
	v_lshlrev_b32_e32 v74, 16, v61
	v_cndmask_b32_e32 v117, v55, v91, vcc
	v_cndmask_b32_e64 v116, v54, v90, s[4:5]
	v_and_b32_e32 v55, 0xffff0000, v93
	v_and_b32_e32 v54, 0xffff0000, v23
	v_pk_mul_f32 v[122:123], v[116:117], v[54:55]
	v_pk_fma_f32 v[54:55], v[100:101], s[20:21], v[52:53] op_sel_hi:[1,0,0]
	v_mul_f32_e32 v120, v116, v56
	v_cmp_gt_f32_e32 vcc, s2, v55
	v_cmp_gt_f32_e64 s[4:5], s2, v54
	v_and_b32_e32 v61, 0xffff0000, v92
	v_mov_b32_e32 v23, v55
	v_rsq_f32_e32 v55, v23
	v_mov_b32_e32 v23, v54
	v_rsq_f32_e32 v54, v23
	s_waitcnt vmcnt(4)
	v_lshlrev_b32_e32 v23, 16, v19
	v_lshlrev_b32_e32 v60, 16, v92
	v_lshlrev_b32_e32 v92, 16, v43
	v_pk_mul_f32 v[56:57], v[54:55], s[22:23] op_sel_hi:[1,0]
	v_lshl_add_u64 v[128:129], v[130:131], 0, v[192:193]
	v_cndmask_b32_e32 v95, v55, v57, vcc
	v_cndmask_b32_e64 v94, v54, v56, s[4:5]
	v_mul_f32_e32 v96, v95, v88
	v_and_b32_e32 v55, 0xffff0000, v39
	v_and_b32_e32 v54, 0xffff0000, v19
	v_mov_b32_e32 v88, v58
	v_pk_mul_f32 v[100:101], v[94:95], v[54:55]
	v_pk_fma_f32 v[54:55], v[88:89], s[20:21], v[52:53] op_sel_hi:[1,0,0]
	v_pk_fma_f32 v[52:53], v[102:103], s[20:21], v[52:53] op_sel_hi:[1,0,0]
	v_cmp_gt_f32_e32 vcc, s2, v55
	v_cmp_gt_f32_e64 s[4:5], s2, v54
	v_add_u32_e32 v192, 0x2800, v121
	v_mov_b32_e32 v19, v55
	v_rsq_f32_e32 v55, v19
	v_mov_b32_e32 v19, v54
	v_rsq_f32_e32 v54, v19
	s_waitcnt vmcnt(3)
	v_lshlrev_b32_e32 v19, 16, v15
	v_pk_fma_f32 v[152:153], v[64:65], v[76:77], v[152:153] op_sel_hi:[0,1,1]
	v_mov_b32_e32 v166, v117
	v_pk_mul_f32 v[56:57], v[54:55], s[22:23] op_sel_hi:[1,0]
	v_lshl_add_u64 v[124:125], v[130:131], 0, v[192:193]
	v_cndmask_b32_e32 v89, v55, v57, vcc
	v_cndmask_b32_e64 v88, v54, v56, s[4:5]
	v_and_b32_e32 v54, 0xffff0000, v15
	v_cmp_gt_f32_e32 vcc, s2, v53
	v_cmp_gt_f32_e64 s[4:5], s2, v52
	v_and_b32_e32 v55, 0xffff0000, v43
	v_mov_b32_e32 v15, v53
	v_rsq_f32_e32 v53, v15
	v_mov_b32_e32 v15, v52
	v_rsq_f32_e32 v52, v15
	v_mul_f32_e32 v58, v89, v92
	v_pk_mul_f32 v[92:93], v[88:89], v[54:55]
	v_add_u32_e32 v192, 0x3000, v121
	v_pk_mul_f32 v[54:55], v[52:53], s[22:23] op_sel_hi:[1,0]
	v_and_b32_e32 v155, 0xffff0000, v36
	v_lshlrev_b32_e32 v154, 16, v36
	v_and_b32_e32 v159, 0xffff0000, v48
	v_lshlrev_b32_e32 v158, 16, v48
	v_pk_fma_f32 v[152:153], v[166:167], v[66:67], v[152:153] op_sel_hi:[0,1,1]
	v_mov_b32_e32 v48, v95
	v_lshl_add_u64 v[102:103], v[130:131], 0, v[192:193]
	v_cndmask_b32_e32 v53, v53, v55, vcc
	v_and_b32_e32 v137, 0xffff0000, v40
	v_lshlrev_b32_e32 v136, 16, v40
	v_and_b32_e32 v131, 0xffff0000, v44
	v_lshlrev_b32_e32 v130, 16, v44
	v_pk_fma_f32 v[152:153], v[48:49], v[154:155], v[152:153] op_sel_hi:[0,1,1]
	v_mov_b32_e32 v44, v89
	v_pk_fma_f32 v[152:153], v[44:45], v[136:137], v[152:153] op_sel_hi:[0,1,1]
	v_mov_b32_e32 v36, v53
	v_pk_fma_f32 v[168:169], v[86:87], v[144:145], 0 op_sel_hi:[0,1,0]
	v_pk_fma_f32 v[152:153], v[36:37], v[130:131], v[152:153] op_sel_hi:[0,1,1]
	v_pk_mul_f32 v[170:171], v[162:163], v[158:159] op_sel_hi:[0,1]
	v_pk_fma_f32 v[178:179], v[162:163], v[158:159], v[152:153] op_sel_hi:[0,1,1]
	s_mov_b32 s0, 0x3e000000
	v_pk_fma_f32 v[168:169], v[70:71], v[82:83], v[168:169] op_sel_hi:[0,1,1]
	v_pk_fma_f32 v[152:153], v[178:179], s[0:1], v[170:171] op_sel_hi:[1,0,1] neg_lo:[0,0,1] neg_hi:[0,0,1]
	v_pk_fma_f32 v[168:169], v[64:65], v[74:75], v[168:169] op_sel_hi:[0,1,1]
	s_waitcnt vmcnt(0)
	v_pk_mul_f32 v[152:153], v[8:9], v[152:153]
	v_and_b32_e32 v159, 0xffff0000, v37
	v_lshlrev_b32_e32 v158, 16, v37
	v_pk_fma_f32 v[168:169], v[166:167], v[62:63], v[168:169] op_sel_hi:[0,1,1]
	v_cvt_pk_bf16_f32 v174, v152, v153
	v_and_b32_e32 v153, 0xffff0000, v41
	v_lshlrev_b32_e32 v152, 16, v41
	v_pk_fma_f32 v[168:169], v[48:49], v[158:159], v[168:169] op_sel_hi:[0,1,1]
	v_and_b32_e32 v41, 0xffff0000, v45
	v_lshlrev_b32_e32 v40, 16, v45
	v_pk_fma_f32 v[168:169], v[44:45], v[152:153], v[168:169] op_sel_hi:[0,1,1]
	v_and_b32_e32 v171, 0xffff0000, v49
	v_lshlrev_b32_e32 v170, 16, v49
	v_pk_fma_f32 v[168:169], v[36:37], v[40:41], v[168:169] op_sel_hi:[0,1,1]
	v_pk_mul_f32 v[176:177], v[162:163], v[170:171] op_sel_hi:[0,1]
	v_pk_fma_f32 v[170:171], v[162:163], v[170:171], v[168:169] op_sel_hi:[0,1,1]
	v_pk_fma_f32 v[168:169], v[170:171], s[0:1], v[176:177] op_sel_hi:[1,0,1] neg_lo:[0,0,1] neg_hi:[0,0,1]
	v_pk_fma_f32 v[164:165], v[86:87], v[142:143], 0 op_sel_hi:[0,1,0]
	v_pk_mul_f32 v[168:169], v[10:11], v[168:169]
	v_lshlrev_b32_e32 v119, 16, v47
	v_and_b32_e32 v57, 0xffff0000, v47
	v_cvt_pk_bf16_f32 v175, v168, v169
	v_and_b32_e32 v169, 0xffff0000, v38
	v_lshlrev_b32_e32 v168, 16, v38
	v_and_b32_e32 v39, 0xffff0000, v46
	v_lshlrev_b32_e32 v38, 16, v46
	v_pk_fma_f32 v[46:47], v[70:71], v[78:79], v[164:165] op_sel_hi:[0,1,1]
	v_pk_fma_f32 v[46:47], v[64:65], v[72:73], v[46:47] op_sel_hi:[0,1,1]
	v_pk_fma_f32 v[46:47], v[166:167], v[60:61], v[46:47] op_sel_hi:[0,1,1]
	v_pk_fma_f32 v[160:161], v[86:87], v[138:139], 0 op_sel_hi:[0,1,0]
	v_and_b32_e32 v43, 0xffff0000, v42
	v_lshlrev_b32_e32 v42, 16, v42
	v_pk_fma_f32 v[46:47], v[48:49], v[168:169], v[46:47] op_sel_hi:[0,1,1]
	v_pk_fma_f32 v[46:47], v[44:45], v[42:43], v[46:47] op_sel_hi:[0,1,1]
	v_pk_fma_f32 v[160:161], v[70:71], v[80:81], v[160:161] op_sel_hi:[0,1,1]
	v_mul_f32_e32 v118, v117, v87
	v_cndmask_b32_e64 v52, v52, v54, s[4:5]
	v_mul_f32_e32 v54, v53, v119
	v_and_b32_e32 v165, 0xffff0000, v50
	v_lshlrev_b32_e32 v164, 16, v50
	v_pk_fma_f32 v[46:47], v[36:37], v[38:39], v[46:47] op_sel_hi:[0,1,1]
	v_pk_fma_f32 v[160:161], v[64:65], v[68:69], v[160:161] op_sel_hi:[0,1,1]
	v_mov_b32_e32 v119, v123
	v_and_b32_e32 v56, 0xffff0000, v7
	v_pk_mul_f32 v[176:177], v[162:163], v[164:165] op_sel_hi:[0,1]
	v_pk_fma_f32 v[46:47], v[162:163], v[164:165], v[46:47] op_sel_hi:[0,1,1]
	v_pk_add_f32 v[160:161], v[118:119], v[160:161]
	v_mov_b32_e32 v97, v101
	v_pk_mul_f32 v[56:57], v[52:53], v[56:57]
	v_pk_fma_f32 v[164:165], v[46:47], s[0:1], v[176:177] op_sel_hi:[1,0,1] neg_lo:[0,0,1] neg_hi:[0,0,1]
	v_pk_add_f32 v[160:161], v[96:97], v[160:161]
	v_mov_b32_e32 v59, v93
	v_pk_mul_f32 v[164:165], v[0:1], v[164:165]
	v_pk_add_f32 v[160:161], v[58:59], v[160:161]
	v_mov_b32_e32 v55, v57
	v_cvt_pk_bf16_f32 v176, v164, v165
	v_and_b32_e32 v165, 0xffff0000, v51
	v_lshlrev_b32_e32 v164, 16, v51
	v_pk_add_f32 v[160:161], v[54:55], v[160:161]
	v_pk_mul_f32 v[50:51], v[162:163], v[164:165] op_sel_hi:[0,1]
	v_pk_fma_f32 v[160:161], v[162:163], v[164:165], v[160:161] op_sel_hi:[0,1,1]
	v_pk_fma_f32 v[50:51], v[160:161], s[0:1], v[50:51] op_sel_hi:[1,0,1] neg_lo:[0,0,1] neg_hi:[0,0,1]
	v_pk_fma_f32 v[146:147], v[86:87], v[146:147], v[178:179] op_sel_hi:[0,1,1] neg_lo:[1,0,0] neg_hi:[1,0,0]
	v_pk_mul_f32 v[50:51], v[2:3], v[50:51]
	v_pk_fma_f32 v[144:145], v[86:87], v[144:145], v[170:171] op_sel_hi:[0,1,1] neg_lo:[1,0,0] neg_hi:[1,0,0]
	v_cvt_pk_bf16_f32 v177, v50, v51
	v_and_b32_e32 v51, 0xffff0000, v32
	v_lshlrev_b32_e32 v50, 16, v32
	global_store_dwordx4 v[156:157], v[174:177], off
	v_pk_mul_f32 v[156:157], v[150:151], v[50:51] op_sel_hi:[0,1]
	v_pk_fma_f32 v[50:51], v[150:151], v[50:51], v[146:147] op_sel_hi:[0,1,1]
	v_pk_fma_f32 v[146:147], v[50:51], s[0:1], v[156:157] op_sel_hi:[1,0,1] neg_lo:[0,0,1] neg_hi:[0,0,1]
	v_pk_fma_f32 v[46:47], v[86:87], v[142:143], v[46:47] op_sel_hi:[0,1,1] neg_lo:[1,0,0] neg_hi:[1,0,0]
	v_pk_mul_f32 v[146:147], v[8:9], v[146:147]
	v_pk_fma_f32 v[86:87], v[86:87], v[138:139], v[160:161] op_sel_hi:[0,1,1] neg_lo:[1,0,0] neg_hi:[1,0,0]
	v_cvt_pk_bf16_f32 v32, v146, v147
	v_and_b32_e32 v147, 0xffff0000, v33
	v_lshlrev_b32_e32 v146, 16, v33
	v_pk_mul_f32 v[156:157], v[150:151], v[146:147] op_sel_hi:[0,1]
	v_pk_fma_f32 v[144:145], v[150:151], v[146:147], v[144:145] op_sel_hi:[0,1,1]
	v_pk_fma_f32 v[146:147], v[144:145], s[0:1], v[156:157] op_sel_hi:[1,0,1] neg_lo:[0,0,1] neg_hi:[0,0,1]
	v_pk_fma_f32 v[50:51], v[70:71], v[84:85], v[50:51] op_sel_hi:[0,1,1] neg_lo:[1,0,0] neg_hi:[1,0,0]
	v_pk_mul_f32 v[146:147], v[10:11], v[146:147]
	v_pk_fma_f32 v[82:83], v[70:71], v[82:83], v[144:145] op_sel_hi:[0,1,1] neg_lo:[1,0,0] neg_hi:[1,0,0]
	v_cvt_pk_bf16_f32 v33, v146, v147
	v_and_b32_e32 v147, 0xffff0000, v34
	v_lshlrev_b32_e32 v146, 16, v34
	v_pk_mul_f32 v[156:157], v[150:151], v[146:147] op_sel_hi:[0,1]
	v_pk_fma_f32 v[46:47], v[150:151], v[146:147], v[46:47] op_sel_hi:[0,1,1]
	v_pk_fma_f32 v[142:143], v[46:47], s[0:1], v[156:157] op_sel_hi:[1,0,1] neg_lo:[0,0,1] neg_hi:[0,0,1]
	v_pk_fma_f32 v[46:47], v[70:71], v[78:79], v[46:47] op_sel_hi:[0,1,1] neg_lo:[1,0,0] neg_hi:[1,0,0]
	v_pk_mul_f32 v[142:143], v[0:1], v[142:143]
	v_lshlrev_b32_e32 v127, 16, v7
	v_cvt_pk_bf16_f32 v34, v142, v143
	v_and_b32_e32 v143, 0xffff0000, v35
	v_lshlrev_b32_e32 v142, 16, v35
	v_pk_mul_f32 v[146:147], v[150:151], v[142:143] op_sel_hi:[0,1]
	v_pk_fma_f32 v[86:87], v[150:151], v[142:143], v[86:87] op_sel_hi:[0,1,1]
	v_pk_fma_f32 v[138:139], v[86:87], s[0:1], v[146:147] op_sel_hi:[1,0,1] neg_lo:[0,0,1] neg_hi:[0,0,1]
	v_pk_fma_f32 v[80:81], v[70:71], v[80:81], v[86:87] op_sel_hi:[0,1,1] neg_lo:[1,0,0] neg_hi:[1,0,0]
	v_pk_mul_f32 v[138:139], v[2:3], v[138:139]
	v_mul_f32_e32 v98, v94, v23
	v_cvt_pk_bf16_f32 v35, v138, v139
	global_store_dwordx4 v[148:149], v[32:35], off
	v_and_b32_e32 v23, 0xffff0000, v22
	v_lshlrev_b32_e32 v22, 16, v22
	v_and_b32_e32 v33, 0xffff0000, v28
	v_lshlrev_b32_e32 v32, 16, v28
	v_pk_mul_f32 v[34:35], v[140:141], v[32:33] op_sel_hi:[0,1]
	v_pk_fma_f32 v[32:33], v[140:141], v[32:33], v[50:51] op_sel_hi:[0,1,1]
	v_pk_fma_f32 v[34:35], v[32:33], s[0:1], v[34:35] op_sel_hi:[1,0,1] neg_lo:[0,0,1] neg_hi:[0,0,1]
	v_pk_fma_f32 v[32:33], v[64:65], v[76:77], v[32:33] op_sel_hi:[0,1,1] neg_lo:[1,0,0] neg_hi:[1,0,0]
	v_pk_mul_f32 v[34:35], v[8:9], v[34:35]
	v_mov_b32_e32 v121, v122
	v_cvt_pk_bf16_f32 v28, v34, v35
	v_and_b32_e32 v35, 0xffff0000, v29
	v_lshlrev_b32_e32 v34, 16, v29
	v_pk_mul_f32 v[50:51], v[140:141], v[34:35] op_sel_hi:[0,1]
	v_pk_fma_f32 v[34:35], v[140:141], v[34:35], v[82:83] op_sel_hi:[0,1,1]
	v_pk_fma_f32 v[50:51], v[34:35], s[0:1], v[50:51] op_sel_hi:[1,0,1] neg_lo:[0,0,1] neg_hi:[0,0,1]
	v_pk_fma_f32 v[34:35], v[64:65], v[74:75], v[34:35] op_sel_hi:[0,1,1] neg_lo:[1,0,0] neg_hi:[1,0,0]
	v_pk_mul_f32 v[50:51], v[10:11], v[50:51]
	v_mul_f32_e32 v90, v88, v19
	v_cvt_pk_bf16_f32 v29, v50, v51
	v_and_b32_e32 v51, 0xffff0000, v30
	v_lshlrev_b32_e32 v50, 16, v30
	v_pk_mul_f32 v[82:83], v[140:141], v[50:51] op_sel_hi:[0,1]
	v_pk_fma_f32 v[46:47], v[140:141], v[50:51], v[46:47] op_sel_hi:[0,1,1]
	v_pk_fma_f32 v[50:51], v[46:47], s[0:1], v[82:83] op_sel_hi:[1,0,1] neg_lo:[0,0,1] neg_hi:[0,0,1]
	v_pk_fma_f32 v[46:47], v[64:65], v[72:73], v[46:47] op_sel_hi:[0,1,1] neg_lo:[1,0,0] neg_hi:[1,0,0]
	v_pk_mul_f32 v[50:51], v[0:1], v[50:51]
	v_and_b32_e32 v19, 0xffff0000, v18
	v_cvt_pk_bf16_f32 v30, v50, v51
	v_and_b32_e32 v51, 0xffff0000, v31
	v_lshlrev_b32_e32 v50, 16, v31
	v_pk_mul_f32 v[78:79], v[140:141], v[50:51] op_sel_hi:[0,1]
	v_pk_fma_f32 v[50:51], v[140:141], v[50:51], v[80:81] op_sel_hi:[0,1,1]
	v_pk_fma_f32 v[78:79], v[50:51], s[0:1], v[78:79] op_sel_hi:[1,0,1] neg_lo:[0,0,1] neg_hi:[0,0,1]
	v_pk_fma_f32 v[50:51], v[64:65], v[68:69], v[50:51] op_sel_hi:[0,1,1] neg_lo:[1,0,0] neg_hi:[1,0,0]
	v_pk_mul_f32 v[78:79], v[2:3], v[78:79]
	v_lshlrev_b32_e32 v18, 16, v18
	v_cvt_pk_bf16_f32 v31, v78, v79
	global_store_dwordx4 v[134:135], v[28:31], off
	v_mov_b32_e32 v99, v100
	v_and_b32_e32 v15, 0xffff0000, v14
	v_and_b32_e32 v29, 0xffff0000, v24
	v_lshlrev_b32_e32 v28, 16, v24
	v_pk_mul_f32 v[30:31], v[126:127], v[28:29] op_sel_hi:[0,1]
	v_pk_fma_f32 v[28:29], v[126:127], v[28:29], v[32:33] op_sel_hi:[0,1,1]
	v_pk_fma_f32 v[30:31], v[28:29], s[0:1], v[30:31] op_sel_hi:[1,0,1] neg_lo:[0,0,1] neg_hi:[0,0,1]
	v_pk_fma_f32 v[28:29], v[166:167], v[66:67], v[28:29] op_sel_hi:[0,1,1] neg_lo:[1,0,0] neg_hi:[1,0,0]
	v_pk_mul_f32 v[30:31], v[8:9], v[30:31]
	v_lshlrev_b32_e32 v14, 16, v14
	v_cvt_pk_bf16_f32 v24, v30, v31
	v_and_b32_e32 v31, 0xffff0000, v25
	v_lshlrev_b32_e32 v30, 16, v25
	v_pk_mul_f32 v[32:33], v[126:127], v[30:31] op_sel_hi:[0,1]
	v_pk_fma_f32 v[30:31], v[126:127], v[30:31], v[34:35] op_sel_hi:[0,1,1]
	v_pk_fma_f32 v[32:33], v[30:31], s[0:1], v[32:33] op_sel_hi:[1,0,1] neg_lo:[0,0,1] neg_hi:[0,0,1]
	v_pk_fma_f32 v[30:31], v[166:167], v[62:63], v[30:31] op_sel_hi:[0,1,1] neg_lo:[1,0,0] neg_hi:[1,0,0]
	v_pk_mul_f32 v[32:33], v[10:11], v[32:33]
	v_mov_b32_e32 v91, v92
	v_cvt_pk_bf16_f32 v25, v32, v33
	v_and_b32_e32 v33, 0xffff0000, v26
	v_lshlrev_b32_e32 v32, 16, v26
	v_pk_mul_f32 v[34:35], v[126:127], v[32:33] op_sel_hi:[0,1]
	v_pk_fma_f32 v[32:33], v[126:127], v[32:33], v[46:47] op_sel_hi:[0,1,1]
	v_pk_fma_f32 v[34:35], v[32:33], s[0:1], v[34:35] op_sel_hi:[1,0,1] neg_lo:[0,0,1] neg_hi:[0,0,1]
	v_and_b32_e32 v7, 0xffff0000, v6
	v_pk_mul_f32 v[34:35], v[0:1], v[34:35]
	v_lshlrev_b32_e32 v6, 16, v6
	v_cvt_pk_bf16_f32 v26, v34, v35
	v_and_b32_e32 v35, 0xffff0000, v27
	v_lshlrev_b32_e32 v34, 16, v27
	v_pk_mul_f32 v[46:47], v[126:127], v[34:35] op_sel_hi:[0,1]
	v_pk_fma_f32 v[34:35], v[126:127], v[34:35], v[50:51] op_sel_hi:[0,1,1]
	v_pk_fma_f32 v[46:47], v[34:35], s[0:1], v[46:47] op_sel_hi:[1,0,1] neg_lo:[0,0,1] neg_hi:[0,0,1]
	v_add_u32_e32 v192, 7, v71
	v_pk_mul_f32 v[46:47], v[2:3], v[46:47]
	s_xor_b64 s[4:5], exec, -1
	v_cvt_pk_bf16_f32 v27, v46, v47
	global_store_dwordx4 v[132:133], v[24:27], off
	s_nop 1
	v_and_b32_e32 v25, 0xffff0000, v20
	v_lshlrev_b32_e32 v24, 16, v20
	v_pk_mul_f32 v[26:27], v[116:117], v[24:25] op_sel_hi:[0,1]
	v_pk_fma_f32 v[24:25], v[116:117], v[24:25], v[28:29] op_sel_hi:[0,1,1]
	v_pk_fma_f32 v[26:27], v[24:25], s[0:1], v[26:27] op_sel_hi:[1,0,1] neg_lo:[0,0,1] neg_hi:[0,0,1]
	v_pk_fma_f32 v[24:25], v[48:49], v[154:155], v[24:25] op_sel_hi:[0,1,1] neg_lo:[1,0,0] neg_hi:[1,0,0]
	v_pk_mul_f32 v[26:27], v[8:9], v[26:27]
	s_nop 0
	v_cvt_pk_bf16_f32 v20, v26, v27
	v_and_b32_e32 v27, 0xffff0000, v21
	v_lshlrev_b32_e32 v26, 16, v21
	v_pk_mul_f32 v[28:29], v[116:117], v[26:27] op_sel_hi:[0,1]
	v_pk_fma_f32 v[26:27], v[116:117], v[26:27], v[30:31] op_sel_hi:[0,1,1]
	v_pk_fma_f32 v[28:29], v[26:27], s[0:1], v[28:29] op_sel_hi:[1,0,1] neg_lo:[0,0,1] neg_hi:[0,0,1]
	v_pk_fma_f32 v[30:31], v[166:167], v[60:61], v[32:33] op_sel_hi:[0,1,1] neg_lo:[1,0,0] neg_hi:[1,0,0]
	v_pk_mul_f32 v[28:29], v[10:11], v[28:29]
	v_pk_fma_f32 v[30:31], v[116:117], v[22:23], v[30:31] op_sel_hi:[0,1,1]
	v_cvt_pk_bf16_f32 v21, v28, v29
	v_pk_mul_f32 v[28:29], v[116:117], v[22:23] op_sel_hi:[0,1]
	v_pk_fma_f32 v[22:23], v[30:31], s[0:1], v[28:29] op_sel_hi:[1,0,1] neg_lo:[0,0,1] neg_hi:[0,0,1]
	v_pk_add_f32 v[28:29], v[34:35], v[118:119] neg_lo:[0,1] neg_hi:[0,1]
	v_pk_mul_f32 v[22:23], v[0:1], v[22:23]
	v_pk_add_f32 v[28:29], v[120:121], v[28:29]
	v_cvt_pk_bf16_f32 v22, v22, v23
	v_pk_fma_f32 v[32:33], v[28:29], s[0:1], v[120:121] op_sel_hi:[1,0,1] neg_lo:[0,0,1] neg_hi:[0,0,1]
	v_pk_fma_f32 v[26:27], v[48:49], v[158:159], v[26:27] op_sel_hi:[0,1,1] neg_lo:[1,0,0] neg_hi:[1,0,0]
	v_pk_mul_f32 v[32:33], v[2:3], v[32:33]
	s_nop 0
	v_cvt_pk_bf16_f32 v23, v32, v33
	global_store_dwordx4 v[128:129], v[20:23], off
	s_nop 1
	v_and_b32_e32 v21, 0xffff0000, v16
	v_lshlrev_b32_e32 v20, 16, v16
	v_pk_mul_f32 v[22:23], v[94:95], v[20:21] op_sel_hi:[0,1]
	v_pk_fma_f32 v[20:21], v[94:95], v[20:21], v[24:25] op_sel_hi:[0,1,1]
	v_pk_fma_f32 v[22:23], v[20:21], s[0:1], v[22:23] op_sel_hi:[1,0,1] neg_lo:[0,0,1] neg_hi:[0,0,1]
	v_pk_fma_f32 v[20:21], v[44:45], v[136:137], v[20:21] op_sel_hi:[0,1,1] neg_lo:[1,0,0] neg_hi:[1,0,0]
	v_pk_mul_f32 v[22:23], v[8:9], v[22:23]
	s_nop 0
	v_cvt_pk_bf16_f32 v16, v22, v23
	v_and_b32_e32 v23, 0xffff0000, v17
	v_lshlrev_b32_e32 v22, 16, v17
	v_pk_mul_f32 v[24:25], v[94:95], v[22:23] op_sel_hi:[0,1]
	v_pk_fma_f32 v[22:23], v[94:95], v[22:23], v[26:27] op_sel_hi:[0,1,1]
	v_pk_fma_f32 v[24:25], v[22:23], s[0:1], v[24:25] op_sel_hi:[1,0,1] neg_lo:[0,0,1] neg_hi:[0,0,1]
	v_pk_fma_f32 v[26:27], v[48:49], v[168:169], v[30:31] op_sel_hi:[0,1,1] neg_lo:[1,0,0] neg_hi:[1,0,0]
	v_pk_mul_f32 v[24:25], v[10:11], v[24:25]
	v_pk_fma_f32 v[26:27], v[94:95], v[18:19], v[26:27] op_sel_hi:[0,1,1]
	v_cvt_pk_bf16_f32 v17, v24, v25
	v_pk_mul_f32 v[24:25], v[94:95], v[18:19] op_sel_hi:[0,1]
	v_pk_fma_f32 v[18:19], v[26:27], s[0:1], v[24:25] op_sel_hi:[1,0,1] neg_lo:[0,0,1] neg_hi:[0,0,1]
	v_pk_add_f32 v[24:25], v[28:29], v[96:97] neg_lo:[0,1] neg_hi:[0,1]
	v_pk_mul_f32 v[18:19], v[0:1], v[18:19]
	v_pk_add_f32 v[24:25], v[98:99], v[24:25]
	v_cvt_pk_bf16_f32 v18, v18, v19
	v_pk_fma_f32 v[28:29], v[24:25], s[0:1], v[98:99] op_sel_hi:[1,0,1] neg_lo:[0,0,1] neg_hi:[0,0,1]
	v_pk_fma_f32 v[22:23], v[44:45], v[152:153], v[22:23] op_sel_hi:[0,1,1] neg_lo:[1,0,0] neg_hi:[1,0,0]
	v_pk_mul_f32 v[28:29], v[2:3], v[28:29]
	s_nop 0
	v_cvt_pk_bf16_f32 v19, v28, v29
	global_store_dwordx4 v[124:125], v[16:19], off
	s_nop 1
	v_and_b32_e32 v17, 0xffff0000, v12
	v_lshlrev_b32_e32 v16, 16, v12
	v_pk_mul_f32 v[18:19], v[88:89], v[16:17] op_sel_hi:[0,1]
	v_pk_fma_f32 v[16:17], v[88:89], v[16:17], v[20:21] op_sel_hi:[0,1,1]
	v_pk_fma_f32 v[18:19], v[16:17], s[0:1], v[18:19] op_sel_hi:[1,0,1] neg_lo:[0,0,1] neg_hi:[0,0,1]
	s_nop 0
	v_pk_mul_f32 v[18:19], v[8:9], v[18:19]
	s_nop 0
	v_cvt_pk_bf16_f32 v12, v18, v19
	v_and_b32_e32 v19, 0xffff0000, v13
	v_lshlrev_b32_e32 v18, 16, v13
	v_pk_mul_f32 v[20:21], v[88:89], v[18:19] op_sel_hi:[0,1]
	v_pk_fma_f32 v[18:19], v[88:89], v[18:19], v[22:23] op_sel_hi:[0,1,1]
	v_pk_fma_f32 v[20:21], v[18:19], s[0:1], v[20:21] op_sel_hi:[1,0,1] neg_lo:[0,0,1] neg_hi:[0,0,1]
	v_pk_fma_f32 v[22:23], v[44:45], v[42:43], v[26:27] op_sel_hi:[0,1,1] neg_lo:[1,0,0] neg_hi:[1,0,0]
	v_pk_mul_f32 v[20:21], v[10:11], v[20:21]
	v_pk_fma_f32 v[22:23], v[88:89], v[14:15], v[22:23] op_sel_hi:[0,1,1]
	v_cvt_pk_bf16_f32 v13, v20, v21
	v_pk_mul_f32 v[20:21], v[88:89], v[14:15] op_sel_hi:[0,1]
	v_pk_fma_f32 v[14:15], v[22:23], s[0:1], v[20:21] op_sel_hi:[1,0,1] neg_lo:[0,0,1] neg_hi:[0,0,1]
	v_pk_add_f32 v[20:21], v[24:25], v[58:59] neg_lo:[0,1] neg_hi:[0,1]
	v_pk_mul_f32 v[14:15], v[0:1], v[14:15]
	v_pk_add_f32 v[20:21], v[90:91], v[20:21]
	v_cvt_pk_bf16_f32 v14, v14, v15
	v_pk_fma_f32 v[24:25], v[20:21], s[0:1], v[90:91] op_sel_hi:[1,0,1] neg_lo:[0,0,1] neg_hi:[0,0,1]
	s_nop 0
	v_pk_mul_f32 v[24:25], v[2:3], v[24:25]
	s_nop 0
	v_cvt_pk_bf16_f32 v15, v24, v25
	global_store_dwordx4 v[102:103], v[12:15], off
	s_nop 1
	v_pk_fma_f32 v[14:15], v[36:37], v[130:131], v[16:17] op_sel_hi:[0,1,1] neg_lo:[1,0,0] neg_hi:[1,0,0]
	v_and_b32_e32 v17, 0xffff0000, v4
	v_lshlrev_b32_e32 v16, 16, v4
	v_pk_mul_f32 v[24:25], v[52:53], v[16:17] op_sel_hi:[0,1]
	v_pk_fma_f32 v[14:15], v[52:53], v[16:17], v[14:15] op_sel_hi:[0,1,1]
	v_pk_fma_f32 v[14:15], v[14:15], s[0:1], v[24:25] op_sel_hi:[1,0,1] neg_lo:[0,0,1] neg_hi:[0,0,1]
	v_mul_f32_e32 v12, v52, v127
	v_pk_mul_f32 v[8:9], v[8:9], v[14:15]
	v_pk_fma_f32 v[14:15], v[36:37], v[40:41], v[18:19] op_sel_hi:[0,1,1] neg_lo:[1,0,0] neg_hi:[1,0,0]
	v_cvt_pk_bf16_f32 v4, v8, v9
	v_and_b32_e32 v9, 0xffff0000, v5
	v_lshlrev_b32_e32 v8, 16, v5
	v_pk_mul_f32 v[16:17], v[52:53], v[8:9] op_sel_hi:[0,1]
	v_pk_fma_f32 v[8:9], v[52:53], v[8:9], v[14:15] op_sel_hi:[0,1,1]
	v_pk_fma_f32 v[8:9], v[8:9], s[0:1], v[16:17] op_sel_hi:[1,0,1] neg_lo:[0,0,1] neg_hi:[0,0,1]
	v_mov_b32_e32 v13, v56
	v_pk_mul_f32 v[8:9], v[10:11], v[8:9]
	v_pk_mul_f32 v[10:11], v[52:53], v[6:7] op_sel_hi:[0,1]
	v_cvt_pk_bf16_f32 v5, v8, v9
	v_pk_fma_f32 v[8:9], v[36:37], v[38:39], v[22:23] op_sel_hi:[0,1,1] neg_lo:[1,0,0] neg_hi:[1,0,0]
	v_pk_fma_f32 v[6:7], v[52:53], v[6:7], v[8:9] op_sel_hi:[0,1,1]
	v_pk_fma_f32 v[6:7], v[6:7], s[0:1], v[10:11] op_sel_hi:[1,0,1] neg_lo:[0,0,1] neg_hi:[0,0,1]
	s_nop 0
	v_pk_mul_f32 v[0:1], v[0:1], v[6:7]
	s_nop 0
	v_cvt_pk_bf16_f32 v6, v0, v1
	v_pk_add_f32 v[0:1], v[20:21], v[54:55] neg_lo:[0,1] neg_hi:[0,1]
	s_nop 0
	v_pk_add_f32 v[0:1], v[12:13], v[0:1]
	s_nop 0
	v_pk_fma_f32 v[0:1], v[0:1], s[0:1], v[12:13] op_sel_hi:[1,0,1] neg_lo:[0,0,1] neg_hi:[0,0,1]
	s_nop 0
	v_pk_mul_f32 v[0:1], v[2:3], v[0:1]
	s_nop 0
	v_cvt_pk_bf16_f32 v7, v0, v1

.LBB0_2592:
	s_andn2_saveexec_b64 s[16:17], s[16:17]
	v_cmp_ne_u32_e32 vcc, 1, v1
	s_andn2_b64 s[0:1], s[4:5], exec
	s_and_b64 s[4:5], vcc, exec
	s_or_b64 s[4:5], s[0:1], s[4:5]
	s_mov_b64 s[14:15], exec
	s_or_b64 exec, exec, s[16:17]
	v_readlane_b32 s0, v254, 29
	v_or_b32_e32 v0, v65, v151
	v_add_u32_e32 v123, v151, v65
	v_readlane_b32 s1, v254, 30
	v_lshlrev_b32_e32 v118, 11, v0
	v_lshlrev_b32_e32 v145, 2, v0
	v_lshl_add_u64 v[120:121], v[112:113], 2, s[6:7]
	v_lshl_add_u64 v[116:117], v[112:113], 1, s[0:1]
	v_lshlrev_b32_e32 v143, 11, v123
	s_and_saveexec_b64 s[0:1], s[4:5]
	s_xor_b64 s[16:17], exec, s[0:1]
	s_cbranch_execz .LBB0_2596
	v_add_u32_e32 v140, v173, v151
	v_cmp_lt_u32_e32 vcc, 14, v151
	v_add_u32_e32 v0, 1, v140
	v_or_b32_e32 v1, 0x4001, v151
	v_cndmask_b32_e32 v0, v1, v0, vcc
	v_ashrrev_i32_e32 v1, 31, v0
	v_lshlrev_b64 v[2:3], 11, v[0:1]
	v_lshl_add_u64 v[2:3], v[114:115], 0, v[2:3]
	v_lshl_add_u64 v[0:1], v[0:1], 2, s[42:43]
	global_load_dwordx4 v[100:103], v[2:3], off
	global_load_dword v122, v[0:1], off
	v_cmp_lt_u32_e32 vcc, 12, v151
	v_add_u32_e32 v0, 3, v140
	v_or_b32_e32 v1, 0x4003, v151
	v_cndmask_b32_e32 v0, v1, v0, vcc
	v_ashrrev_i32_e32 v1, 31, v0
	v_lshlrev_b64 v[2:3], 11, v[0:1]
	v_lshl_add_u64 v[2:3], v[114:115], 0, v[2:3]
	v_lshl_add_u64 v[0:1], v[0:1], 2, s[42:43]
	global_load_dwordx4 v[36:39], v[2:3], off
	global_load_dword v134, v[0:1], off
	v_cmp_lt_u32_e32 vcc, 11, v151
	v_add_u32_e32 v0, 4, v140
	v_or_b32_e32 v1, 0x4004, v151
	v_cndmask_b32_e32 v0, v1, v0, vcc
	v_ashrrev_i32_e32 v1, 31, v0
	v_lshlrev_b64 v[2:3], 11, v[0:1]
	v_lshl_add_u64 v[2:3], v[114:115], 0, v[2:3]
	v_lshl_add_u64 v[0:1], v[0:1], 2, s[42:43]
	global_load_dwordx4 v[68:71], v[2:3], off
	global_load_dword v139, v[0:1], off
	v_cmp_lt_u32_e32 vcc, 10, v151
	v_add_u32_e32 v0, 5, v140
	v_or_b32_e32 v1, 0x4005, v151
	v_cndmask_b32_e32 v0, v1, v0, vcc
	v_ashrrev_i32_e32 v1, 31, v0
	v_lshlrev_b64 v[2:3], 11, v[0:1]
	v_lshl_add_u64 v[2:3], v[114:115], 0, v[2:3]
	v_lshl_add_u64 v[0:1], v[0:1], 2, s[42:43]
	global_load_dwordx4 v[64:67], v[2:3], off
	global_load_dword v137, v[0:1], off
	v_cmp_lt_u32_e32 vcc, 9, v151
	v_add_u32_e32 v0, 6, v140
	v_or_b32_e32 v1, 0x4006, v151
	v_cndmask_b32_e32 v0, v1, v0, vcc
	v_ashrrev_i32_e32 v1, 31, v0
	v_lshlrev_b64 v[2:3], 11, v[0:1]
	v_lshl_add_u64 v[2:3], v[114:115], 0, v[2:3]
	v_lshl_add_u64 v[0:1], v[0:1], 2, s[42:43]
	global_load_dwordx4 v[72:75], v[2:3], off
	global_load_dword v135, v[0:1], off
	v_cmp_lt_u32_e32 vcc, 8, v151
	v_add_u32_e32 v0, 7, v140
	v_or_b32_e32 v1, 0x4007, v151
	v_cndmask_b32_e32 v0, v1, v0, vcc
	v_ashrrev_i32_e32 v1, 31, v0
	v_lshlrev_b64 v[2:3], 11, v[0:1]
	v_lshl_add_u64 v[2:3], v[114:115], 0, v[2:3]
	v_lshl_add_u64 v[0:1], v[0:1], 2, s[42:43]
	global_load_dwordx4 v[76:79], v[2:3], off
	global_load_dword v133, v[0:1], off
	v_cmp_eq_u32_e32 vcc, 0, v151
	v_add_u32_e32 v0, 8, v140
	v_mov_b32_e32 v1, 0x4008
	v_cndmask_b32_e32 v0, v0, v1, vcc
	v_ashrrev_i32_e32 v1, 31, v0
	v_lshlrev_b64 v[2:3], 11, v[0:1]
	v_lshl_add_u64 v[2:3], v[114:115], 0, v[2:3]
	v_lshl_add_u64 v[0:1], v[0:1], 2, s[42:43]
	global_load_dwordx4 v[60:63], v[2:3], off
	global_load_dword v149, v[0:1], off
	v_add_u32_e32 v0, 9, v140
	v_mov_b32_e32 v1, 0x4009
	v_cndmask_b32_e32 v0, v0, v1, vcc
	v_ashrrev_i32_e32 v1, 31, v0
	v_lshlrev_b64 v[2:3], 11, v[0:1]
	v_lshl_add_u64 v[2:3], v[114:115], 0, v[2:3]
	v_lshl_add_u64 v[0:1], v[0:1], 2, s[42:43]
	global_load_dwordx4 v[56:59], v[2:3], off
	global_load_dword v148, v[0:1], off
	v_add_u32_e32 v0, 10, v140
	v_mov_b32_e32 v1, 0x400a
	v_cndmask_b32_e32 v0, v0, v1, vcc
	v_ashrrev_i32_e32 v1, 31, v0
	v_lshlrev_b64 v[2:3], 11, v[0:1]
	v_lshl_add_u64 v[2:3], v[114:115], 0, v[2:3]
	v_lshl_add_u64 v[0:1], v[0:1], 2, s[42:43]
	global_load_dwordx4 v[84:87], v[2:3], off
	global_load_dword v144, v[0:1], off
	v_add_u32_e32 v0, 11, v140
	v_mov_b32_e32 v1, 0x400b
	v_cndmask_b32_e32 v0, v0, v1, vcc
	v_ashrrev_i32_e32 v1, 31, v0
	v_lshlrev_b64 v[2:3], 11, v[0:1]
	v_lshl_add_u64 v[2:3], v[114:115], 0, v[2:3]
	v_lshl_add_u64 v[0:1], v[0:1], 2, s[42:43]
	global_load_dwordx4 v[92:95], v[2:3], off
	global_load_dword v146, v[0:1], off
	v_add_u32_e32 v0, 12, v140
	v_mov_b32_e32 v1, 0x400c
	v_cndmask_b32_e32 v0, v0, v1, vcc
	v_ashrrev_i32_e32 v1, 31, v0
	v_lshlrev_b64 v[2:3], 11, v[0:1]
	v_lshl_add_u64 v[2:3], v[114:115], 0, v[2:3]
	v_lshl_add_u64 v[0:1], v[0:1], 2, s[42:43]
	global_load_dwordx4 v[96:99], v[2:3], off
	global_load_dword v147, v[0:1], off
	v_add_u32_e32 v0, 13, v140
	v_mov_b32_e32 v1, 0x400d
	v_cndmask_b32_e32 v0, v0, v1, vcc
	v_ashrrev_i32_e32 v1, 31, v0
	v_lshlrev_b64 v[2:3], 11, v[0:1]
	v_lshl_add_u64 v[2:3], v[114:115], 0, v[2:3]
	v_lshl_add_u64 v[0:1], v[0:1], 2, s[42:43]
	global_load_dwordx4 v[40:43], v[2:3], off
	global_load_dword v138, v[0:1], off
	v_add_u32_e32 v0, 14, v140
	v_mov_b32_e32 v1, 0x400e
	v_cndmask_b32_e32 v0, v0, v1, vcc
	v_ashrrev_i32_e32 v1, 31, v0
	v_lshlrev_b64 v[2:3], 11, v[0:1]
	v_lshl_add_u64 v[2:3], v[114:115], 0, v[2:3]
	v_lshl_add_u64 v[0:1], v[0:1], 2, s[42:43]
	global_load_dwordx4 v[44:47], v[2:3], off
	global_load_dword v136, v[0:1], off
	v_add_u32_e32 v0, 15, v140
	v_mov_b32_e32 v1, 0x400f
	v_cndmask_b32_e32 v0, v0, v1, vcc
	v_ashrrev_i32_e32 v1, 31, v0
	v_lshlrev_b64 v[2:3], 11, v[0:1]
	v_lshl_add_u64 v[2:3], v[114:115], 0, v[2:3]
	v_lshl_add_u64 v[0:1], v[0:1], 2, s[42:43]
	v_mov_b32_e32 v119, v193
	global_load_dwordx4 v[48:51], v[2:3], off
	global_load_dword v132, v[0:1], off
	v_lshl_add_u64 v[0:1], v[114:115], 0, v[118:119]
	v_add_u32_e32 v192, 17, v140
	global_load_dwordx4 v[52:55], v[0:1], off
	v_lshlrev_b64 v[0:1], 11, v[192:193]
	v_lshl_add_u64 v[0:1], v[114:115], 0, v[0:1]
	v_add_u32_e32 v192, 18, v140
	global_load_dwordx4 v[32:35], v[0:1], off
	v_lshlrev_b64 v[0:1], 11, v[192:193]
	s_waitcnt vmcnt(28)
	v_fmamk_f32 v122, v122, 0x3a800000, v194
	v_lshl_add_u64 v[0:1], v[114:115], 0, v[0:1]
	v_add_u32_e32 v192, 19, v140
	v_cmp_gt_f32_e32 vcc, s2, v122
	global_load_dwordx4 v[28:31], v[0:1], off
	v_lshlrev_b64 v[0:1], 11, v[192:193]
	v_lshl_add_u64 v[0:1], v[114:115], 0, v[0:1]
	v_add_u32_e32 v192, 20, v140
	v_rsq_f32_e32 v122, v122
	global_load_dwordx4 v[24:27], v[0:1], off
	v_lshlrev_b64 v[0:1], 11, v[192:193]
	v_lshl_add_u64 v[0:1], v[114:115], 0, v[0:1]
	v_add_u32_e32 v192, 21, v140
	global_load_dwordx4 v[20:23], v[0:1], off
	global_load_dwordx4 v[80:83], v145, s[42:43] offset:16
	global_load_dwordx4 v[88:91], v145, s[42:43]
	v_lshlrev_b64 v[0:1], 11, v[192:193]
	v_lshl_add_u64 v[0:1], v[114:115], 0, v[0:1]
	v_add_u32_e32 v192, 22, v140
	global_load_dwordx4 v[16:19], v[0:1], off
	v_lshlrev_b64 v[0:1], 11, v[192:193]
	v_and_b32_e32 v131, 0xffff0000, v100
	v_lshlrev_b32_e32 v130, 16, v100
	v_and_b32_e32 v129, 0xffff0000, v101
	v_lshlrev_b32_e32 v128, 16, v101
	v_cmp_lt_u32_e32 vcc, 13, v151
	v_add_u32_e32 v100, 2, v140
	v_or_b32_e32 v101, 0x4002, v151
	v_lshl_add_u64 v[0:1], v[114:115], 0, v[0:1]
	v_add_u32_e32 v192, 23, v140
	v_cndmask_b32_e32 v100, v101, v100, vcc
	global_load_dwordx4 v[12:15], v[0:1], off
	v_lshlrev_b64 v[0:1], 11, v[192:193]
	v_ashrrev_i32_e32 v101, 31, v100
	v_lshl_add_u64 v[0:1], v[114:115], 0, v[0:1]
	v_and_b32_e32 v127, 0xffff0000, v102
	v_lshlrev_b32_e32 v126, 16, v102
	v_and_b32_e32 v125, 0xffff0000, v103
	v_lshlrev_b32_e32 v124, 16, v103
	v_lshl_add_u64 v[102:103], v[100:101], 2, s[42:43]
	global_load_dwordx4 v[4:7], v[0:1], off
	s_nop 0
	global_load_dwordx4 v[0:3], v[120:121], off offset:16
	global_load_dwordx4 v[8:11], v[120:121], off
	global_load_dword v140, v[102:103], off
	s_waitcnt vmcnt(37)
	v_fmamk_f32 v134, v134, 0x3a800000, v194
	s_waitcnt vmcnt(27)
	v_fmamk_f32 v149, v149, 0x3a800000, v194
	s_waitcnt vmcnt(25)
	v_fmamk_f32 v148, v148, 0x3a800000, v194
	s_waitcnt vmcnt(23)
	v_fmamk_f32 v144, v144, 0x3a800000, v194
	s_waitcnt vmcnt(21)
	v_fmamk_f32 v146, v146, 0x3a800000, v194
	v_lshlrev_b64 v[100:101], 11, v[100:101]
	v_lshl_add_u64 v[100:101], v[114:115], 0, v[100:101]
	global_load_dwordx4 v[100:103], v[100:101], off
	s_waitcnt vmcnt(20)
	v_fmamk_f32 v147, v147, 0x3a800000, v194
	s_waitcnt vmcnt(18)
	v_fmamk_f32 v138, v138, 0x3a800000, v194
	v_mov_b64_e32 v[190:191], s[24:25]
	v_and_b32_e32 v217, 0xffff0000, v84
	v_lshlrev_b32_e32 v216, 16, v84
	v_and_b32_e32 v211, 0xffff0000, v85
	v_lshlrev_b32_e32 v210, 16, v85
	v_and_b32_e32 v185, 0xffff0000, v86
	s_waitcnt vmcnt(16)
	v_fmamk_f32 v136, v136, 0x3a800000, v194
	v_lshlrev_b32_e32 v184, 16, v86
	v_and_b32_e32 v171, 0xffff0000, v87
	v_lshlrev_b32_e32 v170, 16, v87
	v_and_b32_e32 v209, 0xffff0000, v98
	v_lshlrev_b32_e32 v208, 16, v98
	v_and_b32_e32 v219, 0xffff0000, v92
	v_lshlrev_b32_e32 v218, 16, v92
	v_and_b32_e32 v213, 0xffff0000, v93
	v_lshlrev_b32_e32 v212, 16, v93
	s_waitcnt vmcnt(14)
	v_fmamk_f32 v132, v132, 0x3a800000, v194
	v_and_b32_e32 v199, 0xffff0000, v79
	v_and_b32_e32 v231, 0xffff0000, v36
	v_lshlrev_b32_e32 v230, 16, v36
	v_and_b32_e32 v229, 0xffff0000, v68
	v_lshlrev_b32_e32 v228, 16, v68
	v_and_b32_e32 v225, 0xffff0000, v72
	v_lshlrev_b32_e32 v224, 16, v72
	v_and_b32_e32 v227, 0xffff0000, v64
	v_lshlrev_b32_e32 v226, 16, v64
	v_and_b32_e32 v201, 0xffff0000, v60
	v_lshlrev_b32_e32 v200, 16, v60
	v_and_b32_e32 v233, 0xffff0000, v56
	v_lshlrev_b32_e32 v232, 16, v56
	v_and_b32_e32 v223, 0xffff0000, v76
	v_lshlrev_b32_e32 v222, 16, v76
	v_lshlrev_b32_e32 v64, 16, v77
	v_lshlrev_b32_e32 v157, 16, v67
	v_and_b32_e32 v237, 0xffff0000, v37
	v_lshlrev_b32_e32 v236, 16, v37
	v_lshlrev_b32_e32 v68, 16, v73
	v_lshlrev_b32_e32 v155, 16, v75
	v_and_b32_e32 v243, 0xffff0000, v70
	v_lshlrev_b32_e32 v242, 16, v70
	s_waitcnt vmcnt(7)
	v_pk_fma_f32 v[84:85], v[88:89], s[20:21], v[190:191] op_sel_hi:[1,0,0]
	v_lshlrev_b32_e32 v89, 16, v23
	v_cmp_gt_f32_e64 s[4:5], s2, v84
	v_lshlrev_b32_e32 v70, 16, v74
	v_and_b32_e32 v241, 0xffff0000, v66
	v_rsq_f32_e32 v84, v84
	v_lshlrev_b32_e32 v240, 16, v66
	v_lshlrev_b32_e32 v66, 16, v78
	v_lshlrev_b32_e32 v153, 16, v79
	v_mov_b32_e32 v186, v84
	v_pk_fma_f32 v[86:87], v[90:91], s[20:21], v[190:191] op_sel_hi:[1,0,0]
	v_cmp_gt_f32_e64 s[4:5], s2, v86
	v_and_b32_e32 v79, 0xffff0000, v62
	v_and_b32_e32 v221, 0xffff0000, v96
	v_rsq_f32_e32 v86, v86
	v_lshlrev_b32_e32 v220, 16, v96
	v_and_b32_e32 v215, 0xffff0000, v97
	v_lshlrev_b32_e32 v214, 16, v97
	v_mov_b32_e32 v98, v86
	s_waitcnt vmcnt(4)
	v_and_b32_e32 v198, 0xffff0000, v7
	s_waitcnt vmcnt(1)
	v_fmamk_f32 v140, v140, 0x3a800000, v194
	v_cmp_gt_f32_e32 vcc, s2, v140
	v_and_b32_e32 v189, 0xffff0000, v94
	v_rsq_f32_e32 v140, v140
	v_lshlrev_b32_e32 v188, 16, v94
	v_and_b32_e32 v175, 0xffff0000, v95
	v_lshlrev_b32_e32 v174, 16, v95
	v_mov_b32_e32 v142, v140
	v_cmp_gt_f32_e32 vcc, s2, v134
	s_waitcnt vmcnt(0)
	v_and_b32_e32 v235, 0xffff0000, v100
	v_rsq_f32_e32 v134, v134
	v_lshlrev_b32_e32 v234, 16, v100
	v_and_b32_e32 v239, 0xffff0000, v101
	v_lshlrev_b32_e32 v238, 16, v101
	v_mov_b32_e32 v140, v134
	v_cmp_gt_f32_e32 vcc, s2, v149
	v_lshlrev_b32_e32 v134, 16, v71
	v_and_b32_e32 v101, 0xffff0000, v65
	v_rsq_f32_e32 v149, v149
	v_lshlrev_b32_e32 v100, 16, v65
	v_and_b32_e32 v65, 0xffff0000, v77
	v_pk_fma_f32 v[76:77], v[122:123], v[128:129], 0 op_sel_hi:[0,1,0]
	v_mov_b32_e32 v150, v149
	v_cmp_gt_f32_e32 vcc, s2, v148
	v_pk_fma_f32 v[76:77], v[142:143], v[238:239], v[76:77] op_sel_hi:[0,1,1]
	v_rsq_f32_e32 v148, v148
	v_pk_fma_f32 v[76:77], v[140:141], v[236:237], v[76:77] op_sel_hi:[0,1,1]
	v_and_b32_e32 v245, 0xffff0000, v102
	v_lshlrev_b32_e32 v244, 16, v102
	v_mul_f32_e32 v149, 0x45800000, v148
	v_mov_b32_e32 v156, v148
	v_cmp_gt_f32_e32 vcc, s2, v144
	v_lshlrev_b32_e32 v102, 16, v63
	v_rsq_f32_e32 v144, v144
	v_and_b32_e32 v177, 0xffff0000, v99
	v_lshlrev_b32_e32 v176, 16, v99
	v_lshl_add_u64 v[164:165], v[116:117], 0, v[118:119]
	v_cmp_gt_f32_e32 vcc, s2, v146
	v_add_u32_e32 v192, 0x800, v143
	v_rsq_f32_e32 v146, v146
	v_lshl_add_u64 v[168:169], v[116:117], 0, v[192:193]
	v_add_u32_e32 v192, 0x1000, v143
	s_andn2_b64 s[14:15], s[14:15], exec
	v_cmp_gt_f32_e32 vcc, s2, v147
	s_nop 0
	v_rsq_f32_e32 v147, v147
	s_nop 0
	v_mov_b32_e32 v148, v147
	v_cmp_gt_f32_e32 vcc, s2, v138
	s_nop 0
	v_rsq_f32_e32 v138, v138
	s_nop 0
	v_mul_f32_e32 v147, 0x45800000, v138
	v_mov_b32_e32 v152, v138
	v_cmp_gt_f32_e32 vcc, s2, v136
	s_nop 0
	v_rsq_f32_e32 v136, v136
	s_nop 0
	v_mov_b32_e32 v154, v136
	v_cmp_gt_f32_e32 vcc, s2, v132
	v_mov_b32_e32 v138, v80
	v_rsq_f32_e32 v132, v132
	v_pk_fma_f32 v[90:91], v[138:139], s[20:21], v[190:191] op_sel_hi:[1,0,0]
	v_mov_b32_e32 v158, v132
	v_cmp_gt_f32_e32 vcc, s2, v85
	v_cmp_gt_f32_e64 s[4:5], s2, v91
	v_mov_b32_e32 v84, v85
	v_rsq_f32_e32 v84, v84
	v_mov_b32_e32 v80, v91
	v_rsq_f32_e32 v91, v80
	v_mov_b32_e32 v172, v84
	v_cmp_gt_f32_e32 vcc, s2, v87
	v_mov_b32_e32 v136, v81
	v_pk_fma_f32 v[136:137], v[136:137], s[20:21], v[190:191] op_sel_hi:[1,0,0]
	v_mov_b32_e32 v86, v87
	v_rsq_f32_e32 v86, v86
	v_mov_b32_e32 v132, v83
	v_pk_fma_f32 v[132:133], v[132:133], s[20:21], v[190:191] op_sel_hi:[1,0,0]
	v_lshl_add_u64 v[84:85], v[116:117], 0, v[192:193]
	v_mov_b32_e32 v88, v86
	v_cmp_gt_f32_e32 vcc, s2, v90
	v_add_u32_e32 v192, 0x1800, v143
	v_lshl_add_u64 v[86:87], v[116:117], 0, v[192:193]
	v_mov_b32_e32 v80, v90
	v_rsq_f32_e32 v90, v80
	v_add_u32_e32 v192, 0x2000, v143
	v_pk_mul_f32 v[92:93], v[90:91], s[22:23] op_sel_hi:[1,0]
	s_nop 0
	v_cndmask_b32_e64 v93, v91, v93, s[4:5]
	v_and_b32_e32 v91, 0xffff0000, v71
	v_cmp_gt_f32_e64 s[4:5], s2, v137
	v_cndmask_b32_e32 v92, v90, v92, vcc
	v_cmp_gt_f32_e32 vcc, s2, v136
	v_mov_b32_e32 v71, v137
	v_rsq_f32_e32 v137, v71
	v_mov_b32_e32 v71, v136
	v_rsq_f32_e32 v136, v71
	v_mul_f32_e32 v80, v93, v134
	v_mov_b32_e32 v134, v82
	v_and_b32_e32 v90, 0xffff0000, v23
	v_pk_mul_f32 v[138:139], v[136:137], s[22:23] op_sel_hi:[1,0]
	v_lshlrev_b32_e32 v23, 16, v19
	v_cndmask_b32_e32 v138, v136, v138, vcc
	v_pk_fma_f32 v[134:135], v[134:135], s[20:21], v[190:191] op_sel_hi:[1,0,0]
	v_cndmask_b32_e64 v139, v137, v139, s[4:5]
	v_mul_f32_e32 v162, v138, v23
	v_cmp_gt_f32_e64 s[4:5], s2, v135
	v_cmp_gt_f32_e32 vcc, s2, v134
	v_and_b32_e32 v136, 0xffff0000, v19
	v_mov_b32_e32 v23, v135
	v_rsq_f32_e32 v135, v23
	v_mov_b32_e32 v23, v134
	v_rsq_f32_e32 v134, v23
	v_lshlrev_b32_e32 v19, 16, v15
	v_mov_b32_e32 v72, v93
	v_mov_b32_e32 v60, v139
	v_pk_mul_f32 v[178:179], v[134:135], s[22:23] op_sel_hi:[1,0]
	v_and_b32_e32 v71, 0xffff0000, v74
	v_cndmask_b32_e32 v178, v134, v178, vcc
	v_cndmask_b32_e64 v179, v135, v179, s[4:5]
	v_mul_f32_e32 v180, v178, v19
	v_cmp_gt_f32_e64 s[4:5], s2, v133
	v_cmp_gt_f32_e32 vcc, s2, v132
	v_mov_b32_e32 v56, v179
	v_mov_b32_e32 v19, v133
	v_rsq_f32_e32 v133, v19
	v_mov_b32_e32 v19, v132
	v_rsq_f32_e32 v132, v19
	v_and_b32_e32 v135, 0xffff0000, v75
	v_pk_fma_f32 v[74:75], v[122:123], v[126:127], 0 op_sel_hi:[0,1,0]
	v_pk_fma_f32 v[74:75], v[142:143], v[244:245], v[74:75] op_sel_hi:[0,1,1]
	v_pk_mul_f32 v[190:191], v[132:133], s[22:23] op_sel_hi:[1,0]
	v_and_b32_e32 v137, 0xffff0000, v67
	v_cndmask_b32_e64 v133, v133, v191, s[4:5]
	v_cndmask_b32_e32 v132, v132, v190, vcc
	v_pk_mul_f32 v[206:207], v[132:133], v[198:199]
	v_pk_fma_f32 v[198:199], v[122:123], v[130:131], 0 op_sel_hi:[0,1,0]
	v_pk_fma_f32 v[198:199], v[142:143], v[234:235], v[198:199] op_sel_hi:[0,1,1]
	v_pk_fma_f32 v[198:199], v[140:141], v[230:231], v[198:199] op_sel_hi:[0,1,1]
	v_pk_fma_f32 v[198:199], v[72:73], v[228:229], v[198:199] op_sel_hi:[0,1,1]
	v_pk_fma_f32 v[198:199], v[60:61], v[226:227], v[198:199] op_sel_hi:[0,1,1]
	v_pk_fma_f32 v[198:199], v[56:57], v[224:225], v[198:199] op_sel_hi:[0,1,1]
	v_mov_b32_e32 v36, v133
	v_pk_fma_f32 v[198:199], v[36:37], v[222:223], v[198:199] op_sel_hi:[0,1,1]
	v_pk_fma_f32 v[198:199], v[150:151], v[200:201], v[198:199] op_sel_hi:[0,1,1]
	v_pk_fma_f32 v[246:247], v[156:157], v[232:233], v[198:199] op_sel_hi:[0,1,1]
	v_and_b32_e32 v233, 0xffff0000, v69
	v_lshlrev_b32_e32 v232, 16, v69
	v_pk_fma_f32 v[76:77], v[72:73], v[232:233], v[76:77] op_sel_hi:[0,1,1]
	v_and_b32_e32 v69, 0xffff0000, v73
	v_pk_fma_f32 v[76:77], v[60:61], v[100:101], v[76:77] op_sel_hi:[0,1,1]
	v_pk_fma_f32 v[76:77], v[56:57], v[68:69], v[76:77] op_sel_hi:[0,1,1]
	v_and_b32_e32 v199, 0xffff0000, v61
	v_lshlrev_b32_e32 v198, 16, v61
	v_pk_fma_f32 v[76:77], v[36:37], v[64:65], v[76:77] op_sel_hi:[0,1,1]
	v_and_b32_e32 v201, 0xffff0000, v57
	v_lshlrev_b32_e32 v200, 16, v57
	v_pk_fma_f32 v[76:77], v[150:151], v[198:199], v[76:77] op_sel_hi:[0,1,1]
	v_pk_fma_f32 v[248:249], v[156:157], v[200:201], v[76:77] op_sel_hi:[0,1,1]
	v_and_b32_e32 v77, 0xffff0000, v38
	v_lshlrev_b32_e32 v76, 16, v38
	v_pk_fma_f32 v[74:75], v[140:141], v[76:77], v[74:75] op_sel_hi:[0,1,1]
	v_pk_fma_f32 v[74:75], v[72:73], v[242:243], v[74:75] op_sel_hi:[0,1,1]
	v_pk_fma_f32 v[74:75], v[60:61], v[240:241], v[74:75] op_sel_hi:[0,1,1]
	v_and_b32_e32 v67, 0xffff0000, v78
	v_pk_fma_f32 v[74:75], v[56:57], v[70:71], v[74:75] op_sel_hi:[0,1,1]
	v_lshlrev_b32_e32 v78, 16, v62
	v_pk_fma_f32 v[74:75], v[36:37], v[66:67], v[74:75] op_sel_hi:[0,1,1]
	v_and_b32_e32 v199, 0xffff0000, v58
	v_lshlrev_b32_e32 v198, 16, v58
	v_pk_fma_f32 v[74:75], v[150:151], v[78:79], v[74:75] op_sel_hi:[0,1,1]
	v_pk_fma_f32 v[198:199], v[156:157], v[198:199], v[74:75] op_sel_hi:[0,1,1]
	v_and_b32_e32 v79, 0xffff0000, v103
	v_lshlrev_b32_e32 v78, 16, v103
	v_and_b32_e32 v75, 0xffff0000, v39
	v_lshlrev_b32_e32 v74, 16, v39
	v_pk_fma_f32 v[38:39], v[122:123], v[124:125], 0 op_sel_hi:[0,1,0]
	v_pk_mul_f32 v[96:97], v[92:93], v[90:91]
	v_pk_fma_f32 v[38:39], v[142:143], v[78:79], v[38:39] op_sel_hi:[0,1,1]
	v_pk_mul_f32 v[166:167], v[138:139], v[136:137]
	v_and_b32_e32 v134, 0xffff0000, v15
	v_pk_fma_f32 v[38:39], v[140:141], v[74:75], v[38:39] op_sel_hi:[0,1,1]
	v_mov_b32_e32 v81, v97
	v_mul_f32_e32 v160, v139, v157
	v_pk_mul_f32 v[182:183], v[178:179], v[134:135]
	v_pk_add_f32 v[38:39], v[80:81], v[38:39]
	v_mov_b32_e32 v161, v167
	v_mul_f32_e32 v82, v179, v155
	v_pk_add_f32 v[38:39], v[160:161], v[38:39]
	v_mov_b32_e32 v83, v183
	v_mul_f32_e32 v190, v133, v153
	v_pk_add_f32 v[38:39], v[82:83], v[38:39]
	v_mov_b32_e32 v191, v207
	v_and_b32_e32 v103, 0xffff0000, v63
	v_pk_add_f32 v[38:39], v[190:191], v[38:39]
	v_pk_fma_f32 v[216:217], v[144:145], v[216:217], v[246:247] op_sel_hi:[0,1,1]
	v_and_b32_e32 v63, 0xffff0000, v59
	v_lshlrev_b32_e32 v62, 16, v59
	v_pk_fma_f32 v[38:39], v[150:151], v[102:103], v[38:39] op_sel_hi:[0,1,1]
	v_pk_fma_f32 v[216:217], v[146:147], v[218:219], v[216:217] op_sel_hi:[0,1,1]
	v_pk_fma_f32 v[58:59], v[156:157], v[62:63], v[38:39] op_sel_hi:[0,1,1]
	v_and_b32_e32 v39, 0xffff0000, v40
	v_lshlrev_b32_e32 v38, 16, v40
	v_pk_fma_f32 v[216:217], v[148:149], v[220:221], v[216:217] op_sel_hi:[0,1,1]
	v_and_b32_e32 v63, 0xffff0000, v44
	v_lshlrev_b32_e32 v62, 16, v44
	v_pk_fma_f32 v[38:39], v[152:153], v[38:39], v[216:217] op_sel_hi:[0,1,1]
	v_and_b32_e32 v103, 0xffff0000, v48
	v_lshlrev_b32_e32 v102, 16, v48
	v_pk_fma_f32 v[38:39], v[154:155], v[62:63], v[38:39] op_sel_hi:[0,1,1]
	v_and_b32_e32 v157, 0xffff0000, v52
	v_lshlrev_b32_e32 v156, 16, v52
	v_pk_fma_f32 v[38:39], v[158:159], v[102:103], v[38:39] op_sel_hi:[0,1,1]
	v_pk_mul_f32 v[200:201], v[186:187], v[156:157] op_sel_hi:[0,1]
	v_pk_fma_f32 v[62:63], v[186:187], v[156:157], v[38:39] op_sel_hi:[0,1,1]
	v_pk_fma_f32 v[156:157], v[144:145], v[210:211], v[248:249] op_sel_hi:[0,1,1]
	v_pk_fma_f32 v[156:157], v[146:147], v[212:213], v[156:157] op_sel_hi:[0,1,1]
	v_and_b32_e32 v103, 0xffff0000, v41
	v_lshlrev_b32_e32 v102, 16, v41
	v_pk_fma_f32 v[156:157], v[148:149], v[214:215], v[156:157] op_sel_hi:[0,1,1]
	v_and_b32_e32 v41, 0xffff0000, v45
	v_lshlrev_b32_e32 v40, 16, v45
	v_pk_fma_f32 v[102:103], v[152:153], v[102:103], v[156:157] op_sel_hi:[0,1,1]
	v_and_b32_e32 v45, 0xffff0000, v49
	v_lshlrev_b32_e32 v44, 16, v49
	v_pk_fma_f32 v[40:41], v[154:155], v[40:41], v[102:103] op_sel_hi:[0,1,1]
	v_and_b32_e32 v49, 0xffff0000, v53
	v_lshlrev_b32_e32 v48, 16, v53
	v_pk_fma_f32 v[40:41], v[158:159], v[44:45], v[40:41] op_sel_hi:[0,1,1]
	v_pk_mul_f32 v[52:53], v[186:187], v[48:49] op_sel_hi:[0,1]
	v_pk_fma_f32 v[44:45], v[186:187], v[48:49], v[40:41] op_sel_hi:[0,1,1]
	v_pk_fma_f32 v[38:39], v[62:63], s[26:27], v[200:201] op_sel_hi:[1,0,1] neg_lo:[0,0,1] neg_hi:[0,0,1]
	v_pk_fma_f32 v[40:41], v[44:45], s[26:27], v[52:53] op_sel_hi:[1,0,1] neg_lo:[0,0,1] neg_hi:[0,0,1]
	v_pk_fma_f32 v[184:185], v[144:145], v[184:185], v[198:199] op_sel_hi:[0,1,1]
	v_pk_mul_f32 v[38:39], v[8:9], v[38:39]
	v_pk_mul_f32 v[40:41], v[10:11], v[40:41]
	v_pk_fma_f32 v[184:185], v[146:147], v[188:189], v[184:185] op_sel_hi:[0,1,1]
	v_cvt_pk_bf16_f32 v38, v38, v39
	v_cvt_pk_bf16_f32 v39, v40, v41
	v_and_b32_e32 v41, 0xffff0000, v42
	v_lshlrev_b32_e32 v40, 16, v42
	v_pk_fma_f32 v[184:185], v[148:149], v[208:209], v[184:185] op_sel_hi:[0,1,1]
	v_and_b32_e32 v49, 0xffff0000, v46
	v_lshlrev_b32_e32 v48, 16, v46
	v_pk_fma_f32 v[40:41], v[152:153], v[40:41], v[184:185] op_sel_hi:[0,1,1]
	v_pk_fma_f32 v[58:59], v[144:145], v[170:171], v[58:59] op_sel_hi:[0,1,1]
	v_and_b32_e32 v53, 0xffff0000, v50
	v_lshlrev_b32_e32 v52, 16, v50
	v_pk_fma_f32 v[40:41], v[154:155], v[48:49], v[40:41] op_sel_hi:[0,1,1]
	v_pk_fma_f32 v[58:59], v[146:147], v[174:175], v[58:59] op_sel_hi:[0,1,1]
	v_pk_fma_f32 v[40:41], v[158:159], v[52:53], v[40:41] op_sel_hi:[0,1,1]
	v_and_b32_e32 v53, 0xffff0000, v43
	v_lshlrev_b32_e32 v52, 16, v43
	v_pk_fma_f32 v[58:59], v[148:149], v[176:177], v[58:59] op_sel_hi:[0,1,1]
	v_and_b32_e32 v43, 0xffff0000, v47
	v_lshlrev_b32_e32 v42, 16, v47
	v_pk_fma_f32 v[52:53], v[152:153], v[52:53], v[58:59] op_sel_hi:[0,1,1]
	v_and_b32_e32 v47, 0xffff0000, v51
	v_lshlrev_b32_e32 v46, 16, v51
	v_pk_fma_f32 v[42:43], v[154:155], v[42:43], v[52:53] op_sel_hi:[0,1,1]
	v_and_b32_e32 v103, 0xffff0000, v54
	v_lshlrev_b32_e32 v102, 16, v54
	v_and_b32_e32 v51, 0xffff0000, v55
	v_lshlrev_b32_e32 v50, 16, v55
	v_pk_fma_f32 v[42:43], v[158:159], v[46:47], v[42:43] op_sel_hi:[0,1,1]
	v_pk_mul_f32 v[156:157], v[186:187], v[102:103] op_sel_hi:[0,1]
	v_pk_fma_f32 v[48:49], v[186:187], v[102:103], v[40:41] op_sel_hi:[0,1,1]
	v_pk_mul_f32 v[54:55], v[186:187], v[50:51] op_sel_hi:[0,1]
	v_pk_fma_f32 v[42:43], v[186:187], v[50:51], v[42:43] op_sel_hi:[0,1,1]
	v_pk_fma_f32 v[40:41], v[48:49], s[26:27], v[156:157] op_sel_hi:[1,0,1] neg_lo:[0,0,1] neg_hi:[0,0,1]
	v_pk_fma_f32 v[46:47], v[42:43], s[26:27], v[54:55] op_sel_hi:[1,0,1] neg_lo:[0,0,1] neg_hi:[0,0,1]
	v_pk_mul_f32 v[40:41], v[0:1], v[40:41]
	v_pk_mul_f32 v[46:47], v[2:3], v[46:47]
	v_cvt_pk_bf16_f32 v40, v40, v41
	v_cvt_pk_bf16_f32 v41, v46, v47
	global_store_dwordx4 v[164:165], v[38:41], off
	v_pk_fma_f32 v[46:47], v[122:123], v[130:131], v[62:63] op_sel_hi:[0,1,1] neg_lo:[1,0,0] neg_hi:[1,0,0]
	v_pk_fma_f32 v[44:45], v[122:123], v[128:129], v[44:45] op_sel_hi:[0,1,1] neg_lo:[1,0,0] neg_hi:[1,0,0]
	v_and_b32_e32 v39, 0xffff0000, v32
	v_lshlrev_b32_e32 v38, 16, v32
	v_pk_mul_f32 v[40:41], v[172:173], v[38:39] op_sel_hi:[0,1]
	v_pk_fma_f32 v[38:39], v[172:173], v[38:39], v[46:47] op_sel_hi:[0,1,1]
	v_pk_fma_f32 v[40:41], v[38:39], s[26:27], v[40:41] op_sel_hi:[1,0,1] neg_lo:[0,0,1] neg_hi:[0,0,1]
	v_pk_fma_f32 v[48:49], v[122:123], v[126:127], v[48:49] op_sel_hi:[0,1,1] neg_lo:[1,0,0] neg_hi:[1,0,0]
	v_pk_mul_f32 v[40:41], v[8:9], v[40:41]
	v_pk_fma_f32 v[42:43], v[122:123], v[124:125], v[42:43] op_sel_hi:[0,1,1] neg_lo:[1,0,0] neg_hi:[1,0,0]
	v_cvt_pk_bf16_f32 v32, v40, v41
	v_and_b32_e32 v41, 0xffff0000, v33
	v_lshlrev_b32_e32 v40, 16, v33
	v_pk_mul_f32 v[46:47], v[172:173], v[40:41] op_sel_hi:[0,1]
	v_pk_fma_f32 v[40:41], v[172:173], v[40:41], v[44:45] op_sel_hi:[0,1,1]
	v_pk_fma_f32 v[44:45], v[40:41], s[26:27], v[46:47] op_sel_hi:[1,0,1] neg_lo:[0,0,1] neg_hi:[0,0,1]
	v_pk_fma_f32 v[38:39], v[142:143], v[234:235], v[38:39] op_sel_hi:[0,1,1] neg_lo:[1,0,0] neg_hi:[1,0,0]
	v_pk_mul_f32 v[44:45], v[10:11], v[44:45]
	v_pk_fma_f32 v[40:41], v[142:143], v[238:239], v[40:41] op_sel_hi:[0,1,1] neg_lo:[1,0,0] neg_hi:[1,0,0]
	v_cvt_pk_bf16_f32 v33, v44, v45
	v_and_b32_e32 v45, 0xffff0000, v34
	v_lshlrev_b32_e32 v44, 16, v34
	v_pk_mul_f32 v[46:47], v[172:173], v[44:45] op_sel_hi:[0,1]
	v_pk_fma_f32 v[44:45], v[172:173], v[44:45], v[48:49] op_sel_hi:[0,1,1]
	v_pk_fma_f32 v[46:47], v[44:45], s[26:27], v[46:47] op_sel_hi:[1,0,1] neg_lo:[0,0,1] neg_hi:[0,0,1]
	v_pk_fma_f32 v[44:45], v[142:143], v[244:245], v[44:45] op_sel_hi:[0,1,1] neg_lo:[1,0,0] neg_hi:[1,0,0]
	v_pk_mul_f32 v[46:47], v[0:1], v[46:47]
	v_and_b32_e32 v23, 0xffff0000, v22
	v_cvt_pk_bf16_f32 v34, v46, v47
	v_and_b32_e32 v47, 0xffff0000, v35
	v_lshlrev_b32_e32 v46, 16, v35
	v_pk_mul_f32 v[48:49], v[172:173], v[46:47] op_sel_hi:[0,1]
	v_pk_fma_f32 v[42:43], v[172:173], v[46:47], v[42:43] op_sel_hi:[0,1,1]
	v_pk_fma_f32 v[46:47], v[42:43], s[26:27], v[48:49] op_sel_hi:[1,0,1] neg_lo:[0,0,1] neg_hi:[0,0,1]
	v_pk_fma_f32 v[42:43], v[142:143], v[78:79], v[42:43] op_sel_hi:[0,1,1] neg_lo:[1,0,0] neg_hi:[1,0,0]
	v_pk_mul_f32 v[46:47], v[2:3], v[46:47]
	v_lshlrev_b32_e32 v22, 16, v22
	v_cvt_pk_bf16_f32 v35, v46, v47
	global_store_dwordx4 v[168:169], v[32:35], off
	v_mul_f32_e32 v94, v92, v89
	v_mov_b32_e32 v95, v96
	v_and_b32_e32 v33, 0xffff0000, v28
	v_lshlrev_b32_e32 v32, 16, v28
	v_pk_mul_f32 v[34:35], v[98:99], v[32:33] op_sel_hi:[0,1]
	v_pk_fma_f32 v[32:33], v[98:99], v[32:33], v[38:39] op_sel_hi:[0,1,1]
	v_pk_fma_f32 v[34:35], v[32:33], s[26:27], v[34:35] op_sel_hi:[1,0,1] neg_lo:[0,0,1] neg_hi:[0,0,1]
	v_pk_fma_f32 v[32:33], v[140:141], v[230:231], v[32:33] op_sel_hi:[0,1,1] neg_lo:[1,0,0] neg_hi:[1,0,0]
	v_pk_mul_f32 v[34:35], v[8:9], v[34:35]
	v_lshl_add_u64 v[90:91], v[116:117], 0, v[192:193]
	v_cvt_pk_bf16_f32 v28, v34, v35
	v_and_b32_e32 v35, 0xffff0000, v29
	v_lshlrev_b32_e32 v34, 16, v29
	v_pk_mul_f32 v[38:39], v[98:99], v[34:35] op_sel_hi:[0,1]
	v_pk_fma_f32 v[34:35], v[98:99], v[34:35], v[40:41] op_sel_hi:[0,1,1]
	v_pk_fma_f32 v[38:39], v[34:35], s[26:27], v[38:39] op_sel_hi:[1,0,1] neg_lo:[0,0,1] neg_hi:[0,0,1]
	v_pk_fma_f32 v[34:35], v[140:141], v[236:237], v[34:35] op_sel_hi:[0,1,1] neg_lo:[1,0,0] neg_hi:[1,0,0]
	v_pk_mul_f32 v[38:39], v[10:11], v[38:39]
	v_and_b32_e32 v19, 0xffff0000, v18
	v_cvt_pk_bf16_f32 v29, v38, v39
	v_and_b32_e32 v39, 0xffff0000, v30
	v_lshlrev_b32_e32 v38, 16, v30
	v_pk_mul_f32 v[40:41], v[98:99], v[38:39] op_sel_hi:[0,1]
	v_pk_fma_f32 v[38:39], v[98:99], v[38:39], v[44:45] op_sel_hi:[0,1,1]
	v_pk_fma_f32 v[40:41], v[38:39], s[26:27], v[40:41] op_sel_hi:[1,0,1] neg_lo:[0,0,1] neg_hi:[0,0,1]
	v_pk_fma_f32 v[38:39], v[140:141], v[76:77], v[38:39] op_sel_hi:[0,1,1] neg_lo:[1,0,0] neg_hi:[1,0,0]
	v_pk_mul_f32 v[40:41], v[0:1], v[40:41]
	v_lshlrev_b32_e32 v18, 16, v18
	v_cvt_pk_bf16_f32 v30, v40, v41
	v_and_b32_e32 v41, 0xffff0000, v31
	v_lshlrev_b32_e32 v40, 16, v31
	v_pk_mul_f32 v[44:45], v[98:99], v[40:41] op_sel_hi:[0,1]
	v_pk_fma_f32 v[40:41], v[98:99], v[40:41], v[42:43] op_sel_hi:[0,1,1]
	v_pk_fma_f32 v[42:43], v[40:41], s[26:27], v[44:45] op_sel_hi:[1,0,1] neg_lo:[0,0,1] neg_hi:[0,0,1]
	v_pk_fma_f32 v[40:41], v[140:141], v[74:75], v[40:41] op_sel_hi:[0,1,1] neg_lo:[1,0,0] neg_hi:[1,0,0]
	v_pk_mul_f32 v[42:43], v[2:3], v[42:43]
	v_mov_b32_e32 v163, v166
	v_cvt_pk_bf16_f32 v31, v42, v43
	global_store_dwordx4 v[84:85], v[28:31], off
	v_add_u32_e32 v192, 0x2800, v143
	v_lshl_add_u64 v[136:137], v[116:117], 0, v[192:193]
	v_and_b32_e32 v29, 0xffff0000, v24
	v_lshlrev_b32_e32 v28, 16, v24
	v_pk_mul_f32 v[30:31], v[88:89], v[28:29] op_sel_hi:[0,1]
	v_pk_fma_f32 v[28:29], v[88:89], v[28:29], v[32:33] op_sel_hi:[0,1,1]
	v_pk_fma_f32 v[30:31], v[28:29], s[26:27], v[30:31] op_sel_hi:[1,0,1] neg_lo:[0,0,1] neg_hi:[0,0,1]
	v_pk_fma_f32 v[28:29], v[72:73], v[228:229], v[28:29] op_sel_hi:[0,1,1] neg_lo:[1,0,0] neg_hi:[1,0,0]
	v_pk_mul_f32 v[30:31], v[8:9], v[30:31]
	v_mov_b32_e32 v181, v182
	v_cvt_pk_bf16_f32 v24, v30, v31
	v_and_b32_e32 v31, 0xffff0000, v25
	v_lshlrev_b32_e32 v30, 16, v25
	v_pk_mul_f32 v[32:33], v[88:89], v[30:31] op_sel_hi:[0,1]
	v_pk_fma_f32 v[30:31], v[88:89], v[30:31], v[34:35] op_sel_hi:[0,1,1]
	v_pk_fma_f32 v[32:33], v[30:31], s[26:27], v[32:33] op_sel_hi:[1,0,1] neg_lo:[0,0,1] neg_hi:[0,0,1]
	v_pk_fma_f32 v[30:31], v[72:73], v[232:233], v[30:31] op_sel_hi:[0,1,1] neg_lo:[1,0,0] neg_hi:[1,0,0]
	v_pk_mul_f32 v[32:33], v[10:11], v[32:33]
	v_add_u32_e32 v192, 0x3000, v143
	v_cvt_pk_bf16_f32 v25, v32, v33
	v_and_b32_e32 v33, 0xffff0000, v26
	v_lshlrev_b32_e32 v32, 16, v26
	v_pk_mul_f32 v[34:35], v[88:89], v[32:33] op_sel_hi:[0,1]
	v_pk_fma_f32 v[32:33], v[88:89], v[32:33], v[38:39] op_sel_hi:[0,1,1]
	v_pk_fma_f32 v[34:35], v[32:33], s[26:27], v[34:35] op_sel_hi:[1,0,1] neg_lo:[0,0,1] neg_hi:[0,0,1]
	v_lshl_add_u64 v[134:135], v[116:117], 0, v[192:193]
	v_pk_mul_f32 v[34:35], v[0:1], v[34:35]
	v_lshlrev_b32_e32 v15, 16, v7
	v_cvt_pk_bf16_f32 v26, v34, v35
	v_and_b32_e32 v35, 0xffff0000, v27
	v_lshlrev_b32_e32 v34, 16, v27
	v_pk_mul_f32 v[38:39], v[88:89], v[34:35] op_sel_hi:[0,1]
	v_pk_fma_f32 v[34:35], v[88:89], v[34:35], v[40:41] op_sel_hi:[0,1,1]
	v_pk_fma_f32 v[38:39], v[34:35], s[26:27], v[38:39] op_sel_hi:[1,0,1] neg_lo:[0,0,1] neg_hi:[0,0,1]
	v_and_b32_e32 v7, 0xffff0000, v6
	v_pk_mul_f32 v[38:39], v[2:3], v[38:39]
	v_lshlrev_b32_e32 v6, 16, v6
	v_cvt_pk_bf16_f32 v27, v38, v39
	global_store_dwordx4 v[86:87], v[24:27], off
	v_add_u32_e32 v192, 7, v123
	s_nop 0
	v_and_b32_e32 v25, 0xffff0000, v20
	v_lshlrev_b32_e32 v24, 16, v20
	v_pk_mul_f32 v[26:27], v[92:93], v[24:25] op_sel_hi:[0,1]
	v_pk_fma_f32 v[24:25], v[92:93], v[24:25], v[28:29] op_sel_hi:[0,1,1]
	v_pk_fma_f32 v[26:27], v[24:25], s[26:27], v[26:27] op_sel_hi:[1,0,1] neg_lo:[0,0,1] neg_hi:[0,0,1]
	v_pk_fma_f32 v[24:25], v[60:61], v[226:227], v[24:25] op_sel_hi:[0,1,1] neg_lo:[1,0,0] neg_hi:[1,0,0]
	v_pk_mul_f32 v[26:27], v[8:9], v[26:27]
	s_nop 0
	v_cvt_pk_bf16_f32 v20, v26, v27
	v_and_b32_e32 v27, 0xffff0000, v21
	v_lshlrev_b32_e32 v26, 16, v21
	v_pk_mul_f32 v[28:29], v[92:93], v[26:27] op_sel_hi:[0,1]
	v_pk_fma_f32 v[26:27], v[92:93], v[26:27], v[30:31] op_sel_hi:[0,1,1]
	v_pk_fma_f32 v[28:29], v[26:27], s[26:27], v[28:29] op_sel_hi:[1,0,1] neg_lo:[0,0,1] neg_hi:[0,0,1]
	v_pk_fma_f32 v[30:31], v[72:73], v[242:243], v[32:33] op_sel_hi:[0,1,1] neg_lo:[1,0,0] neg_hi:[1,0,0]
	v_pk_mul_f32 v[28:29], v[10:11], v[28:29]
	v_pk_fma_f32 v[30:31], v[92:93], v[22:23], v[30:31] op_sel_hi:[0,1,1]
	v_cvt_pk_bf16_f32 v21, v28, v29
	v_pk_mul_f32 v[28:29], v[92:93], v[22:23] op_sel_hi:[0,1]
	v_pk_fma_f32 v[22:23], v[30:31], s[26:27], v[28:29] op_sel_hi:[1,0,1] neg_lo:[0,0,1] neg_hi:[0,0,1]
	v_pk_add_f32 v[28:29], v[34:35], v[80:81] neg_lo:[0,1] neg_hi:[0,1]
	v_pk_mul_f32 v[22:23], v[0:1], v[22:23]
	v_pk_add_f32 v[28:29], v[94:95], v[28:29]
	v_cvt_pk_bf16_f32 v22, v22, v23
	v_pk_fma_f32 v[32:33], v[28:29], s[26:27], v[94:95] op_sel_hi:[1,0,1] neg_lo:[0,0,1] neg_hi:[0,0,1]
	v_pk_fma_f32 v[26:27], v[60:61], v[100:101], v[26:27] op_sel_hi:[0,1,1] neg_lo:[1,0,0] neg_hi:[1,0,0]
	v_pk_mul_f32 v[32:33], v[2:3], v[32:33]
	s_nop 0
	v_cvt_pk_bf16_f32 v23, v32, v33
	global_store_dwordx4 v[90:91], v[20:23], off
	s_nop 1
	v_and_b32_e32 v21, 0xffff0000, v16
	v_lshlrev_b32_e32 v20, 16, v16
	v_pk_mul_f32 v[22:23], v[138:139], v[20:21] op_sel_hi:[0,1]
	v_pk_fma_f32 v[20:21], v[138:139], v[20:21], v[24:25] op_sel_hi:[0,1,1]
	v_pk_fma_f32 v[22:23], v[20:21], s[26:27], v[22:23] op_sel_hi:[1,0,1] neg_lo:[0,0,1] neg_hi:[0,0,1]
	v_pk_fma_f32 v[20:21], v[56:57], v[224:225], v[20:21] op_sel_hi:[0,1,1] neg_lo:[1,0,0] neg_hi:[1,0,0]
	v_pk_mul_f32 v[22:23], v[8:9], v[22:23]
	s_nop 0
	v_cvt_pk_bf16_f32 v16, v22, v23
	v_and_b32_e32 v23, 0xffff0000, v17
	v_lshlrev_b32_e32 v22, 16, v17
	v_pk_mul_f32 v[24:25], v[138:139], v[22:23] op_sel_hi:[0,1]
	v_pk_fma_f32 v[22:23], v[138:139], v[22:23], v[26:27] op_sel_hi:[0,1,1]
	v_pk_fma_f32 v[24:25], v[22:23], s[26:27], v[24:25] op_sel_hi:[1,0,1] neg_lo:[0,0,1] neg_hi:[0,0,1]
	v_pk_fma_f32 v[26:27], v[60:61], v[240:241], v[30:31] op_sel_hi:[0,1,1] neg_lo:[1,0,0] neg_hi:[1,0,0]
	v_pk_mul_f32 v[24:25], v[10:11], v[24:25]
	v_pk_fma_f32 v[26:27], v[138:139], v[18:19], v[26:27] op_sel_hi:[0,1,1]
	v_cvt_pk_bf16_f32 v17, v24, v25
	v_pk_mul_f32 v[24:25], v[138:139], v[18:19] op_sel_hi:[0,1]
	v_pk_fma_f32 v[18:19], v[26:27], s[26:27], v[24:25] op_sel_hi:[1,0,1] neg_lo:[0,0,1] neg_hi:[0,0,1]
	v_pk_add_f32 v[24:25], v[28:29], v[160:161] neg_lo:[0,1] neg_hi:[0,1]
	v_pk_mul_f32 v[18:19], v[0:1], v[18:19]
	v_pk_add_f32 v[24:25], v[162:163], v[24:25]
	v_cvt_pk_bf16_f32 v18, v18, v19
	v_pk_fma_f32 v[28:29], v[24:25], s[26:27], v[162:163] op_sel_hi:[1,0,1] neg_lo:[0,0,1] neg_hi:[0,0,1]
	v_pk_fma_f32 v[22:23], v[56:57], v[68:69], v[22:23] op_sel_hi:[0,1,1] neg_lo:[1,0,0] neg_hi:[1,0,0]
	v_pk_mul_f32 v[28:29], v[2:3], v[28:29]
	v_pk_fma_f32 v[26:27], v[56:57], v[70:71], v[26:27] op_sel_hi:[0,1,1] neg_lo:[1,0,0] neg_hi:[1,0,0]
	v_cvt_pk_bf16_f32 v19, v28, v29
	global_store_dwordx4 v[136:137], v[16:19], off
	v_pk_add_f32 v[24:25], v[24:25], v[82:83] neg_lo:[0,1] neg_hi:[0,1]
	s_nop 0
	v_and_b32_e32 v17, 0xffff0000, v12
	v_lshlrev_b32_e32 v16, 16, v12
	v_pk_mul_f32 v[18:19], v[178:179], v[16:17] op_sel_hi:[0,1]
	v_pk_fma_f32 v[20:21], v[178:179], v[16:17], v[20:21] op_sel_hi:[0,1,1]
	v_pk_fma_f32 v[16:17], v[20:21], s[26:27], v[18:19] op_sel_hi:[1,0,1] neg_lo:[0,0,1] neg_hi:[0,0,1]
	v_and_b32_e32 v19, 0xffff0000, v13
	v_lshlrev_b32_e32 v18, 16, v13
	v_pk_mul_f32 v[12:13], v[178:179], v[18:19] op_sel_hi:[0,1]
	v_pk_fma_f32 v[22:23], v[178:179], v[18:19], v[22:23] op_sel_hi:[0,1,1]
	v_pk_fma_f32 v[12:13], v[22:23], s[26:27], v[12:13] op_sel_hi:[1,0,1] neg_lo:[0,0,1] neg_hi:[0,0,1]
	v_pk_mul_f32 v[16:17], v[8:9], v[16:17]
	v_pk_mul_f32 v[12:13], v[10:11], v[12:13]
	v_cvt_pk_bf16_f32 v16, v16, v17
	v_cvt_pk_bf16_f32 v17, v12, v13
	v_and_b32_e32 v13, 0xffff0000, v14
	v_lshlrev_b32_e32 v12, 16, v14
	v_pk_mul_f32 v[18:19], v[178:179], v[12:13] op_sel_hi:[0,1]
	v_pk_fma_f32 v[12:13], v[178:179], v[12:13], v[26:27] op_sel_hi:[0,1,1]
	v_pk_add_f32 v[24:25], v[180:181], v[24:25]
	v_pk_fma_f32 v[18:19], v[12:13], s[26:27], v[18:19] op_sel_hi:[1,0,1] neg_lo:[0,0,1] neg_hi:[0,0,1]
	v_pk_fma_f32 v[26:27], v[24:25], s[26:27], v[180:181] op_sel_hi:[1,0,1] neg_lo:[0,0,1] neg_hi:[0,0,1]
	v_pk_mul_f32 v[18:19], v[0:1], v[18:19]
	v_pk_mul_f32 v[26:27], v[2:3], v[26:27]
	v_cvt_pk_bf16_f32 v18, v18, v19
	v_cvt_pk_bf16_f32 v19, v26, v27
	global_store_dwordx4 v[134:135], v[16:19], off
	v_mul_f32_e32 v14, v132, v15
	v_mov_b32_e32 v15, v206
	v_pk_fma_f32 v[16:17], v[36:37], v[222:223], v[20:21] op_sel_hi:[0,1,1] neg_lo:[1,0,0] neg_hi:[1,0,0]
	v_and_b32_e32 v19, 0xffff0000, v4
	v_lshlrev_b32_e32 v18, 16, v4
	v_pk_mul_f32 v[20:21], v[132:133], v[18:19] op_sel_hi:[0,1]
	v_pk_fma_f32 v[16:17], v[132:133], v[18:19], v[16:17] op_sel_hi:[0,1,1]
	v_pk_fma_f32 v[16:17], v[16:17], s[26:27], v[20:21] op_sel_hi:[1,0,1] neg_lo:[0,0,1] neg_hi:[0,0,1]
	s_nop 0
	v_pk_mul_f32 v[8:9], v[8:9], v[16:17]
	v_pk_fma_f32 v[16:17], v[36:37], v[64:65], v[22:23] op_sel_hi:[0,1,1] neg_lo:[1,0,0] neg_hi:[1,0,0]
	v_cvt_pk_bf16_f32 v4, v8, v9
	v_and_b32_e32 v9, 0xffff0000, v5
	v_lshlrev_b32_e32 v8, 16, v5
	v_pk_mul_f32 v[18:19], v[132:133], v[8:9] op_sel_hi:[0,1]
	v_pk_fma_f32 v[8:9], v[132:133], v[8:9], v[16:17] op_sel_hi:[0,1,1]
	v_pk_fma_f32 v[8:9], v[8:9], s[26:27], v[18:19] op_sel_hi:[1,0,1] neg_lo:[0,0,1] neg_hi:[0,0,1]
	s_nop 0
	v_pk_mul_f32 v[8:9], v[10:11], v[8:9]
	v_pk_mul_f32 v[10:11], v[132:133], v[6:7] op_sel_hi:[0,1]
	v_cvt_pk_bf16_f32 v5, v8, v9
	v_pk_fma_f32 v[8:9], v[36:37], v[66:67], v[12:13] op_sel_hi:[0,1,1] neg_lo:[1,0,0] neg_hi:[1,0,0]
	v_pk_fma_f32 v[6:7], v[132:133], v[6:7], v[8:9] op_sel_hi:[0,1,1]
	v_pk_fma_f32 v[6:7], v[6:7], s[26:27], v[10:11] op_sel_hi:[1,0,1] neg_lo:[0,0,1] neg_hi:[0,0,1]
	s_nop 0
	v_pk_mul_f32 v[0:1], v[0:1], v[6:7]
	s_nop 0
	v_cvt_pk_bf16_f32 v6, v0, v1
	v_pk_add_f32 v[0:1], v[24:25], v[190:191] neg_lo:[0,1] neg_hi:[0,1]
	s_nop 0
	v_pk_add_f32 v[0:1], v[14:15], v[0:1]
	s_nop 0
	v_pk_fma_f32 v[0:1], v[0:1], s[26:27], v[14:15] op_sel_hi:[1,0,1] neg_lo:[0,0,1] neg_hi:[0,0,1]
	s_nop 0
	v_pk_mul_f32 v[0:1], v[2:3], v[0:1]
	s_nop 0
	v_cvt_pk_bf16_f32 v7, v0, v1
.LBB0_2596:
	s_or_b64 exec, exec, s[16:17]
	s_and_saveexec_b64 s[16:17], s[14:15]
	s_cbranch_execz .LBB0_2598
	v_add_u32_e32 v56, v151, v173
	v_cmp_eq_u32_e32 vcc, 0, v151
	v_add_u32_e32 v0, 13, v56
	v_mov_b32_e32 v1, 0x400d
	v_cndmask_b32_e32 v0, v0, v1, vcc
	v_ashrrev_i32_e32 v1, 31, v0
	v_lshlrev_b64 v[2:3], 11, v[0:1]
	v_lshl_add_u64 v[2:3], v[114:115], 0, v[2:3]
	v_lshl_add_u64 v[0:1], v[0:1], 2, s[42:43]
	global_load_dwordx4 v[44:47], v[2:3], off
	global_load_dword v57, v[0:1], off
	v_add_u32_e32 v0, 15, v56
	v_mov_b32_e32 v1, 0x400f
	v_cndmask_b32_e32 v0, v0, v1, vcc
	v_ashrrev_i32_e32 v1, 31, v0
	v_lshlrev_b64 v[2:3], 11, v[0:1]
	v_lshl_add_u64 v[2:3], v[114:115], 0, v[2:3]
	v_lshl_add_u64 v[0:1], v[0:1], 2, s[42:43]
	v_mov_b32_e32 v119, v193
	global_load_dwordx4 v[48:51], v[2:3], off
	global_load_dword v61, v[0:1], off
	v_lshl_add_u64 v[0:1], v[114:115], 0, v[118:119]
	v_add_u32_e32 v192, 17, v56
	global_load_dwordx4 v[52:55], v[0:1], off
	global_load_dwordx4 v[28:31], v145, s[42:43]
	global_load_dwordx4 v[32:35], v145, s[42:43] offset:16
	v_lshlrev_b64 v[0:1], 11, v[192:193]
	v_lshl_add_u64 v[0:1], v[114:115], 0, v[0:1]
	v_add_u32_e32 v192, 18, v56
	global_load_dwordx4 v[40:43], v[0:1], off
	v_lshlrev_b64 v[0:1], 11, v[192:193]
	v_lshl_add_u64 v[0:1], v[114:115], 0, v[0:1]
	v_add_u32_e32 v192, 19, v56
	global_load_dwordx4 v[36:39], v[0:1], off
	v_lshlrev_b64 v[0:1], 11, v[192:193]
	v_lshl_add_u64 v[0:1], v[114:115], 0, v[0:1]
	v_add_u32_e32 v192, 20, v56
	global_load_dwordx4 v[24:27], v[0:1], off
	v_lshlrev_b64 v[0:1], 11, v[192:193]
	v_lshl_add_u64 v[0:1], v[114:115], 0, v[0:1]
	v_add_u32_e32 v192, 21, v56
	global_load_dwordx4 v[20:23], v[0:1], off
	v_lshlrev_b64 v[0:1], 11, v[192:193]
	v_lshl_add_u64 v[0:1], v[114:115], 0, v[0:1]
	v_add_u32_e32 v192, 22, v56
	global_load_dwordx4 v[16:19], v[0:1], off
	v_lshlrev_b64 v[0:1], 11, v[192:193]
	v_add_u32_e32 v192, 23, v56
	v_add_u32_e32 v56, 14, v56
	v_lshl_add_u64 v[0:1], v[114:115], 0, v[0:1]
	global_load_dwordx4 v[12:15], v[0:1], off
	v_lshlrev_b64 v[0:1], 11, v[192:193]
	v_lshl_add_u64 v[0:1], v[114:115], 0, v[0:1]
	global_load_dwordx4 v[4:7], v[0:1], off
	s_nop 0
	global_load_dwordx4 v[0:3], v[120:121], off offset:16
	global_load_dwordx4 v[8:11], v[120:121], off
	v_mov_b64_e32 v[72:73], s[24:25]
	v_lshl_add_u64 v[74:75], v[116:117], 0, v[118:119]
	v_add_u32_e32 v192, 0x800, v143
	v_lshl_add_u64 v[70:71], v[116:117], 0, v[192:193]
	v_add_u32_e32 v192, 0x1000, v143
	v_lshl_add_u64 v[68:69], v[116:117], 0, v[192:193]
	v_add_u32_e32 v192, 0x1800, v143
	s_waitcnt vmcnt(15)
	v_and_b32_e32 v99, 0xffff0000, v45
	s_waitcnt vmcnt(14)
	v_fmamk_f32 v57, v57, 0x3a800000, v194
	v_cmp_gt_f32_e64 s[4:5], s2, v57
	v_lshlrev_b32_e32 v98, 16, v45
	v_rsq_f32_e32 v57, v57
	v_and_b32_e32 v93, 0xffff0000, v44
	v_lshlrev_b32_e32 v92, 16, v44
	v_and_b32_e32 v125, 0xffff0000, v47
	v_mov_b32_e32 v60, v57
	v_mov_b32_e32 v57, 0x400e
	v_cndmask_b32_e32 v56, v56, v57, vcc
	v_ashrrev_i32_e32 v57, 31, v56
	v_lshl_add_u64 v[58:59], v[56:57], 2, s[42:43]
	global_load_dword v62, v[58:59], off
	v_lshlrev_b64 v[56:57], 11, v[56:57]
	v_lshl_add_u64 v[56:57], v[114:115], 0, v[56:57]
	global_load_dwordx4 v[56:59], v[56:57], off
	s_waitcnt vmcnt(14)
	v_fmamk_f32 v61, v61, 0x3a800000, v194
	s_waitcnt vmcnt(11)
	v_mov_b32_e32 v76, v32
	v_mov_b32_e32 v77, v28
	v_pk_fma_f32 v[76:77], v[76:77], s[20:21], v[72:73] op_sel_hi:[1,0,0]
	s_waitcnt vmcnt(9)
	v_lshlrev_b32_e32 v67, 16, v39
	v_cmp_gt_f32_e64 s[4:5], s2, v77
	s_waitcnt vmcnt(8)
	v_lshlrev_b32_e32 v65, 16, v27
	v_and_b32_e32 v85, 0xffff0000, v48
	v_mov_b32_e32 v28, v77
	v_rsq_f32_e32 v77, v28
	v_lshlrev_b32_e32 v84, 16, v48
	v_and_b32_e32 v115, 0xffff0000, v46
	v_lshlrev_b32_e32 v114, 16, v46
	v_lshlrev_b32_e32 v80, 16, v55
	v_and_b32_e32 v81, 0xffff0000, v55
	v_lshlrev_b32_e32 v124, 16, v47
	s_waitcnt vmcnt(7)
	v_lshlrev_b32_e32 v122, 16, v23
	s_waitcnt vmcnt(1)
	v_fmamk_f32 v62, v62, 0x3a800000, v194
	v_cmp_gt_f32_e32 vcc, s2, v62
	s_waitcnt vmcnt(0)
	v_and_b32_e32 v101, 0xffff0000, v57
	v_rsq_f32_e32 v62, v62
	v_lshlrev_b32_e32 v100, 16, v57
	v_and_b32_e32 v97, 0xffff0000, v56
	v_lshlrev_b32_e32 v96, 16, v56
	v_mov_b32_e32 v66, v62
	v_cmp_gt_f32_e32 vcc, s2, v61
	v_and_b32_e32 v57, 0xffff0000, v49
	v_rsq_f32_e32 v61, v61
	v_lshlrev_b32_e32 v56, 16, v49
	v_and_b32_e32 v119, 0xffff0000, v58
	v_lshlrev_b32_e32 v118, 16, v58
	v_mov_b32_e32 v64, v61
	v_cmp_gt_f32_e32 vcc, s2, v76
	v_lshlrev_b32_e32 v61, 16, v43
	v_pk_fma_f32 v[44:45], v[60:61], v[98:99], 0 op_sel_hi:[0,1,0]
	v_mov_b32_e32 v28, v76
	v_rsq_f32_e32 v76, v28
	v_pk_fma_f32 v[82:83], v[60:61], v[92:93], 0 op_sel_hi:[0,1,0]
	v_pk_fma_f32 v[44:45], v[66:67], v[100:101], v[44:45] op_sel_hi:[0,1,1]
	v_pk_fma_f32 v[82:83], v[66:67], v[96:97], v[82:83] op_sel_hi:[0,1,1]
	v_pk_mul_f32 v[78:79], v[76:77], s[22:23] op_sel_hi:[1,0]
	v_pk_fma_f32 v[48:49], v[64:65], v[56:57], v[44:45] op_sel_hi:[0,1,1]
	v_cndmask_b32_e64 v77, v77, v79, s[4:5]
	v_mov_b32_e32 v32, v77
	v_and_b32_e32 v45, 0xffff0000, v53
	v_lshlrev_b32_e32 v44, 16, v53
	v_pk_fma_f32 v[86:87], v[64:65], v[84:85], v[82:83] op_sel_hi:[0,1,1]
	v_and_b32_e32 v83, 0xffff0000, v52
	v_lshlrev_b32_e32 v82, 16, v52
	v_pk_mul_f32 v[52:53], v[32:33], v[44:45] op_sel_hi:[0,1]
	v_pk_fma_f32 v[102:103], v[32:33], v[44:45], v[48:49] op_sel_hi:[0,1,1]
	v_pk_fma_f32 v[48:49], v[102:103], s[28:29], v[52:53] op_sel_hi:[1,0,1] neg_lo:[0,0,1] neg_hi:[0,0,1]
	v_pk_mul_f32 v[88:89], v[32:33], v[82:83] op_sel_hi:[0,1]
	v_pk_fma_f32 v[94:95], v[32:33], v[82:83], v[86:87] op_sel_hi:[0,1,1]
	v_pk_mul_f32 v[48:49], v[10:11], v[48:49]
	v_pk_fma_f32 v[86:87], v[94:95], s[28:29], v[88:89] op_sel_hi:[1,0,1] neg_lo:[0,0,1] neg_hi:[0,0,1]
	v_cvt_pk_bf16_f32 v89, v48, v49
	v_pk_fma_f32 v[48:49], v[60:61], v[114:115], 0 op_sel_hi:[0,1,0]
	v_pk_mul_f32 v[86:87], v[8:9], v[86:87]
	v_and_b32_e32 v53, 0xffff0000, v50
	v_lshlrev_b32_e32 v52, 16, v50
	v_pk_fma_f32 v[48:49], v[66:67], v[118:119], v[48:49] op_sel_hi:[0,1,1]
	v_mov_b32_e32 v28, v33
	v_cvt_pk_bf16_f32 v88, v86, v87
	v_pk_fma_f32 v[86:87], v[64:65], v[52:53], v[48:49] op_sel_hi:[0,1,1]
	v_and_b32_e32 v49, 0xffff0000, v54
	v_lshlrev_b32_e32 v48, 16, v54
	v_pk_fma_f32 v[28:29], v[28:29], s[20:21], v[72:73] op_sel_hi:[1,0,0]
	v_pk_mul_f32 v[54:55], v[32:33], v[48:49] op_sel_hi:[0,1]
	v_pk_fma_f32 v[120:121], v[32:33], v[48:49], v[86:87] op_sel_hi:[0,1,1]
	v_cmp_gt_f32_e64 s[4:5], s2, v29
	v_cndmask_b32_e32 v76, v76, v78, vcc
	v_cmp_gt_f32_e32 vcc, s2, v28
	v_mul_f32_e32 v33, 0x4b800000, v28
	v_mul_f32_e32 v78, v77, v80
	v_and_b32_e32 v80, 0xffff0000, v23
	v_and_b32_e32 v127, 0xffff0000, v59
	v_lshlrev_b32_e32 v126, 16, v59
	v_pk_fma_f32 v[46:47], v[60:61], v[124:125], 0 op_sel_hi:[0,1,0]
	v_pk_mul_f32 v[80:81], v[76:77], v[80:81]
	v_and_b32_e32 v87, 0xffff0000, v51
	v_lshlrev_b32_e32 v86, 16, v51
	v_pk_fma_f32 v[46:47], v[66:67], v[126:127], v[46:47] op_sel_hi:[0,1,1]
	v_rsq_f32_e32 v29, v29
	v_rsq_f32_e32 v28, v28
	v_pk_fma_f32 v[46:47], v[64:65], v[86:87], v[46:47] op_sel_hi:[0,1,1]
	v_mov_b32_e32 v79, v81
	v_pk_fma_f32 v[54:55], v[120:121], s[28:29], v[54:55] op_sel_hi:[1,0,1] neg_lo:[0,0,1] neg_hi:[0,0,1]
	v_pk_add_f32 v[128:129], v[78:79], v[46:47]
	v_pk_mul_f32 v[54:55], v[0:1], v[54:55]
	v_pk_fma_f32 v[46:47], v[128:129], s[28:29], v[78:79] op_sel_hi:[1,0,1] neg_lo:[0,0,1] neg_hi:[0,0,1]
	v_cvt_pk_bf16_f32 v90, v54, v55
	v_pk_mul_f32 v[46:47], v[2:3], v[46:47]
	v_pk_mul_f32 v[54:55], v[28:29], s[22:23] op_sel_hi:[1,0]
	v_cvt_pk_bf16_f32 v91, v46, v47
	v_cndmask_b32_e64 v29, v29, v55, s[4:5]
	global_store_dwordx4 v[74:75], v[88:91], off
	v_and_b32_e32 v75, 0xffff0000, v40
	v_lshlrev_b32_e32 v74, 16, v40
	v_pk_fma_f32 v[88:89], v[60:61], v[92:93], v[94:95] op_sel_hi:[0,1,1] neg_lo:[1,0,0] neg_hi:[1,0,0]
	v_mov_b32_e32 v40, v29
	v_pk_mul_f32 v[90:91], v[40:41], v[74:75] op_sel_hi:[0,1]
	v_pk_fma_f32 v[130:131], v[40:41], v[74:75], v[88:89] op_sel_hi:[0,1,1]
	v_pk_fma_f32 v[88:89], v[130:131], s[28:29], v[90:91] op_sel_hi:[1,0,1] neg_lo:[0,0,1] neg_hi:[0,0,1]
	v_pk_fma_f32 v[92:93], v[60:61], v[98:99], v[102:103] op_sel_hi:[0,1,1] neg_lo:[1,0,0] neg_hi:[1,0,0]
	v_pk_mul_f32 v[88:89], v[8:9], v[88:89]
	v_cndmask_b32_e32 v28, v28, v54, vcc
	v_cvt_pk_bf16_f32 v90, v88, v89
	v_and_b32_e32 v89, 0xffff0000, v41
	v_lshlrev_b32_e32 v88, 16, v41
	v_pk_mul_f32 v[94:95], v[40:41], v[88:89] op_sel_hi:[0,1]
	v_pk_fma_f32 v[98:99], v[40:41], v[88:89], v[92:93] op_sel_hi:[0,1,1]
	v_and_b32_e32 v59, 0xffff0000, v43
	v_and_b32_e32 v58, 0xffff0000, v19
	v_pk_fma_f32 v[92:93], v[98:99], s[28:29], v[94:95] op_sel_hi:[1,0,1] neg_lo:[0,0,1] neg_hi:[0,0,1]
	v_pk_mul_f32 v[58:59], v[28:29], v[58:59]
	v_pk_mul_f32 v[92:93], v[10:11], v[92:93]
	v_mul_f32_e32 v54, v29, v61
	v_cvt_pk_bf16_f32 v91, v92, v93
	v_and_b32_e32 v43, 0xffff0000, v42
	v_lshlrev_b32_e32 v42, 16, v42
	v_pk_fma_f32 v[92:93], v[60:61], v[114:115], v[120:121] op_sel_hi:[0,1,1] neg_lo:[1,0,0] neg_hi:[1,0,0]
	v_pk_fma_f32 v[60:61], v[60:61], v[124:125], v[128:129] op_sel_hi:[0,1,1] neg_lo:[1,0,0] neg_hi:[1,0,0]
	v_mov_b32_e32 v55, v59
	v_pk_mul_f32 v[94:95], v[40:41], v[42:43] op_sel_hi:[0,1]
	v_pk_fma_f32 v[102:103], v[40:41], v[42:43], v[92:93] op_sel_hi:[0,1,1]
	v_pk_add_f32 v[114:115], v[54:55], v[60:61]
	v_pk_fma_f32 v[92:93], v[102:103], s[28:29], v[94:95] op_sel_hi:[1,0,1] neg_lo:[0,0,1] neg_hi:[0,0,1]
	v_pk_fma_f32 v[60:61], v[114:115], s[28:29], v[54:55] op_sel_hi:[1,0,1] neg_lo:[0,0,1] neg_hi:[0,0,1]
	v_pk_mul_f32 v[92:93], v[0:1], v[92:93]
	v_pk_mul_f32 v[60:61], v[2:3], v[60:61]
	v_cvt_pk_bf16_f32 v92, v92, v93
	v_cvt_pk_bf16_f32 v93, v60, v61
	global_store_dwordx4 v[70:71], v[90:93], off
	v_lshlrev_b32_e32 v23, 16, v19
	v_mul_f32_e32 v70, v28, v23
	v_mov_b32_e32 v90, v34
	v_mov_b32_e32 v91, v30
	v_pk_fma_f32 v[90:91], v[90:91], s[20:21], v[72:73] op_sel_hi:[1,0,0]
	v_and_b32_e32 v121, 0xffff0000, v36
	v_cmp_gt_f32_e64 s[4:5], s2, v91
	v_cmp_gt_f32_e32 vcc, s2, v90
	v_lshlrev_b32_e32 v120, 16, v36
	v_mov_b32_e32 v23, v91
	v_rsq_f32_e32 v91, v23
	v_mov_b32_e32 v23, v90
	v_rsq_f32_e32 v90, v23
	v_pk_fma_f32 v[96:97], v[66:67], v[96:97], v[130:131] op_sel_hi:[0,1,1] neg_lo:[1,0,0] neg_hi:[1,0,0]
	v_mov_b32_e32 v30, v35
	v_pk_fma_f32 v[98:99], v[66:67], v[100:101], v[98:99] op_sel_hi:[0,1,1] neg_lo:[1,0,0] neg_hi:[1,0,0]
	v_pk_mul_f32 v[92:93], v[90:91], s[22:23] op_sel_hi:[1,0]
	v_pk_fma_f32 v[30:31], v[30:31], s[20:21], v[72:73] op_sel_hi:[1,0,0]
	v_cndmask_b32_e64 v91, v91, v93, s[4:5]
	v_mov_b32_e32 v34, v91
	v_pk_mul_f32 v[124:125], v[34:35], v[120:121] op_sel_hi:[0,1]
	v_pk_fma_f32 v[96:97], v[34:35], v[120:121], v[96:97] op_sel_hi:[0,1,1]
	v_pk_fma_f32 v[124:125], v[96:97], s[28:29], v[124:125] op_sel_hi:[1,0,1] neg_lo:[0,0,1] neg_hi:[0,0,1]
	v_lshlrev_b32_e32 v19, 16, v15
	v_pk_mul_f32 v[124:125], v[8:9], v[124:125]
	v_and_b32_e32 v94, 0xffff0000, v15
	v_cvt_pk_bf16_f32 v36, v124, v125
	v_and_b32_e32 v125, 0xffff0000, v37
	v_lshlrev_b32_e32 v124, 16, v37
	v_pk_mul_f32 v[100:101], v[34:35], v[124:125] op_sel_hi:[0,1]
	v_pk_fma_f32 v[98:99], v[34:35], v[124:125], v[98:99] op_sel_hi:[0,1,1]
	v_cmp_gt_f32_e64 s[4:5], s2, v31
	v_cndmask_b32_e32 v90, v90, v92, vcc
	v_and_b32_e32 v95, 0xffff0000, v39
	v_pk_fma_f32 v[100:101], v[98:99], s[28:29], v[100:101] op_sel_hi:[1,0,1] neg_lo:[0,0,1] neg_hi:[0,0,1]
	v_mov_b32_e32 v15, v31
	v_pk_mul_f32 v[94:95], v[90:91], v[94:95]
	v_pk_mul_f32 v[100:101], v[10:11], v[100:101]
	v_cmp_gt_f32_e32 vcc, s2, v30
	v_rsq_f32_e32 v31, v15
	v_mul_f32_e32 v92, v91, v67
	v_cvt_pk_bf16_f32 v37, v100, v101
	v_and_b32_e32 v101, 0xffff0000, v38
	v_lshlrev_b32_e32 v100, 16, v38
	v_pk_fma_f32 v[38:39], v[66:67], v[118:119], v[102:103] op_sel_hi:[0,1,1] neg_lo:[1,0,0] neg_hi:[1,0,0]
	v_pk_fma_f32 v[66:67], v[66:67], v[126:127], v[114:115] op_sel_hi:[0,1,1] neg_lo:[1,0,0] neg_hi:[1,0,0]
	v_mov_b32_e32 v93, v95
	v_mov_b32_e32 v15, v30
	v_pk_mul_f32 v[102:103], v[34:35], v[100:101] op_sel_hi:[0,1]
	v_pk_fma_f32 v[118:119], v[34:35], v[100:101], v[38:39] op_sel_hi:[0,1,1]
	v_pk_add_f32 v[66:67], v[92:93], v[66:67]
	v_rsq_f32_e32 v30, v15
	v_pk_fma_f32 v[38:39], v[118:119], s[28:29], v[102:103] op_sel_hi:[1,0,1] neg_lo:[0,0,1] neg_hi:[0,0,1]
	v_pk_fma_f32 v[102:103], v[66:67], s[28:29], v[92:93] op_sel_hi:[1,0,1] neg_lo:[0,0,1] neg_hi:[0,0,1]
	v_pk_mul_f32 v[38:39], v[0:1], v[38:39]
	v_pk_mul_f32 v[102:103], v[2:3], v[102:103]
	v_cvt_pk_bf16_f32 v38, v38, v39
	v_cvt_pk_bf16_f32 v39, v102, v103
	global_store_dwordx4 v[68:69], v[36:39], off
	v_pk_mul_f32 v[68:69], v[30:31], s[22:23] op_sel_hi:[1,0]
	v_and_b32_e32 v103, 0xffff0000, v24
	v_cndmask_b32_e64 v31, v31, v69, s[4:5]
	v_lshlrev_b32_e32 v102, 16, v24
	v_pk_fma_f32 v[84:85], v[64:65], v[84:85], v[96:97] op_sel_hi:[0,1,1] neg_lo:[1,0,0] neg_hi:[1,0,0]
	v_mov_b32_e32 v96, v31
	v_pk_mul_f32 v[114:115], v[96:97], v[102:103] op_sel_hi:[0,1]
	v_pk_fma_f32 v[84:85], v[96:97], v[102:103], v[84:85] op_sel_hi:[0,1,1]
	v_pk_fma_f32 v[114:115], v[84:85], s[28:29], v[114:115] op_sel_hi:[1,0,1] neg_lo:[0,0,1] neg_hi:[0,0,1]
	v_pk_fma_f32 v[56:57], v[64:65], v[56:57], v[98:99] op_sel_hi:[0,1,1] neg_lo:[1,0,0] neg_hi:[1,0,0]
	v_pk_mul_f32 v[114:115], v[8:9], v[114:115]
	v_lshl_add_u64 v[62:63], v[116:117], 0, v[192:193]
	v_cvt_pk_bf16_f32 v24, v114, v115
	v_and_b32_e32 v115, 0xffff0000, v25
	v_lshlrev_b32_e32 v114, 16, v25
	v_pk_mul_f32 v[98:99], v[96:97], v[114:115] op_sel_hi:[0,1]
	v_pk_fma_f32 v[56:57], v[96:97], v[114:115], v[56:57] op_sel_hi:[0,1,1]
	v_add_u32_e32 v192, 0x2000, v143
	v_pk_fma_f32 v[98:99], v[56:57], s[28:29], v[98:99] op_sel_hi:[1,0,1] neg_lo:[0,0,1] neg_hi:[0,0,1]
	v_lshl_add_u64 v[46:47], v[116:117], 0, v[192:193]
	v_add_u32_e32 v192, 0x2800, v143
	v_pk_mul_f32 v[98:99], v[10:11], v[98:99]
	v_lshl_add_u64 v[60:61], v[116:117], 0, v[192:193]
	v_add_u32_e32 v192, 0x3000, v143
	v_cndmask_b32_e32 v30, v30, v68, vcc
	v_and_b32_e32 v73, 0xffff0000, v27
	v_and_b32_e32 v72, 0xffff0000, v7
	v_cvt_pk_bf16_f32 v25, v98, v99
	v_and_b32_e32 v99, 0xffff0000, v26
	v_lshlrev_b32_e32 v98, 16, v26
	v_pk_fma_f32 v[26:27], v[64:65], v[52:53], v[118:119] op_sel_hi:[0,1,1] neg_lo:[1,0,0] neg_hi:[1,0,0]
	v_lshl_add_u64 v[38:39], v[116:117], 0, v[192:193]
	v_pk_mul_f32 v[72:73], v[30:31], v[72:73]
	v_pk_mul_f32 v[52:53], v[96:97], v[98:99] op_sel_hi:[0,1]
	v_pk_fma_f32 v[116:117], v[96:97], v[98:99], v[26:27] op_sel_hi:[0,1,1]
	v_mul_f32_e32 v68, v31, v65
	v_pk_fma_f32 v[26:27], v[116:117], s[28:29], v[52:53] op_sel_hi:[1,0,1] neg_lo:[0,0,1] neg_hi:[0,0,1]
	v_pk_fma_f32 v[52:53], v[64:65], v[86:87], v[66:67] op_sel_hi:[0,1,1] neg_lo:[1,0,0] neg_hi:[1,0,0]
	v_mov_b32_e32 v69, v73
	v_pk_add_f32 v[52:53], v[68:69], v[52:53]
	v_pk_mul_f32 v[26:27], v[0:1], v[26:27]
	v_pk_fma_f32 v[64:65], v[52:53], s[28:29], v[68:69] op_sel_hi:[1,0,1] neg_lo:[0,0,1] neg_hi:[0,0,1]
	v_cvt_pk_bf16_f32 v26, v26, v27
	v_pk_mul_f32 v[64:65], v[2:3], v[64:65]
	v_pk_fma_f32 v[44:45], v[32:33], v[44:45], v[56:57] op_sel_hi:[0,1,1] neg_lo:[1,0,0] neg_hi:[1,0,0]
	v_cvt_pk_bf16_f32 v27, v64, v65
	global_store_dwordx4 v[62:63], v[24:27], off
	v_pk_fma_f32 v[62:63], v[32:33], v[82:83], v[84:85] op_sel_hi:[0,1,1] neg_lo:[1,0,0] neg_hi:[1,0,0]
	v_and_b32_e32 v23, 0xffff0000, v22
	v_and_b32_e32 v25, 0xffff0000, v20
	v_lshlrev_b32_e32 v24, 16, v20
	v_pk_mul_f32 v[26:27], v[76:77], v[24:25] op_sel_hi:[0,1]
	v_pk_fma_f32 v[24:25], v[76:77], v[24:25], v[62:63] op_sel_hi:[0,1,1]
	v_pk_fma_f32 v[26:27], v[24:25], s[28:29], v[26:27] op_sel_hi:[1,0,1] neg_lo:[0,0,1] neg_hi:[0,0,1]
	v_lshlrev_b32_e32 v22, 16, v22
	v_pk_mul_f32 v[26:27], v[8:9], v[26:27]
	v_pk_fma_f32 v[32:33], v[32:33], v[48:49], v[116:117] op_sel_hi:[0,1,1] neg_lo:[1,0,0] neg_hi:[1,0,0]
	v_cvt_pk_bf16_f32 v20, v26, v27
	v_and_b32_e32 v27, 0xffff0000, v21
	v_lshlrev_b32_e32 v26, 16, v21
	v_pk_mul_f32 v[62:63], v[76:77], v[26:27] op_sel_hi:[0,1]
	v_pk_fma_f32 v[26:27], v[76:77], v[26:27], v[44:45] op_sel_hi:[0,1,1]
	v_pk_fma_f32 v[44:45], v[26:27], s[28:29], v[62:63] op_sel_hi:[1,0,1] neg_lo:[0,0,1] neg_hi:[0,0,1]
	v_pk_fma_f32 v[32:33], v[76:77], v[22:23], v[32:33] op_sel_hi:[0,1,1]
	v_pk_mul_f32 v[44:45], v[10:11], v[44:45]
	v_mul_f32_e32 v50, v76, v122
	v_cvt_pk_bf16_f32 v21, v44, v45
	v_pk_mul_f32 v[44:45], v[76:77], v[22:23] op_sel_hi:[0,1]
	v_pk_fma_f32 v[22:23], v[32:33], s[28:29], v[44:45] op_sel_hi:[1,0,1] neg_lo:[0,0,1] neg_hi:[0,0,1]
	v_pk_add_f32 v[44:45], v[52:53], v[78:79] neg_lo:[0,1] neg_hi:[0,1]
	v_mov_b32_e32 v51, v80
	v_pk_add_f32 v[44:45], v[50:51], v[44:45]
	v_pk_mul_f32 v[22:23], v[0:1], v[22:23]
	v_pk_fma_f32 v[48:49], v[44:45], s[28:29], v[50:51] op_sel_hi:[1,0,1] neg_lo:[0,0,1] neg_hi:[0,0,1]
	v_lshlrev_b32_e32 v41, 16, v7
	v_pk_mul_f32 v[48:49], v[2:3], v[48:49]
	v_cvt_pk_bf16_f32 v22, v22, v23
	v_cvt_pk_bf16_f32 v23, v48, v49
	global_store_dwordx4 v[46:47], v[20:23], off
	v_pk_fma_f32 v[24:25], v[40:41], v[74:75], v[24:25] op_sel_hi:[0,1,1] neg_lo:[1,0,0] neg_hi:[1,0,0]
	v_pk_fma_f32 v[26:27], v[40:41], v[88:89], v[26:27] op_sel_hi:[0,1,1] neg_lo:[1,0,0] neg_hi:[1,0,0]
	v_and_b32_e32 v21, 0xffff0000, v16
	v_lshlrev_b32_e32 v20, 16, v16
	v_pk_mul_f32 v[22:23], v[28:29], v[20:21] op_sel_hi:[0,1]
	v_pk_fma_f32 v[20:21], v[28:29], v[20:21], v[24:25] op_sel_hi:[0,1,1]
	v_pk_fma_f32 v[22:23], v[20:21], s[28:29], v[22:23] op_sel_hi:[1,0,1] neg_lo:[0,0,1] neg_hi:[0,0,1]
	v_mul_f32_e32 v36, v90, v19
	v_pk_mul_f32 v[22:23], v[8:9], v[22:23]
	v_and_b32_e32 v19, 0xffff0000, v18
	v_cvt_pk_bf16_f32 v16, v22, v23
	v_and_b32_e32 v23, 0xffff0000, v17
	v_lshlrev_b32_e32 v22, 16, v17
	v_pk_mul_f32 v[24:25], v[28:29], v[22:23] op_sel_hi:[0,1]
	v_pk_fma_f32 v[22:23], v[28:29], v[22:23], v[26:27] op_sel_hi:[0,1,1]
	v_pk_fma_f32 v[24:25], v[22:23], s[28:29], v[24:25] op_sel_hi:[1,0,1] neg_lo:[0,0,1] neg_hi:[0,0,1]
	v_lshlrev_b32_e32 v18, 16, v18
	v_pk_mul_f32 v[24:25], v[10:11], v[24:25]
	v_pk_fma_f32 v[26:27], v[40:41], v[42:43], v[32:33] op_sel_hi:[0,1,1] neg_lo:[1,0,0] neg_hi:[1,0,0]
	v_cvt_pk_bf16_f32 v17, v24, v25
	v_pk_mul_f32 v[24:25], v[28:29], v[18:19] op_sel_hi:[0,1]
	v_pk_fma_f32 v[26:27], v[28:29], v[18:19], v[26:27] op_sel_hi:[0,1,1]
	v_pk_fma_f32 v[18:19], v[26:27], s[28:29], v[24:25] op_sel_hi:[1,0,1] neg_lo:[0,0,1] neg_hi:[0,0,1]
	v_pk_add_f32 v[24:25], v[44:45], v[54:55] neg_lo:[0,1] neg_hi:[0,1]
	v_mov_b32_e32 v71, v58
	v_pk_add_f32 v[24:25], v[70:71], v[24:25]
	v_pk_mul_f32 v[18:19], v[0:1], v[18:19]
	v_pk_fma_f32 v[28:29], v[24:25], s[28:29], v[70:71] op_sel_hi:[1,0,1] neg_lo:[0,0,1] neg_hi:[0,0,1]
	v_cvt_pk_bf16_f32 v18, v18, v19
	v_pk_mul_f32 v[28:29], v[2:3], v[28:29]
	v_pk_fma_f32 v[20:21], v[34:35], v[120:121], v[20:21] op_sel_hi:[0,1,1] neg_lo:[1,0,0] neg_hi:[1,0,0]
	v_cvt_pk_bf16_f32 v19, v28, v29
	global_store_dwordx4 v[60:61], v[16:19], off
	v_pk_fma_f32 v[22:23], v[34:35], v[124:125], v[22:23] op_sel_hi:[0,1,1] neg_lo:[1,0,0] neg_hi:[1,0,0]
	v_and_b32_e32 v15, 0xffff0000, v14
	v_and_b32_e32 v17, 0xffff0000, v12
	v_lshlrev_b32_e32 v16, 16, v12
	v_pk_mul_f32 v[18:19], v[90:91], v[16:17] op_sel_hi:[0,1]
	v_pk_fma_f32 v[16:17], v[90:91], v[16:17], v[20:21] op_sel_hi:[0,1,1]
	v_pk_fma_f32 v[18:19], v[16:17], s[28:29], v[18:19] op_sel_hi:[1,0,1] neg_lo:[0,0,1] neg_hi:[0,0,1]
	v_lshlrev_b32_e32 v14, 16, v14
	v_pk_mul_f32 v[18:19], v[8:9], v[18:19]
	v_mov_b32_e32 v37, v94
	v_cvt_pk_bf16_f32 v12, v18, v19
	v_and_b32_e32 v19, 0xffff0000, v13
	v_lshlrev_b32_e32 v18, 16, v13
	v_pk_mul_f32 v[20:21], v[90:91], v[18:19] op_sel_hi:[0,1]
	v_pk_fma_f32 v[18:19], v[90:91], v[18:19], v[22:23] op_sel_hi:[0,1,1]
	v_pk_fma_f32 v[20:21], v[18:19], s[28:29], v[20:21] op_sel_hi:[1,0,1] neg_lo:[0,0,1] neg_hi:[0,0,1]
	v_pk_fma_f32 v[22:23], v[34:35], v[100:101], v[26:27] op_sel_hi:[0,1,1] neg_lo:[1,0,0] neg_hi:[1,0,0]
	v_pk_mul_f32 v[20:21], v[10:11], v[20:21]
	v_pk_fma_f32 v[22:23], v[90:91], v[14:15], v[22:23] op_sel_hi:[0,1,1]
	v_cvt_pk_bf16_f32 v13, v20, v21
	v_pk_mul_f32 v[20:21], v[90:91], v[14:15] op_sel_hi:[0,1]
	v_pk_fma_f32 v[14:15], v[22:23], s[28:29], v[20:21] op_sel_hi:[1,0,1] neg_lo:[0,0,1] neg_hi:[0,0,1]
	v_pk_add_f32 v[20:21], v[24:25], v[92:93] neg_lo:[0,1] neg_hi:[0,1]
	v_pk_mul_f32 v[14:15], v[0:1], v[14:15]
	v_pk_add_f32 v[20:21], v[36:37], v[20:21]
	v_cvt_pk_bf16_f32 v14, v14, v15
	v_pk_fma_f32 v[24:25], v[20:21], s[28:29], v[36:37] op_sel_hi:[1,0,1] neg_lo:[0,0,1] neg_hi:[0,0,1]
	v_and_b32_e32 v7, 0xffff0000, v6
	v_pk_mul_f32 v[24:25], v[2:3], v[24:25]
	v_lshlrev_b32_e32 v6, 16, v6
	v_cvt_pk_bf16_f32 v15, v24, v25
	global_store_dwordx4 v[38:39], v[12:15], off
	v_add_u32_e32 v192, 7, v123
	s_nop 0
	v_pk_fma_f32 v[14:15], v[96:97], v[102:103], v[16:17] op_sel_hi:[0,1,1] neg_lo:[1,0,0] neg_hi:[1,0,0]
	v_and_b32_e32 v17, 0xffff0000, v4
	v_lshlrev_b32_e32 v16, 16, v4
	v_pk_mul_f32 v[24:25], v[30:31], v[16:17] op_sel_hi:[0,1]
	v_pk_fma_f32 v[14:15], v[30:31], v[16:17], v[14:15] op_sel_hi:[0,1,1]
	v_pk_fma_f32 v[14:15], v[14:15], s[28:29], v[24:25] op_sel_hi:[1,0,1] neg_lo:[0,0,1] neg_hi:[0,0,1]
	v_mul_f32_e32 v12, v30, v41
	v_pk_mul_f32 v[8:9], v[8:9], v[14:15]
	v_pk_fma_f32 v[14:15], v[96:97], v[114:115], v[18:19] op_sel_hi:[0,1,1] neg_lo:[1,0,0] neg_hi:[1,0,0]
	v_cvt_pk_bf16_f32 v4, v8, v9
	v_and_b32_e32 v9, 0xffff0000, v5
	v_lshlrev_b32_e32 v8, 16, v5
	v_pk_mul_f32 v[16:17], v[30:31], v[8:9] op_sel_hi:[0,1]
	v_pk_fma_f32 v[8:9], v[30:31], v[8:9], v[14:15] op_sel_hi:[0,1,1]
	v_pk_fma_f32 v[8:9], v[8:9], s[28:29], v[16:17] op_sel_hi:[1,0,1] neg_lo:[0,0,1] neg_hi:[0,0,1]
	v_mov_b32_e32 v13, v72
	v_pk_mul_f32 v[8:9], v[10:11], v[8:9]
	v_pk_mul_f32 v[10:11], v[30:31], v[6:7] op_sel_hi:[0,1]
	v_cvt_pk_bf16_f32 v5, v8, v9
	v_pk_fma_f32 v[8:9], v[96:97], v[98:99], v[22:23] op_sel_hi:[0,1,1] neg_lo:[1,0,0] neg_hi:[1,0,0]
	v_pk_fma_f32 v[6:7], v[30:31], v[6:7], v[8:9] op_sel_hi:[0,1,1]
	v_pk_fma_f32 v[6:7], v[6:7], s[28:29], v[10:11] op_sel_hi:[1,0,1] neg_lo:[0,0,1] neg_hi:[0,0,1]
	s_nop 0
	v_pk_mul_f32 v[0:1], v[0:1], v[6:7]
	s_nop 0
	v_cvt_pk_bf16_f32 v6, v0, v1
	v_pk_add_f32 v[0:1], v[20:21], v[68:69] neg_lo:[0,1] neg_hi:[0,1]
	s_nop 0
	v_pk_add_f32 v[0:1], v[12:13], v[0:1]
	s_nop 0
	v_pk_fma_f32 v[0:1], v[0:1], s[28:29], v[12:13] op_sel_hi:[1,0,1] neg_lo:[0,0,1] neg_hi:[0,0,1]
	s_nop 0
	v_pk_mul_f32 v[0:1], v[2:3], v[0:1]
	s_nop 0
	v_cvt_pk_bf16_f32 v7, v0, v1

.LBB0_2599:
	s_andn2_saveexec_b64 s[12:13], s[12:13]
	s_cbranch_execz .LBB0_2586
	v_lshlrev_b32_e32 v48, 13, v0
	s_waitcnt vmcnt(1)
	v_or_b32_e32 v66, v48, v151
	v_subrev_co_u32_e32 v49, vcc, 1, v151
	v_add_u32_e32 v0, -1, v66
	v_mov_b32_e32 v1, 0x400f
	v_cndmask_b32_e32 v0, v0, v1, vcc
	v_ashrrev_i32_e32 v1, 31, v0
	v_lshlrev_b64 v[2:3], 11, v[0:1]
	v_lshl_add_u64 v[2:3], v[106:107], 0, v[2:3]
	v_lshl_add_u64 v[0:1], v[0:1], 2, s[42:43]
	global_load_dwordx4 v[44:47], v[2:3], off
	global_load_dword v50, v[0:1], off
	v_add_u32_e32 v192, 1, v66
	v_lshlrev_b64 v[0:1], 11, v[192:193]
	v_lshl_add_u64 v[0:1], v[106:107], 0, v[0:1]
	v_add_u32_e32 v192, 2, v66
	global_load_dwordx4 v[36:39], v[0:1], off
	v_lshlrev_b64 v[0:1], 11, v[192:193]
	v_lshl_add_u64 v[0:1], v[106:107], 0, v[0:1]
	v_add_u32_e32 v192, 3, v66
	global_load_dwordx4 v[32:35], v[0:1], off
	v_lshlrev_b64 v[0:1], 11, v[192:193]
	v_lshl_add_u64 v[0:1], v[106:107], 0, v[0:1]
	v_add_u32_e32 v192, 4, v66
	v_add_u32_e32 v49, v49, v48
	global_load_dwordx4 v[28:31], v[0:1], off
	v_lshlrev_b64 v[0:1], 11, v[192:193]
	v_lshl_add_u64 v[0:1], v[106:107], 0, v[0:1]
	global_load_dwordx4 v[16:19], v[0:1], off
	v_lshlrev_b32_e32 v0, 2, v66
	v_add_u32_e32 v192, 5, v66
	global_load_dwordx4 v[24:27], v0, s[42:43] offset:16
	global_load_dwordx4 v[40:43], v0, s[42:43]
	v_lshlrev_b64 v[0:1], 11, v[192:193]
	v_lshl_add_u64 v[0:1], v[106:107], 0, v[0:1]
	v_add_u32_e32 v192, 6, v66
	global_load_dwordx4 v[20:23], v[0:1], off
	v_lshlrev_b64 v[0:1], 11, v[192:193]
	v_mov_b32_e32 v67, v193
	v_lshl_add_u64 v[0:1], v[106:107], 0, v[0:1]
	v_add_u32_e32 v192, 7, v66
	global_load_dwordx4 v[12:15], v[0:1], off
	v_lshlrev_b64 v[0:1], 11, v[192:193]
	v_lshl_add_u64 v[0:1], v[106:107], 0, v[0:1]
	global_load_dwordx4 v[4:7], v[0:1], off
	s_nop 0
	global_load_dwordx4 v[0:3], v[108:109], off offset:16
	global_load_dwordx4 v[8:11], v[108:109], off
	v_lshlrev_b32_e32 v192, 11, v66
	v_mov_b64_e32 v[112:113], v[104:105]
	s_waitcnt vmcnt(12)
	v_and_b32_e32 v63, 0xffff0000, v44
	s_waitcnt vmcnt(11)
	v_fmamk_f32 v48, v50, 0x3a800000, v194
	v_cmp_gt_f32_e32 vcc, s2, v48
	v_lshlrev_b32_e32 v62, 16, v44
	v_rsq_f32_e32 v48, v48
	v_and_b32_e32 v61, 0xffff0000, v45
	v_lshlrev_b32_e32 v60, 16, v45
	v_mov_b64_e32 v[44:45], s[24:25]
	v_lshlrev_b64 v[50:51], 11, v[66:67]
	v_lshl_add_u64 v[50:51], v[106:107], 0, v[50:51]
	global_load_dwordx4 v[74:77], v[50:51], off
	v_pk_fma_f32 v[72:73], v[48:49], v[62:63], 0 op_sel_hi:[0,1,0]
	v_pk_fma_f32 v[70:71], v[48:49], v[60:61], 0 op_sel_hi:[0,1,0]
	v_and_b32_e32 v59, 0xffff0000, v46
	v_lshlrev_b32_e32 v58, 16, v46
	v_and_b32_e32 v57, 0xffff0000, v47
	v_lshlrev_b32_e32 v56, 16, v47
	s_waitcnt vmcnt(6)
	v_pk_fma_f32 v[40:41], v[40:41], s[20:21], v[44:45] op_sel_hi:[1,0,0]
	v_pk_fma_f32 v[68:69], v[48:49], v[58:59], 0 op_sel_hi:[0,1,0]
	v_cmp_gt_f32_e64 s[4:5], s2, v40
	v_pk_fma_f32 v[64:65], v[48:49], v[56:57], 0 op_sel_hi:[0,1,0]
	v_lshl_add_u64 v[66:67], v[110:111], 0, v[192:193]
	v_cmp_gt_f32_e32 vcc, s2, v41
	v_add_u32_e32 v192, 2, v49
	v_pk_fma_f32 v[42:43], v[42:43], s[20:21], v[44:45] op_sel_hi:[1,0,0]
	s_waitcnt vmcnt(0)
	v_and_b32_e32 v55, 0xffff0000, v74
	v_lshlrev_b32_e32 v54, 16, v74
	v_rsq_f32_e32 v40, v40
	v_and_b32_e32 v53, 0xffff0000, v75
	v_lshlrev_b32_e32 v52, 16, v75
	v_and_b32_e32 v51, 0xffff0000, v76
	v_lshlrev_b32_e32 v50, 16, v76
	v_and_b32_e32 v47, 0xffff0000, v77
	v_lshlrev_b32_e32 v46, 16, v77
	v_pk_mul_f32 v[74:75], v[40:41], v[54:55] op_sel_hi:[0,1]
	v_pk_fma_f32 v[76:77], v[40:41], v[54:55], v[72:73] op_sel_hi:[0,1,1]
	v_pk_fma_f32 v[72:73], v[76:77], 0.5, v[74:75] op_sel_hi:[1,0,1] neg_lo:[0,0,1] neg_hi:[0,0,1]
	v_pk_mul_f32 v[74:75], v[40:41], v[52:53] op_sel_hi:[0,1]
	v_pk_fma_f32 v[70:71], v[40:41], v[52:53], v[70:71] op_sel_hi:[0,1,1]
	v_pk_fma_f32 v[74:75], v[70:71], 0.5, v[74:75] op_sel_hi:[1,0,1] neg_lo:[0,0,1] neg_hi:[0,0,1]
	v_pk_mul_f32 v[72:73], v[8:9], v[72:73]
	v_pk_mul_f32 v[74:75], v[10:11], v[74:75]
	v_cvt_pk_bf16_f32 v72, v72, v73
	v_cvt_pk_bf16_f32 v73, v74, v75
	v_pk_mul_f32 v[74:75], v[40:41], v[50:51] op_sel_hi:[0,1]
	v_pk_fma_f32 v[68:69], v[40:41], v[50:51], v[68:69] op_sel_hi:[0,1,1]
	v_pk_mul_f32 v[78:79], v[40:41], v[46:47] op_sel_hi:[0,1]
	v_pk_fma_f32 v[64:65], v[40:41], v[46:47], v[64:65] op_sel_hi:[0,1,1]
	v_pk_fma_f32 v[74:75], v[68:69], 0.5, v[74:75] op_sel_hi:[1,0,1] neg_lo:[0,0,1] neg_hi:[0,0,1]
	v_pk_fma_f32 v[78:79], v[64:65], 0.5, v[78:79] op_sel_hi:[1,0,1] neg_lo:[0,0,1] neg_hi:[0,0,1]
	v_pk_mul_f32 v[74:75], v[0:1], v[74:75]
	v_pk_mul_f32 v[78:79], v[2:3], v[78:79]
	v_cvt_pk_bf16_f32 v74, v74, v75
	v_cvt_pk_bf16_f32 v75, v78, v79
	global_store_dwordx4 v[66:67], v[72:75], off
	v_rsq_f32_e32 v41, v41
	v_pk_fma_f32 v[62:63], v[48:49], v[62:63], v[76:77] op_sel_hi:[0,1,1] neg_lo:[1,0,0] neg_hi:[1,0,0]
	v_and_b32_e32 v73, 0xffff0000, v36
	v_lshlrev_b32_e32 v72, 16, v36
	v_mov_b32_e32 v66, v41
	v_pk_mul_f32 v[74:75], v[66:67], v[72:73] op_sel_hi:[0,1]
	v_pk_fma_f32 v[62:63], v[66:67], v[72:73], v[62:63] op_sel_hi:[0,1,1]
	v_pk_fma_f32 v[74:75], v[62:63], 0.5, v[74:75] op_sel_hi:[1,0,1] neg_lo:[0,0,1] neg_hi:[0,0,1]
	v_pk_fma_f32 v[60:61], v[48:49], v[60:61], v[70:71] op_sel_hi:[0,1,1] neg_lo:[1,0,0] neg_hi:[1,0,0]
	v_pk_mul_f32 v[74:75], v[8:9], v[74:75]
	v_and_b32_e32 v71, 0xffff0000, v37
	v_lshlrev_b32_e32 v70, 16, v37
	v_cvt_pk_bf16_f32 v36, v74, v75
	v_pk_mul_f32 v[74:75], v[66:67], v[70:71] op_sel_hi:[0,1]
	v_pk_fma_f32 v[60:61], v[66:67], v[70:71], v[60:61] op_sel_hi:[0,1,1]
	v_pk_fma_f32 v[74:75], v[60:61], 0.5, v[74:75] op_sel_hi:[1,0,1] neg_lo:[0,0,1] neg_hi:[0,0,1]
	v_pk_fma_f32 v[58:59], v[48:49], v[58:59], v[68:69] op_sel_hi:[0,1,1] neg_lo:[1,0,0] neg_hi:[1,0,0]
	v_pk_mul_f32 v[74:75], v[10:11], v[74:75]
	v_and_b32_e32 v69, 0xffff0000, v38
	v_lshlrev_b32_e32 v68, 16, v38
	v_cvt_pk_bf16_f32 v37, v74, v75
	v_pk_mul_f32 v[74:75], v[66:67], v[68:69] op_sel_hi:[0,1]
	v_pk_fma_f32 v[58:59], v[66:67], v[68:69], v[58:59] op_sel_hi:[0,1,1]
	v_pk_fma_f32 v[74:75], v[58:59], 0.5, v[74:75] op_sel_hi:[1,0,1] neg_lo:[0,0,1] neg_hi:[0,0,1]
	v_pk_fma_f32 v[56:57], v[48:49], v[56:57], v[64:65] op_sel_hi:[0,1,1] neg_lo:[1,0,0] neg_hi:[1,0,0]
	v_pk_mul_f32 v[74:75], v[0:1], v[74:75]
	v_and_b32_e32 v65, 0xffff0000, v39
	v_lshlrev_b32_e32 v64, 16, v39
	v_cvt_pk_bf16_f32 v38, v74, v75
	v_pk_mul_f32 v[74:75], v[66:67], v[64:65] op_sel_hi:[0,1]
	v_pk_fma_f32 v[56:57], v[66:67], v[64:65], v[56:57] op_sel_hi:[0,1,1]
	v_pk_fma_f32 v[74:75], v[56:57], 0.5, v[74:75] op_sel_hi:[1,0,1] neg_lo:[0,0,1] neg_hi:[0,0,1]
	v_pk_fma_f32 v[52:53], v[40:41], v[52:53], v[60:61] op_sel_hi:[0,1,1] neg_lo:[1,0,0] neg_hi:[1,0,0]
	v_pk_mul_f32 v[74:75], v[2:3], v[74:75]
	v_pk_fma_f32 v[50:51], v[40:41], v[50:51], v[58:59] op_sel_hi:[0,1,1] neg_lo:[1,0,0] neg_hi:[1,0,0]
	v_cvt_pk_bf16_f32 v39, v74, v75
	v_lshlrev_b64 v[74:75], 11, v[192:193]
	v_lshl_add_u64 v[74:75], v[110:111], 0, v[74:75]
	v_add_u32_e32 v192, 3, v49
	global_store_dwordx4 v[74:75], v[36:39], off
	v_cmp_gt_f32_e64 s[4:5], s2, v42
	v_and_b32_e32 v59, 0xffff0000, v34
	v_pk_fma_f32 v[36:37], v[40:41], v[54:55], v[62:63] op_sel_hi:[0,1,1] neg_lo:[1,0,0] neg_hi:[1,0,0]
	v_and_b32_e32 v39, 0xffff0000, v32
	v_lshlrev_b32_e32 v38, 16, v32
	v_and_b32_e32 v55, 0xffff0000, v33
	v_lshlrev_b32_e32 v54, 16, v33
	v_lshlrev_b64 v[32:33], 11, v[192:193]
	v_pk_fma_f32 v[40:41], v[40:41], v[46:47], v[56:57] op_sel_hi:[0,1,1] neg_lo:[1,0,0] neg_hi:[1,0,0]
	v_lshl_add_u64 v[56:57], v[110:111], 0, v[32:33]
	v_mov_b32_e32 v32, v42
	v_rsq_f32_e32 v32, v32
	v_lshlrev_b32_e32 v58, 16, v34
	v_and_b32_e32 v47, 0xffff0000, v35
	v_lshlrev_b32_e32 v46, 16, v35
	v_mov_b32_e32 v42, v32
	v_pk_mul_f32 v[32:33], v[42:43], v[38:39] op_sel_hi:[0,1]
	v_pk_fma_f32 v[36:37], v[42:43], v[38:39], v[36:37] op_sel_hi:[0,1,1]
	v_pk_mul_f32 v[34:35], v[42:43], v[54:55] op_sel_hi:[0,1]
	v_pk_fma_f32 v[52:53], v[42:43], v[54:55], v[52:53] op_sel_hi:[0,1,1]
	v_pk_fma_f32 v[32:33], v[36:37], 0.5, v[32:33] op_sel_hi:[1,0,1] neg_lo:[0,0,1] neg_hi:[0,0,1]
	v_pk_fma_f32 v[34:35], v[52:53], 0.5, v[34:35] op_sel_hi:[1,0,1] neg_lo:[0,0,1] neg_hi:[0,0,1]
	v_pk_mul_f32 v[32:33], v[8:9], v[32:33]
	v_pk_mul_f32 v[34:35], v[10:11], v[34:35]
	v_cvt_pk_bf16_f32 v32, v32, v33
	v_cvt_pk_bf16_f32 v33, v34, v35
	v_pk_mul_f32 v[34:35], v[42:43], v[58:59] op_sel_hi:[0,1]
	v_pk_fma_f32 v[50:51], v[42:43], v[58:59], v[50:51] op_sel_hi:[0,1,1]
	v_pk_mul_f32 v[60:61], v[42:43], v[46:47] op_sel_hi:[0,1]
	v_pk_fma_f32 v[40:41], v[42:43], v[46:47], v[40:41] op_sel_hi:[0,1,1]
	v_pk_fma_f32 v[34:35], v[50:51], 0.5, v[34:35] op_sel_hi:[1,0,1] neg_lo:[0,0,1] neg_hi:[0,0,1]
	v_pk_fma_f32 v[60:61], v[40:41], 0.5, v[60:61] op_sel_hi:[1,0,1] neg_lo:[0,0,1] neg_hi:[0,0,1]
	v_pk_mul_f32 v[34:35], v[0:1], v[34:35]
	v_pk_mul_f32 v[60:61], v[2:3], v[60:61]
	v_cvt_pk_bf16_f32 v34, v34, v35
	v_cvt_pk_bf16_f32 v35, v60, v61
	v_cmp_gt_f32_e32 vcc, s2, v43
	global_store_dwordx4 v[56:57], v[32:35], off
	v_pk_fma_f32 v[52:53], v[66:67], v[70:71], v[52:53] op_sel_hi:[0,1,1] neg_lo:[1,0,0] neg_hi:[1,0,0]
	v_pk_fma_f32 v[50:51], v[66:67], v[68:69], v[50:51] op_sel_hi:[0,1,1] neg_lo:[1,0,0] neg_hi:[1,0,0]
	v_mov_b32_e32 v32, v43
	v_rsq_f32_e32 v32, v32
	v_pk_fma_f32 v[34:35], v[66:67], v[72:73], v[36:37] op_sel_hi:[0,1,1] neg_lo:[1,0,0] neg_hi:[1,0,0]
	v_and_b32_e32 v37, 0xffff0000, v28
	v_lshlrev_b32_e32 v36, 16, v28
	v_mul_f32_e32 v33, 0x45800000, v32
	v_pk_mul_f32 v[56:57], v[32:33], v[36:37] op_sel_hi:[0,1]
	v_pk_fma_f32 v[34:35], v[32:33], v[36:37], v[34:35] op_sel_hi:[0,1,1]
	v_pk_fma_f32 v[56:57], v[34:35], 0.5, v[56:57] op_sel_hi:[1,0,1] neg_lo:[0,0,1] neg_hi:[0,0,1]
	v_pk_fma_f32 v[40:41], v[66:67], v[64:65], v[40:41] op_sel_hi:[0,1,1] neg_lo:[1,0,0] neg_hi:[1,0,0]
	v_pk_mul_f32 v[56:57], v[8:9], v[56:57]
	v_add_u32_e32 v192, 4, v49
	v_cvt_pk_bf16_f32 v28, v56, v57
	v_and_b32_e32 v57, 0xffff0000, v29
	v_lshlrev_b32_e32 v56, 16, v29
	v_pk_mul_f32 v[60:61], v[32:33], v[56:57] op_sel_hi:[0,1]
	v_pk_fma_f32 v[52:53], v[32:33], v[56:57], v[52:53] op_sel_hi:[0,1,1]
	v_pk_fma_f32 v[60:61], v[52:53], 0.5, v[60:61] op_sel_hi:[1,0,1] neg_lo:[0,0,1] neg_hi:[0,0,1]
	v_pk_fma_f32 v[34:35], v[42:43], v[38:39], v[34:35] op_sel_hi:[0,1,1] neg_lo:[1,0,0] neg_hi:[1,0,0]
	v_pk_mul_f32 v[60:61], v[10:11], v[60:61]
	v_and_b32_e32 v39, 0xffff0000, v16
	v_cvt_pk_bf16_f32 v29, v60, v61
	v_and_b32_e32 v61, 0xffff0000, v30
	v_lshlrev_b32_e32 v60, 16, v30
	v_pk_mul_f32 v[62:63], v[32:33], v[60:61] op_sel_hi:[0,1]
	v_pk_fma_f32 v[50:51], v[32:33], v[60:61], v[50:51] op_sel_hi:[0,1,1]
	v_pk_fma_f32 v[62:63], v[50:51], 0.5, v[62:63] op_sel_hi:[1,0,1] neg_lo:[0,0,1] neg_hi:[0,0,1]
	v_lshlrev_b32_e32 v38, 16, v16
	v_pk_mul_f32 v[62:63], v[0:1], v[62:63]
	v_and_b32_e32 v69, 0xffff0000, v19
	v_cvt_pk_bf16_f32 v30, v62, v63
	v_and_b32_e32 v63, 0xffff0000, v31
	v_lshlrev_b32_e32 v62, 16, v31
	v_pk_mul_f32 v[64:65], v[32:33], v[62:63] op_sel_hi:[0,1]
	v_pk_fma_f32 v[40:41], v[32:33], v[62:63], v[40:41] op_sel_hi:[0,1,1]
	v_pk_fma_f32 v[64:65], v[40:41], 0.5, v[64:65] op_sel_hi:[1,0,1] neg_lo:[0,0,1] neg_hi:[0,0,1]
	v_and_b32_e32 v68, 0xffff0000, v15
	v_pk_mul_f32 v[64:65], v[2:3], v[64:65]
	v_lshlrev_b32_e32 v33, 16, v19
	v_cvt_pk_bf16_f32 v31, v64, v65
	v_lshlrev_b64 v[64:65], 11, v[192:193]
	v_lshl_add_u64 v[64:65], v[110:111], 0, v[64:65]
	global_store_dwordx4 v[64:65], v[28:31], off
	v_mov_b32_e32 v64, v26
	v_mov_b32_e32 v65, v24
	v_pk_fma_f32 v[64:65], v[64:65], s[20:21], v[44:45] op_sel_hi:[1,0,0]
	v_pk_fma_f32 v[52:53], v[42:43], v[54:55], v[52:53] op_sel_hi:[0,1,1] neg_lo:[1,0,0] neg_hi:[1,0,0]
	v_cmp_gt_f32_e64 s[4:5], s2, v65
	v_cmp_gt_f32_e32 vcc, s2, v64
	v_and_b32_e32 v55, 0xffff0000, v17
	v_mov_b32_e32 v24, v65
	v_rsq_f32_e32 v65, v24
	v_mov_b32_e32 v24, v64
	v_rsq_f32_e32 v64, v24
	v_lshlrev_b32_e32 v54, 16, v17
	v_pk_fma_f32 v[50:51], v[42:43], v[58:59], v[50:51] op_sel_hi:[0,1,1] neg_lo:[1,0,0] neg_hi:[1,0,0]
	v_and_b32_e32 v59, 0xffff0000, v18
	v_pk_mul_f32 v[66:67], v[64:65], s[22:23] op_sel_hi:[1,0]
	v_lshlrev_b32_e32 v58, 16, v18
	v_cndmask_b32_e64 v65, v65, v67, s[4:5]
	v_mov_b32_e32 v26, v65
	v_cndmask_b32_e32 v64, v64, v66, vcc
	v_pk_mul_f32 v[70:71], v[26:27], v[38:39] op_sel_hi:[0,1]
	v_pk_fma_f32 v[34:35], v[26:27], v[38:39], v[34:35] op_sel_hi:[0,1,1]
	v_pk_mul_f32 v[68:69], v[64:65], v[68:69]
	v_pk_fma_f32 v[70:71], v[34:35], 0.5, v[70:71] op_sel_hi:[1,0,1] neg_lo:[0,0,1] neg_hi:[0,0,1]
	v_mul_f32_e32 v66, v65, v33
	v_pk_mul_f32 v[70:71], v[8:9], v[70:71]
	v_pk_fma_f32 v[40:41], v[42:43], v[46:47], v[40:41] op_sel_hi:[0,1,1] neg_lo:[1,0,0] neg_hi:[1,0,0]
	v_mov_b32_e32 v67, v69
	v_cvt_pk_bf16_f32 v16, v70, v71
	v_pk_mul_f32 v[70:71], v[26:27], v[54:55] op_sel_hi:[0,1]
	v_pk_fma_f32 v[52:53], v[26:27], v[54:55], v[52:53] op_sel_hi:[0,1,1]
	v_pk_mul_f32 v[18:19], v[26:27], v[58:59] op_sel_hi:[0,1]
	v_pk_fma_f32 v[50:51], v[26:27], v[58:59], v[50:51] op_sel_hi:[0,1,1]
	v_pk_add_f32 v[40:41], v[66:67], v[40:41]
	v_add_u32_e32 v192, 5, v49
	v_pk_fma_f32 v[70:71], v[52:53], 0.5, v[70:71] op_sel_hi:[1,0,1] neg_lo:[0,0,1] neg_hi:[0,0,1]
	v_pk_fma_f32 v[18:19], v[50:51], 0.5, v[18:19] op_sel_hi:[1,0,1] neg_lo:[0,0,1] neg_hi:[0,0,1]
	v_pk_fma_f32 v[42:43], v[40:41], 0.5, v[66:67] op_sel_hi:[1,0,1] neg_lo:[0,0,1] neg_hi:[0,0,1]
	v_lshlrev_b64 v[28:29], 11, v[192:193]
	v_add_u32_e32 v192, 6, v49
	v_pk_mul_f32 v[70:71], v[10:11], v[70:71]
	v_pk_mul_f32 v[18:19], v[0:1], v[18:19]
	v_pk_mul_f32 v[42:43], v[2:3], v[42:43]
	v_lshl_add_u64 v[28:29], v[110:111], 0, v[28:29]
	v_lshlrev_b64 v[30:31], 11, v[192:193]
	v_cvt_pk_bf16_f32 v17, v70, v71
	v_cvt_pk_bf16_f32 v18, v18, v19
	v_cvt_pk_bf16_f32 v19, v42, v43
	v_add_u32_e32 v192, 7, v49
	global_store_dwordx4 v[28:29], v[16:19], off
	v_mov_b32_e32 v24, v27
	v_lshlrev_b32_e32 v72, 16, v15
	v_lshlrev_b64 v[16:17], 11, v[192:193]
	v_lshl_add_u64 v[42:43], v[110:111], 0, v[16:17]
	v_pk_fma_f32 v[16:17], v[24:25], s[20:21], v[44:45] op_sel_hi:[1,0,0]
	v_and_b32_e32 v71, 0xffff0000, v20
	v_cmp_gt_f32_e64 s[4:5], s2, v17
	v_cmp_gt_f32_e32 vcc, s2, v16
	v_lshlrev_b32_e32 v70, 16, v20
	v_mov_b32_e32 v15, v17
	v_rsq_f32_e32 v17, v15
	v_mov_b32_e32 v15, v16
	v_rsq_f32_e32 v16, v15
	v_lshlrev_b32_e32 v48, 16, v23
	v_lshl_add_u64 v[30:31], v[110:111], 0, v[30:31]
	v_lshlrev_b32_e32 v65, 16, v7
	v_pk_mul_f32 v[18:19], v[16:17], s[22:23] op_sel_hi:[1,0]
	v_and_b32_e32 v15, 0xffff0000, v14
	v_cndmask_b32_e64 v25, v17, v19, s[4:5]
	v_cndmask_b32_e32 v24, v16, v18, vcc
	v_and_b32_e32 v17, 0xffff0000, v23
	v_and_b32_e32 v16, 0xffff0000, v7
	v_pk_mul_f32 v[46:47], v[24:25], v[16:17]
	v_pk_fma_f32 v[16:17], v[32:33], v[36:37], v[34:35] op_sel_hi:[0,1,1] neg_lo:[1,0,0] neg_hi:[1,0,0]
	v_mov_b32_e32 v20, v25
	v_pk_mul_f32 v[18:19], v[20:21], v[70:71] op_sel_hi:[0,1]
	v_pk_fma_f32 v[34:35], v[20:21], v[70:71], v[16:17] op_sel_hi:[0,1,1]
	v_pk_fma_f32 v[16:17], v[34:35], 0.5, v[18:19] op_sel_hi:[1,0,1] neg_lo:[0,0,1] neg_hi:[0,0,1]
	v_and_b32_e32 v37, 0xffff0000, v21
	v_lshlrev_b32_e32 v36, 16, v21
	v_pk_fma_f32 v[18:19], v[32:33], v[56:57], v[52:53] op_sel_hi:[0,1,1] neg_lo:[1,0,0] neg_hi:[1,0,0]
	v_pk_mul_f32 v[52:53], v[20:21], v[36:37] op_sel_hi:[0,1]
	v_pk_fma_f32 v[56:57], v[20:21], v[36:37], v[18:19] op_sel_hi:[0,1,1]
	v_pk_fma_f32 v[18:19], v[56:57], 0.5, v[52:53] op_sel_hi:[1,0,1] neg_lo:[0,0,1] neg_hi:[0,0,1]
	v_pk_mul_f32 v[16:17], v[8:9], v[16:17]
	v_pk_mul_f32 v[18:19], v[10:11], v[18:19]
	v_mul_f32_e32 v44, v25, v48
	v_cvt_pk_bf16_f32 v16, v16, v17
	v_cvt_pk_bf16_f32 v17, v18, v19
	v_and_b32_e32 v23, 0xffff0000, v22
	v_lshlrev_b32_e32 v22, 16, v22
	v_pk_fma_f32 v[18:19], v[32:33], v[60:61], v[50:51] op_sel_hi:[0,1,1] neg_lo:[1,0,0] neg_hi:[1,0,0]
	v_pk_fma_f32 v[32:33], v[32:33], v[62:63], v[40:41] op_sel_hi:[0,1,1] neg_lo:[1,0,0] neg_hi:[1,0,0]
	v_mov_b32_e32 v45, v47
	v_pk_mul_f32 v[50:51], v[20:21], v[22:23] op_sel_hi:[0,1]
	v_pk_fma_f32 v[52:53], v[20:21], v[22:23], v[18:19] op_sel_hi:[0,1,1]
	v_pk_add_f32 v[32:33], v[44:45], v[32:33]
	v_pk_fma_f32 v[18:19], v[52:53], 0.5, v[50:51] op_sel_hi:[1,0,1] neg_lo:[0,0,1] neg_hi:[0,0,1]
	v_pk_fma_f32 v[40:41], v[32:33], 0.5, v[44:45] op_sel_hi:[1,0,1] neg_lo:[0,0,1] neg_hi:[0,0,1]
	v_pk_mul_f32 v[18:19], v[0:1], v[18:19]
	v_pk_mul_f32 v[40:41], v[2:3], v[40:41]
	v_cvt_pk_bf16_f32 v18, v18, v19
	v_cvt_pk_bf16_f32 v19, v40, v41
	global_store_dwordx4 v[30:31], v[16:19], off
	v_pk_fma_f32 v[30:31], v[26:27], v[38:39], v[34:35] op_sel_hi:[0,1,1] neg_lo:[1,0,0] neg_hi:[1,0,0]
	v_pk_fma_f32 v[34:35], v[26:27], v[54:55], v[56:57] op_sel_hi:[0,1,1] neg_lo:[1,0,0] neg_hi:[1,0,0]
	v_and_b32_e32 v17, 0xffff0000, v12
	v_lshlrev_b32_e32 v16, 16, v12
	v_pk_mul_f32 v[18:19], v[64:65], v[16:17] op_sel_hi:[0,1]
	v_pk_fma_f32 v[16:17], v[64:65], v[16:17], v[30:31] op_sel_hi:[0,1,1]
	v_pk_fma_f32 v[18:19], v[16:17], 0.5, v[18:19] op_sel_hi:[1,0,1] neg_lo:[0,0,1] neg_hi:[0,0,1]
	v_lshlrev_b32_e32 v14, 16, v14
	v_pk_mul_f32 v[18:19], v[8:9], v[18:19]
	v_pk_fma_f32 v[26:27], v[26:27], v[58:59], v[52:53] op_sel_hi:[0,1,1] neg_lo:[1,0,0] neg_hi:[1,0,0]
	v_cvt_pk_bf16_f32 v12, v18, v19
	v_and_b32_e32 v19, 0xffff0000, v13
	v_lshlrev_b32_e32 v18, 16, v13
	v_pk_mul_f32 v[30:31], v[64:65], v[18:19] op_sel_hi:[0,1]
	v_pk_fma_f32 v[18:19], v[64:65], v[18:19], v[34:35] op_sel_hi:[0,1,1]
	v_pk_fma_f32 v[30:31], v[18:19], 0.5, v[30:31] op_sel_hi:[1,0,1] neg_lo:[0,0,1] neg_hi:[0,0,1]
	v_pk_fma_f32 v[26:27], v[64:65], v[14:15], v[26:27] op_sel_hi:[0,1,1]
	v_pk_mul_f32 v[30:31], v[10:11], v[30:31]
	v_mul_f32_e32 v28, v64, v72
	v_cvt_pk_bf16_f32 v13, v30, v31
	v_pk_mul_f32 v[30:31], v[64:65], v[14:15] op_sel_hi:[0,1]
	v_pk_fma_f32 v[14:15], v[26:27], 0.5, v[30:31] op_sel_hi:[1,0,1] neg_lo:[0,0,1] neg_hi:[0,0,1]
	v_pk_add_f32 v[30:31], v[32:33], v[66:67] neg_lo:[0,1] neg_hi:[0,1]
	v_mov_b32_e32 v29, v68
	v_pk_add_f32 v[30:31], v[28:29], v[30:31]
	v_pk_mul_f32 v[14:15], v[0:1], v[14:15]
	v_pk_fma_f32 v[28:29], v[30:31], 0.5, v[28:29] op_sel_hi:[1,0,1] neg_lo:[0,0,1] neg_hi:[0,0,1]
	v_cvt_pk_bf16_f32 v14, v14, v15
	v_pk_mul_f32 v[28:29], v[2:3], v[28:29]
	v_and_b32_e32 v7, 0xffff0000, v6
	v_cvt_pk_bf16_f32 v15, v28, v29
	global_store_dwordx4 v[42:43], v[12:15], off
	v_lshlrev_b32_e32 v6, 16, v6
	v_add_u32_e32 v192, 8, v49
	v_pk_fma_f32 v[14:15], v[20:21], v[70:71], v[16:17] op_sel_hi:[0,1,1] neg_lo:[1,0,0] neg_hi:[1,0,0]
	v_and_b32_e32 v17, 0xffff0000, v4
	v_lshlrev_b32_e32 v16, 16, v4
	v_pk_mul_f32 v[28:29], v[24:25], v[16:17] op_sel_hi:[0,1]
	v_pk_fma_f32 v[14:15], v[24:25], v[16:17], v[14:15] op_sel_hi:[0,1,1]
	v_pk_fma_f32 v[14:15], v[14:15], 0.5, v[28:29] op_sel_hi:[1,0,1] neg_lo:[0,0,1] neg_hi:[0,0,1]
	v_mul_f32_e32 v12, v24, v65
	v_pk_mul_f32 v[8:9], v[8:9], v[14:15]
	v_pk_fma_f32 v[14:15], v[20:21], v[36:37], v[18:19] op_sel_hi:[0,1,1] neg_lo:[1,0,0] neg_hi:[1,0,0]
	v_cvt_pk_bf16_f32 v4, v8, v9
	v_and_b32_e32 v9, 0xffff0000, v5
	v_lshlrev_b32_e32 v8, 16, v5
	v_pk_mul_f32 v[16:17], v[24:25], v[8:9] op_sel_hi:[0,1]
	v_pk_fma_f32 v[8:9], v[24:25], v[8:9], v[14:15] op_sel_hi:[0,1,1]
	v_pk_fma_f32 v[8:9], v[8:9], 0.5, v[16:17] op_sel_hi:[1,0,1] neg_lo:[0,0,1] neg_hi:[0,0,1]
	v_mov_b32_e32 v13, v46
	v_pk_mul_f32 v[8:9], v[10:11], v[8:9]
	v_pk_mul_f32 v[10:11], v[24:25], v[6:7] op_sel_hi:[0,1]
	v_cvt_pk_bf16_f32 v5, v8, v9
	v_pk_fma_f32 v[8:9], v[20:21], v[22:23], v[26:27] op_sel_hi:[0,1,1] neg_lo:[1,0,0] neg_hi:[1,0,0]
	v_pk_fma_f32 v[6:7], v[24:25], v[6:7], v[8:9] op_sel_hi:[0,1,1]
	v_pk_fma_f32 v[6:7], v[6:7], 0.5, v[10:11] op_sel_hi:[1,0,1] neg_lo:[0,0,1] neg_hi:[0,0,1]
	s_nop 0
	v_pk_mul_f32 v[0:1], v[0:1], v[6:7]
	s_nop 0
	v_cvt_pk_bf16_f32 v6, v0, v1
	v_pk_add_f32 v[0:1], v[30:31], v[44:45] neg_lo:[0,1] neg_hi:[0,1]
	s_nop 0
	v_pk_add_f32 v[0:1], v[12:13], v[0:1]
	s_nop 0
	v_pk_fma_f32 v[0:1], v[0:1], 0.5, v[12:13] op_sel_hi:[1,0,1] neg_lo:[0,0,1] neg_hi:[0,0,1]
	s_nop 0
	v_pk_mul_f32 v[0:1], v[2:3], v[0:1]
	s_nop 0
	v_cvt_pk_bf16_f32 v7, v0, v1
	s_branch .LBB0_2586

.LBB0_2603:
	s_or_b64 exec, exec, s[36:37]
	v_cmp_gt_f32_e64 s[36:37], s2, v78
	s_waitcnt vmcnt(0)
	v_and_b32_e32 v99, 0xffff0000, v66
	v_rsq_f32_e32 v78, v78
	v_lshlrev_b32_e32 v98, 16, v66
	v_and_b32_e32 v115, 0xffff0000, v64
	v_cndmask_b32_e32 v78, 0, v78, vcc
	v_cmp_gt_f32_e32 vcc, s2, v80
	v_lshlrev_b32_e32 v114, 16, v64
	v_rsq_f32_e32 v80, v80
	v_and_b32_e32 v105, 0xffff0000, v65
	v_lshlrev_b32_e32 v104, 16, v65
	v_and_b32_e32 v65, 0xffff0000, v67
	v_cmp_gt_f32_e32 vcc, s2, v84
	v_lshlrev_b32_e32 v64, 16, v67
	v_mov_b32_e32 v82, v84
	v_rsq_f32_e32 v82, v82
	v_and_b32_e32 v101, 0xffff0000, v70
	v_and_b32_e32 v107, 0xffff0000, v62
	v_lshlrev_b32_e32 v106, 16, v62
	v_cmp_gt_f32_e32 vcc, s2, v83
	v_rsq_f32_e32 v83, v83
	v_and_b32_e32 v123, 0xffff0000, v60
	v_lshlrev_b32_e32 v122, 16, v60
	v_and_b32_e32 v119, 0xffff0000, v61
	v_cndmask_b32_e64 v84, 0, v83, s[8:9]
	v_cmp_gt_f32_e32 vcc, s2, v86
	v_lshlrev_b32_e32 v118, 16, v61
	v_mov_b32_e32 v83, v86
	v_rsq_f32_e32 v83, v83
	v_and_b32_e32 v61, 0xffff0000, v63
	v_lshlrev_b32_e32 v60, 16, v63
	v_and_b32_e32 v121, 0xffff0000, v68
	v_cndmask_b32_e64 v86, 0, v83, s[10:11]
	v_cmp_gt_f32_e32 vcc, s2, v85
	v_lshlrev_b32_e32 v120, 16, v68
	v_mov_b32_e32 v83, v85
	v_rsq_f32_e32 v83, v83
	v_and_b32_e32 v113, 0xffff0000, v69
	v_lshlrev_b32_e32 v112, 16, v69
	v_and_b32_e32 v69, 0xffff0000, v71
	v_cndmask_b32_e64 v88, 0, v83, s[12:13]
	v_cmp_gt_f32_e32 vcc, s2, v90
	v_lshlrev_b32_e32 v68, 16, v71
	v_mov_b32_e32 v83, v90
	v_rsq_f32_e32 v83, v83
	v_and_b32_e32 v125, 0xffff0000, v12
	v_lshlrev_b32_e32 v124, 16, v12
	v_cndmask_b32_e64 v80, 0, v80, s[4:5]
	v_cndmask_b32_e64 v90, 0, v83, s[14:15]
	v_cmp_gt_f32_e32 vcc, s2, v87
	v_pk_mul_f32 v[126:127], v[78:79], v[124:125] op_sel_hi:[0,1]
	v_mov_b32_e32 v83, v87
	v_rsq_f32_e32 v83, v83
	v_and_b32_e32 v129, 0xffff0000, v8
	v_lshlrev_b32_e32 v128, 16, v8
	v_pk_fma_f32 v[124:125], v[78:79], v[124:125], 0 op_sel_hi:[0,1,0]
	v_cndmask_b32_e64 v92, 0, v83, s[18:19]
	v_cmp_gt_f32_e32 vcc, s2, v94
	v_cndmask_b32_e64 v82, 0, v82, s[6:7]
	v_mov_b32_e32 v83, v94
	v_rsq_f32_e32 v83, v83
	v_and_b32_e32 v131, 0xffff0000, v20
	v_lshlrev_b32_e32 v130, 16, v20
	v_pk_fma_f32 v[124:125], v[80:81], v[128:129], v[124:125] op_sel_hi:[0,1,1]
	v_cndmask_b32_e64 v94, 0, v83, s[26:27]
	v_cmp_gt_f32_e32 vcc, s2, v93
	v_and_b32_e32 v133, 0xffff0000, v16
	v_mov_b32_e32 v83, v93
	v_rsq_f32_e32 v83, v83
	v_lshlrev_b32_e32 v132, 16, v16
	v_and_b32_e32 v135, 0xffff0000, v28
	v_lshlrev_b32_e32 v134, 16, v28
	v_cmp_gt_f32_e32 vcc, s2, v100
	v_cndmask_b32_e64 v96, 0, v83, s[30:31]
	v_and_b32_e32 v137, 0xffff0000, v24
	v_mov_b32_e32 v66, v100
	v_rsq_f32_e32 v66, v66
	v_lshlrev_b32_e32 v100, 16, v70
	v_lshlrev_b32_e32 v136, 16, v24
	v_and_b32_e32 v139, 0xffff0000, v36
	v_cmp_gt_f32_e32 vcc, s2, v89
	v_lshlrev_b32_e32 v138, 16, v36
	v_mov_b32_e32 v67, v89
	v_rsq_f32_e32 v67, v67
	v_and_b32_e32 v141, 0xffff0000, v32
	v_lshlrev_b32_e32 v140, 16, v32
	v_and_b32_e32 v143, 0xffff0000, v40
	v_cmp_gt_f32_e32 vcc, s2, v95
	v_cndmask_b32_e64 v70, 0, v67, s[20:21]
	v_lshlrev_b32_e32 v142, 16, v40
	v_mov_b32_e32 v62, v95
	v_rsq_f32_e32 v62, v62
	v_cndmask_b32_e64 v66, 0, v66, s[22:23]
	v_lshlrev_b32_e32 v20, 16, v17
	v_lshlrev_b32_e32 v16, 16, v29
	v_cmp_gt_f32_e32 vcc, s2, v91
	v_cndmask_b32_e64 v62, 0, v62, s[16:17]
	v_mov_b32_e32 v63, v91
	v_rsq_f32_e32 v63, v63
	v_lshlrev_b32_e32 v28, 16, v25
	v_lshlrev_b32_e32 v24, 16, v37
	v_lshlrev_b32_e32 v36, 16, v33
	v_cndmask_b32_e64 v102, 0, v63, s[24:25]
	v_cmp_gt_f32_e32 vcc, s2, v103
	v_lshlrev_b32_e32 v32, 16, v41
	v_mov_b32_e32 v63, v103
	v_rsq_f32_e32 v63, v63
	s_nop 0
	v_cndmask_b32_e64 v108, 0, v63, s[28:29]
	v_cmp_gt_f32_e32 vcc, s2, v97
	s_nop 0
	v_mov_b32_e32 v63, v97
	v_rsq_f32_e32 v63, v63
	s_nop 0
	v_cndmask_b32_e64 v110, 0, v63, s[34:35]
	v_cvt_f32_i32_e32 v63, v77
	v_div_scale_f32 v67, s[0:1], v63, v63, 1.0
	v_rcp_f32_e32 v71, v67
	s_movk_i32 s0, 0x7ff
	v_fma_f32 v77, -v67, v71, 1.0
	v_fmac_f32_e32 v71, v77, v71
	v_div_scale_f32 v77, vcc, 1.0, v63, 1.0
	v_mul_f32_e32 v83, v77, v71
	v_fma_f32 v85, -v67, v83, v77
	v_fmac_f32_e32 v83, v85, v71
	v_pk_fma_f32 v[124:125], v[82:83], v[130:131], v[124:125] op_sel_hi:[0,1,1]
	v_pk_fma_f32 v[124:125], v[84:85], v[132:133], v[124:125] op_sel_hi:[0,1,1]
	v_pk_fma_f32 v[124:125], v[86:87], v[134:135], v[124:125] op_sel_hi:[0,1,1]
	v_pk_fma_f32 v[124:125], v[88:89], v[136:137], v[124:125] op_sel_hi:[0,1,1]
	v_pk_fma_f32 v[124:125], v[90:91], v[138:139], v[124:125] op_sel_hi:[0,1,1]
	v_pk_fma_f32 v[124:125], v[92:93], v[140:141], v[124:125] op_sel_hi:[0,1,1]
	v_fma_f32 v67, -v67, v83, v77
	v_pk_fma_f32 v[124:125], v[94:95], v[142:143], v[124:125] op_sel_hi:[0,1,1]
	v_div_fmas_f32 v67, v67, v71, v83
	v_pk_fma_f32 v[114:115], v[96:97], v[114:115], v[124:125] op_sel_hi:[0,1,1]
	v_pk_fma_f32 v[114:115], v[66:67], v[120:121], v[114:115] op_sel_hi:[0,1,1]
	v_pk_fma_f32 v[114:115], v[70:71], v[122:123], v[114:115] op_sel_hi:[0,1,1]
	v_and_b32_e32 v121, 0xffff0000, v48
	v_lshlrev_b32_e32 v120, 16, v48
	v_pk_fma_f32 v[114:115], v[62:63], v[120:121], v[114:115] op_sel_hi:[0,1,1]
	v_and_b32_e32 v121, 0xffff0000, v44
	v_lshlrev_b32_e32 v120, 16, v44
	v_pk_fma_f32 v[114:115], v[102:103], v[120:121], v[114:115] op_sel_hi:[0,1,1]
	v_and_b32_e32 v121, 0xffff0000, v56
	v_lshlrev_b32_e32 v120, 16, v56
	v_pk_fma_f32 v[114:115], v[108:109], v[120:121], v[114:115] op_sel_hi:[0,1,1]
	v_and_b32_e32 v121, 0xffff0000, v52
	v_lshlrev_b32_e32 v120, 16, v52
	v_div_fixup_f32 v116, v67, v63, 1.0
	v_pk_fma_f32 v[114:115], v[110:111], v[120:121], v[114:115] op_sel_hi:[0,1,1]
	v_pk_fma_f32 v[114:115], v[116:117], v[114:115], v[126:127] op_sel_hi:[0,1,1] neg_lo:[0,0,1] neg_hi:[0,0,1]
	v_pk_mul_f32 v[114:115], v[4:5], v[114:115]
	v_and_b32_e32 v121, 0xffff0000, v9
	v_cvt_pk_bf16_f32 v8, v114, v115
	v_and_b32_e32 v115, 0xffff0000, v13
	v_lshlrev_b32_e32 v114, 16, v13
	v_lshlrev_b32_e32 v120, 16, v9
	v_and_b32_e32 v123, 0xffff0000, v21
	v_lshlrev_b32_e32 v122, 16, v21
	v_and_b32_e32 v21, 0xffff0000, v17
	v_and_b32_e32 v17, 0xffff0000, v29
	v_and_b32_e32 v29, 0xffff0000, v25
	v_and_b32_e32 v25, 0xffff0000, v37
	v_and_b32_e32 v37, 0xffff0000, v33
	v_and_b32_e32 v33, 0xffff0000, v41
	v_pk_fma_f32 v[40:41], v[78:79], v[114:115], 0 op_sel_hi:[0,1,0]
	v_pk_fma_f32 v[40:41], v[80:81], v[120:121], v[40:41] op_sel_hi:[0,1,1]
	v_pk_fma_f32 v[40:41], v[82:83], v[122:123], v[40:41] op_sel_hi:[0,1,1]
	v_pk_fma_f32 v[20:21], v[84:85], v[20:21], v[40:41] op_sel_hi:[0,1,1]
	v_pk_fma_f32 v[16:17], v[86:87], v[16:17], v[20:21] op_sel_hi:[0,1,1]
	v_pk_fma_f32 v[16:17], v[88:89], v[28:29], v[16:17] op_sel_hi:[0,1,1]
	v_pk_fma_f32 v[16:17], v[90:91], v[24:25], v[16:17] op_sel_hi:[0,1,1]
	v_pk_fma_f32 v[16:17], v[92:93], v[36:37], v[16:17] op_sel_hi:[0,1,1]
	v_pk_fma_f32 v[16:17], v[94:95], v[32:33], v[16:17] op_sel_hi:[0,1,1]
	v_pk_fma_f32 v[16:17], v[96:97], v[104:105], v[16:17] op_sel_hi:[0,1,1]
	v_pk_fma_f32 v[16:17], v[66:67], v[112:113], v[16:17] op_sel_hi:[0,1,1]
	v_pk_fma_f32 v[16:17], v[70:71], v[118:119], v[16:17] op_sel_hi:[0,1,1]
	v_and_b32_e32 v21, 0xffff0000, v49
	v_lshlrev_b32_e32 v20, 16, v49
	v_pk_fma_f32 v[16:17], v[62:63], v[20:21], v[16:17] op_sel_hi:[0,1,1]
	v_and_b32_e32 v21, 0xffff0000, v45
	v_lshlrev_b32_e32 v20, 16, v45
	v_pk_fma_f32 v[16:17], v[102:103], v[20:21], v[16:17] op_sel_hi:[0,1,1]
	v_and_b32_e32 v21, 0xffff0000, v57
	v_lshlrev_b32_e32 v20, 16, v57
	v_pk_fma_f32 v[16:17], v[108:109], v[20:21], v[16:17] op_sel_hi:[0,1,1]
	v_and_b32_e32 v21, 0xffff0000, v53
	v_lshlrev_b32_e32 v20, 16, v53
	v_pk_mul_f32 v[12:13], v[78:79], v[114:115] op_sel_hi:[0,1]
	v_pk_fma_f32 v[16:17], v[110:111], v[20:21], v[16:17] op_sel_hi:[0,1,1]
	v_pk_fma_f32 v[12:13], v[116:117], v[16:17], v[12:13] op_sel_hi:[0,1,1] neg_lo:[0,0,1] neg_hi:[0,0,1]
	v_pk_mul_f32 v[12:13], v[6:7], v[12:13]
	v_and_b32_e32 v21, 0xffff0000, v10
	v_cvt_pk_bf16_f32 v9, v12, v13
	v_and_b32_e32 v13, 0xffff0000, v14
	v_lshlrev_b32_e32 v12, 16, v14
	v_pk_mul_f32 v[16:17], v[78:79], v[12:13] op_sel_hi:[0,1]
	v_lshlrev_b32_e32 v20, 16, v10
	v_pk_fma_f32 v[12:13], v[78:79], v[12:13], 0 op_sel_hi:[0,1,0]
	v_and_b32_e32 v25, 0xffff0000, v22
	v_lshlrev_b32_e32 v24, 16, v22
	v_pk_fma_f32 v[12:13], v[80:81], v[20:21], v[12:13] op_sel_hi:[0,1,1]
	v_and_b32_e32 v29, 0xffff0000, v18
	v_lshlrev_b32_e32 v28, 16, v18
	v_pk_fma_f32 v[12:13], v[82:83], v[24:25], v[12:13] op_sel_hi:[0,1,1]
	v_and_b32_e32 v33, 0xffff0000, v30
	v_lshlrev_b32_e32 v32, 16, v30
	v_pk_fma_f32 v[12:13], v[84:85], v[28:29], v[12:13] op_sel_hi:[0,1,1]
	v_and_b32_e32 v37, 0xffff0000, v26
	v_lshlrev_b32_e32 v36, 16, v26
	v_pk_fma_f32 v[12:13], v[86:87], v[32:33], v[12:13] op_sel_hi:[0,1,1]
	v_and_b32_e32 v41, 0xffff0000, v38
	v_lshlrev_b32_e32 v40, 16, v38
	v_pk_fma_f32 v[12:13], v[88:89], v[36:37], v[12:13] op_sel_hi:[0,1,1]
	v_and_b32_e32 v45, 0xffff0000, v34
	v_lshlrev_b32_e32 v44, 16, v34
	v_pk_fma_f32 v[12:13], v[90:91], v[40:41], v[12:13] op_sel_hi:[0,1,1]
	v_and_b32_e32 v49, 0xffff0000, v42
	v_lshlrev_b32_e32 v48, 16, v42
	v_pk_fma_f32 v[12:13], v[92:93], v[44:45], v[12:13] op_sel_hi:[0,1,1]
	v_pk_fma_f32 v[12:13], v[94:95], v[48:49], v[12:13] op_sel_hi:[0,1,1]
	v_pk_fma_f32 v[12:13], v[96:97], v[98:99], v[12:13] op_sel_hi:[0,1,1]
	v_pk_fma_f32 v[12:13], v[66:67], v[100:101], v[12:13] op_sel_hi:[0,1,1]
	v_pk_fma_f32 v[12:13], v[70:71], v[106:107], v[12:13] op_sel_hi:[0,1,1]
	v_and_b32_e32 v21, 0xffff0000, v50
	v_lshlrev_b32_e32 v20, 16, v50
	v_pk_fma_f32 v[12:13], v[62:63], v[20:21], v[12:13] op_sel_hi:[0,1,1]
	v_and_b32_e32 v21, 0xffff0000, v46
	v_lshlrev_b32_e32 v20, 16, v46
	v_pk_fma_f32 v[12:13], v[102:103], v[20:21], v[12:13] op_sel_hi:[0,1,1]
	v_and_b32_e32 v21, 0xffff0000, v58
	v_lshlrev_b32_e32 v20, 16, v58
	v_pk_fma_f32 v[12:13], v[108:109], v[20:21], v[12:13] op_sel_hi:[0,1,1]
	v_and_b32_e32 v21, 0xffff0000, v54
	v_lshlrev_b32_e32 v20, 16, v54
	v_pk_fma_f32 v[12:13], v[110:111], v[20:21], v[12:13] op_sel_hi:[0,1,1]
	v_pk_fma_f32 v[12:13], v[116:117], v[12:13], v[16:17] op_sel_hi:[0,1,1] neg_lo:[0,0,1] neg_hi:[0,0,1]
	v_pk_mul_f32 v[12:13], v[0:1], v[12:13]
	v_and_b32_e32 v17, 0xffff0000, v11
	v_cvt_pk_bf16_f32 v10, v12, v13
	v_and_b32_e32 v13, 0xffff0000, v15
	v_lshlrev_b32_e32 v12, 16, v15
	v_pk_mul_f32 v[14:15], v[78:79], v[12:13] op_sel_hi:[0,1]
	v_lshlrev_b32_e32 v16, 16, v11
	v_pk_fma_f32 v[12:13], v[78:79], v[12:13], 0 op_sel_hi:[0,1,0]
	v_and_b32_e32 v21, 0xffff0000, v23
	v_lshlrev_b32_e32 v20, 16, v23
	v_pk_fma_f32 v[12:13], v[80:81], v[16:17], v[12:13] op_sel_hi:[0,1,1]
	v_and_b32_e32 v23, 0xffff0000, v19
	v_lshlrev_b32_e32 v22, 16, v19
	v_pk_fma_f32 v[12:13], v[82:83], v[20:21], v[12:13] op_sel_hi:[0,1,1]
	v_and_b32_e32 v19, 0xffff0000, v31
	v_lshlrev_b32_e32 v18, 16, v31
	v_pk_fma_f32 v[12:13], v[84:85], v[22:23], v[12:13] op_sel_hi:[0,1,1]
	v_and_b32_e32 v25, 0xffff0000, v27
	v_lshlrev_b32_e32 v24, 16, v27
	v_pk_fma_f32 v[12:13], v[86:87], v[18:19], v[12:13] op_sel_hi:[0,1,1]
	v_and_b32_e32 v27, 0xffff0000, v39
	v_lshlrev_b32_e32 v26, 16, v39
	v_pk_fma_f32 v[12:13], v[88:89], v[24:25], v[12:13] op_sel_hi:[0,1,1]
	v_and_b32_e32 v29, 0xffff0000, v35
	v_lshlrev_b32_e32 v28, 16, v35
	v_pk_fma_f32 v[12:13], v[90:91], v[26:27], v[12:13] op_sel_hi:[0,1,1]
	v_and_b32_e32 v31, 0xffff0000, v43
	v_lshlrev_b32_e32 v30, 16, v43
	v_pk_fma_f32 v[12:13], v[92:93], v[28:29], v[12:13] op_sel_hi:[0,1,1]
	v_pk_fma_f32 v[12:13], v[94:95], v[30:31], v[12:13] op_sel_hi:[0,1,1]
	v_pk_fma_f32 v[12:13], v[96:97], v[64:65], v[12:13] op_sel_hi:[0,1,1]
	v_pk_fma_f32 v[12:13], v[66:67], v[68:69], v[12:13] op_sel_hi:[0,1,1]
	v_pk_fma_f32 v[12:13], v[70:71], v[60:61], v[12:13] op_sel_hi:[0,1,1]
	v_and_b32_e32 v17, 0xffff0000, v51
	v_lshlrev_b32_e32 v16, 16, v51
	v_pk_fma_f32 v[12:13], v[62:63], v[16:17], v[12:13] op_sel_hi:[0,1,1]
	v_and_b32_e32 v17, 0xffff0000, v47
	v_lshlrev_b32_e32 v16, 16, v47
	v_pk_fma_f32 v[12:13], v[102:103], v[16:17], v[12:13] op_sel_hi:[0,1,1]
	v_and_b32_e32 v17, 0xffff0000, v59
	v_lshlrev_b32_e32 v16, 16, v59
	v_pk_fma_f32 v[12:13], v[108:109], v[16:17], v[12:13] op_sel_hi:[0,1,1]
	v_and_b32_e32 v17, 0xffff0000, v55
	v_lshlrev_b32_e32 v16, 16, v55
	v_pk_fma_f32 v[12:13], v[110:111], v[16:17], v[12:13] op_sel_hi:[0,1,1]
	v_pk_fma_f32 v[12:13], v[116:117], v[12:13], v[14:15] op_sel_hi:[0,1,1] neg_lo:[0,0,1] neg_hi:[0,0,1]
	v_pk_mul_f32 v[12:13], v[2:3], v[12:13]
	v_ashrrev_i32_e32 v77, 31, v76
	v_add_u32_e32 v79, s33, v79
	v_cvt_pk_bf16_f32 v11, v12, v13
	v_lshlrev_b64 v[12:13], 11, v[76:77]
	v_cmp_lt_i32_e32 vcc, s0, v79
	v_lshl_add_u64 v[12:13], v[74:75], 0, v[12:13]
	s_or_b64 s[46:47], vcc, s[46:47]
	global_store_dwordx4 v[12:13], v[8:11], off
	s_andn2_b64 exec, exec, s[46:47]
	s_cbranch_execz .LBB0_2636
